# conv phase: second-batch loads of the xBC conv and later batches of the short-conv branch issued right after the first batch (more bytes in flight per wave)
# baseline (speedup 1.0000x reference)
; #define GAS __attribute__((address_space(1)))
; __device__ __forceinline__ void unpack8(const v4u v, float (&f)[8]) { f[0] = bflo(v.x); f[1] = bfhi(v.x); f[2] = bflo(v.y); f[3] = bfhi(v.y); f[4] = bflo(v.z); f[5] = bfhi(v.z); f[6] = bflo(v.w); f[7] = bfhi(v.w); }
; __device__ __forceinline__ v4u pack8(const float (&f)[8]) { v4u o; o.x = cvt_pk_bf16(f[0], f[1]); o.y = cvt_pk_bf16(f[2], f[3]); o.z = cvt_pk_bf16(f[4], f[5]); o.w = cvt_pk_bf16(f[6], f[7]); return o; }
; __device__ __forceinline__ float siluf_(float x) { return x * __builtin_amdgcn_rcpf(1.f + __expf(-x)); }
; __device__ __forceinline__ void phase_conv(const Params& P, int seg) {
;     ...
;     for (int idx = gtid; idx < nruns * (DXBC / 8); idx += NT) {
;         const int r = idx / (DXBC / 8), c = (idx % (DXBC / 8)) * 8, lr0 = (r < RS / 16) ? r * 16 : RS + 48;
;         float w0[8], w1[8], w2[8], w3[8], bb[8];
; #pragma unroll
;         for (int e = 0; e < 8; ++e) { w0[e] = P.mb_conv_w[0 * DXBC + c + e]; w1[e] = P.mb_conv_w[1 * DXBC + c + e]; w2[e] = P.mb_conv_w[2 * DXBC + c + e]; w3[e] = P.mb_conv_w[3 * DXBC + c + e]; bb[e] = P.mb_conv_b[c + e]; }
;         float x0[8], x1[8], x2[8], x3[8];
;         unpack8(*(const GAS v4u*)(prow(lr0, 3) + OFF_XBC + c), x0); unpack8(*(const GAS v4u*)(prow(lr0, 2) + OFF_XBC + c), x1); unpack8(*(const GAS v4u*)(prow(lr0, 1) + OFF_XBC + c), x2);
; #pragma unroll
;         for (int hb = 0; hb < 2; ++hb) { v4u raw[8];
; #pragma unroll
;             for (int i = 0; i < 8; ++i) raw[i] = __builtin_nontemporal_load((const GAS v4u*)(proj + (size_t)(lr0 + hb * 8 + i) * NPROJ + OFF_XBC + c));
; #pragma unroll
;             for (int i = 0; i < 8; ++i) { unpack8(raw[i], x3); float y[8];
; #pragma unroll
;                 for (int e = 0; e < 8; ++e) { y[e] = siluf_(bb[e] + w0[e] * x0[e] + w1[e] * x1[e] + w2[e] * x2[e] + w3[e] * x3[e]); x0[e] = x1[e]; x1[e] = x2[e]; x2[e] = x3[e]; }
;                 *(GAS v4u*)(xconv + (size_t)(lr0 + hb * 8 + i) * DXBC + c) = pack8(y); } }
.LBB0_177:
	s_or_b64 exec, exec, s[0:1]
	v_lshlrev_b64 v[90:91], 1, v[36:37]
	s_waitcnt vmcnt(1)
	v_lshlrev_b32_e32 v108, 16, v28
	v_and_b32_e32 v106, 0xffff0000, v28
	v_lshlrev_b32_e32 v104, 16, v29
	v_and_b32_e32 v102, 0xffff0000, v29
	v_lshl_add_u64 v[28:29], v[38:39], 0, v[90:91]
	v_add_co_u32_e32 v28, vcc, s5, v28
	v_mov_b64_e32 v[92:93], s[40:41]
	s_nop 0
	v_addc_co_u32_e32 v29, vcc, 0, v29, vcc
	global_load_dwordx4 v[72:75], v[28:29], off
	v_mad_i64_i32 v[28:29], s[0:1], v122, s4, v[92:93]
	v_lshl_add_u64 v[28:29], v[28:29], 0, v[90:91]
	v_add_co_u32_e32 v28, vcc, s5, v28
	s_waitcnt vmcnt(1)
	v_lshlrev_b32_e32 v109, 16, v32
	v_addc_co_u32_e32 v29, vcc, 0, v29, vcc
	global_load_dwordx4 v[76:79], v[28:29], off nt
	v_mov_b32_e32 v88, v64
	v_mov_b32_e32 v89, v20
	v_pk_mul_f32 v[82:83], v[88:89], v[108:109]
	v_mov_b32_e32 v86, v68
	v_add_f32_e32 v20, v24, v82
	v_mov_b32_e32 v87, v16
	v_add_f32_e32 v20, v20, v83
	v_and_b32_e32 v107, 0xffff0000, v32
	v_lshlrev_b32_e32 v105, 16, v33
	v_mov_b32_e32 v84, v66
	v_mov_b32_e32 v85, v22
	v_and_b32_e32 v103, 0xffff0000, v33
	v_lshlrev_b32_e32 v101, 16, v34
	v_lshlrev_b32_e32 v100, 16, v30
	v_or_b32_e32 v129, 1, v122
	v_mad_i64_i32 v[28:29], s[0:1], v129, s4, v[92:93]
	v_lshl_add_u64 v[28:29], v[28:29], 0, v[90:91]
	v_add_co_u32_e32 v28, vcc, s5, v28
	v_or_b32_e32 v128, 2, v122
	s_nop 0
	v_addc_co_u32_e32 v29, vcc, 0, v29, vcc
	global_load_dwordx4 v[48:51], v[28:29], off nt
	v_mad_i64_i32 v[28:29], s[0:1], v128, s4, v[92:93]
	v_lshl_add_u64 v[28:29], v[28:29], 0, v[90:91]
	v_add_co_u32_e32 v28, vcc, s5, v28
	v_and_b32_e32 v99, 0xffff0000, v34
	s_nop 0
	v_addc_co_u32_e32 v29, vcc, 0, v29, vcc
	global_load_dwordx4 v[52:55], v[28:29], off nt
	v_and_b32_e32 v98, 0xffff0000, v30
	v_lshlrev_b32_e32 v97, 16, v35
	v_lshlrev_b32_e32 v96, 16, v31
	v_or_b32_e32 v127, 3, v122
	v_mad_i64_i32 v[28:29], s[0:1], v127, s4, v[92:93]
	v_lshl_add_u64 v[28:29], v[28:29], 0, v[90:91]
	v_and_b32_e32 v95, 0xffff0000, v35
	v_and_b32_e32 v94, 0xffff0000, v31
	v_add_co_u32_e32 v28, vcc, s5, v28
	v_or_b32_e32 v126, 4, v122
	s_nop 0
	v_addc_co_u32_e32 v29, vcc, 0, v29, vcc
	global_load_dwordx4 v[40:43], v[28:29], off nt
	v_mad_i64_i32 v[28:29], s[0:1], v126, s4, v[92:93]
	v_lshl_add_u64 v[28:29], v[28:29], 0, v[90:91]
	v_add_co_u32_e32 v28, vcc, s5, v28
	v_or_b32_e32 v125, 5, v122
	s_nop 0
	v_addc_co_u32_e32 v29, vcc, 0, v29, vcc
	global_load_dwordx4 v[44:47], v[28:29], off nt
	v_mad_i64_i32 v[28:29], s[0:1], v125, s4, v[92:93]
	v_lshl_add_u64 v[28:29], v[28:29], 0, v[90:91]
	v_add_co_u32_e32 v28, vcc, s5, v28
	v_or_b32_e32 v124, 6, v122
	s_nop 0
	v_addc_co_u32_e32 v29, vcc, 0, v29, vcc
	global_load_dwordx4 v[32:35], v[28:29], off nt
	v_mad_i64_i32 v[28:29], s[0:1], v124, s4, v[92:93]
	v_lshl_add_u64 v[28:29], v[28:29], 0, v[90:91]
	v_add_co_u32_e32 v28, vcc, s5, v28
	s_waitcnt vmcnt(6)
	v_lshlrev_b32_e32 v118, 16, v72
	v_and_b32_e32 v116, 0xffff0000, v72
	v_lshlrev_b32_e32 v114, 16, v73
	v_and_b32_e32 v112, 0xffff0000, v74
	v_lshlrev_b32_e32 v72, 16, v75
	v_and_b32_e32 v110, 0xffff0000, v75
	v_addc_co_u32_e32 v29, vcc, 0, v29, vcc
	s_waitcnt vmcnt(5)
	v_lshlrev_b32_e32 v119, 16, v76
	v_pk_mul_f32 v[82:83], v[86:87], v[118:119]
	v_and_b32_e32 v117, 0xffff0000, v76
	v_add_f32_e32 v16, v20, v82
	v_add_f32_e32 v16, v16, v83
	v_mul_f32_e32 v20, 0xbfb8aa3b, v16
	v_exp_f32_e32 v20, v20
	v_lshlrev_b32_e32 v115, 16, v77
	v_mov_b32_e32 v82, v70
	v_mov_b32_e32 v83, v18
	v_add_f32_e32 v20, 1.0, v20
	v_rcp_f32_e32 v20, v20
	v_and_b32_e32 v77, 0xffff0000, v77
	v_and_b32_e32 v76, 0xffff0000, v73
	v_lshlrev_b32_e32 v70, 16, v74
	v_mul_f32_e32 v108, v16, v20
	v_mov_b32_e32 v20, v65
	v_pk_mul_f32 v[64:65], v[20:21], v[106:107]
	v_and_b32_e32 v113, 0xffff0000, v78
	v_add_f32_e32 v16, v25, v64
	v_add_f32_e32 v68, v16, v65
	v_mov_b32_e32 v16, v69
	v_pk_mul_f32 v[64:65], v[16:17], v[116:117]
	v_mov_b32_e32 v69, v8
	v_add_f32_e32 v64, v68, v64
	v_add_f32_e32 v64, v64, v65
	v_mul_f32_e32 v65, 0xbfb8aa3b, v64
	v_exp_f32_e32 v65, v65
	v_mov_b32_e32 v68, v56
	v_lshlrev_b32_e32 v73, 16, v79
	v_and_b32_e32 v111, 0xffff0000, v79
	v_add_f32_e32 v65, 1.0, v65
	v_rcp_f32_e32 v65, v65
	v_or_b32_e32 v123, 7, v122
	global_load_dwordx4 v[36:39], v[28:29], off nt
	v_mad_i64_i32 v[28:29], s[0:1], v123, s4, v[92:93]
	v_mul_f32_e32 v106, v64, v65
	v_pk_mul_f32 v[64:65], v[84:85], v[104:105]
	v_lshl_add_u64 v[28:29], v[28:29], 0, v[90:91]
	v_add_f32_e32 v22, v26, v64
	v_add_f32_e32 v22, v22, v65
	v_pk_mul_f32 v[64:65], v[82:83], v[114:115]
	v_add_co_u32_e32 v28, vcc, s5, v28
	v_add_f32_e32 v18, v22, v64
	v_add_f32_e32 v18, v18, v65
	v_mul_f32_e32 v22, 0xbfb8aa3b, v18
	v_exp_f32_e32 v22, v22
	v_lshl_add_u64 v[80:81], s[44:45], 0, v[90:91]
	v_addc_co_u32_e32 v29, vcc, 0, v29, vcc
	v_add_f32_e32 v22, 1.0, v22
	v_rcp_f32_e32 v22, v22
	global_load_dwordx4 v[28:31], v[28:29], off nt
	s_nop 1
	v_or_b32_e32 v251, 8, v122
	v_mad_i64_i32 v[248:249], s[14:15], v251, s4, v[92:93]
	v_lshl_add_u64 v[246:247], v[248:249], 0, v[90:91]
	v_add_co_u32_e64 v250, s[14:15], s5, v246
	v_addc_co_u32_e64 v245, s[14:15], 0, v247, s[14:15]
	v_mov_b32_e32 v232, v250
	v_mov_b32_e32 v233, v245
	global_load_dwordx4 v[234:237], v[232:233], off nt
	v_or_b32_e32 v251, 9, v122
	v_mad_i64_i32 v[248:249], s[14:15], v251, s4, v[92:93]
	v_lshl_add_u64 v[246:247], v[248:249], 0, v[90:91]
	v_add_co_u32_e64 v250, s[14:15], s5, v246
	v_addc_co_u32_e64 v245, s[14:15], 0, v247, s[14:15]
	v_mov_b32_e32 v228, v250
	v_mov_b32_e32 v229, v245
	global_load_dwordx4 v[230:233], v[228:229], off nt
	v_or_b32_e32 v251, 10, v122
	v_mad_i64_i32 v[248:249], s[14:15], v251, s4, v[92:93]
	v_lshl_add_u64 v[246:247], v[248:249], 0, v[90:91]
; #define GAS __attribute__((address_space(1)))
; __device__ __forceinline__ void unpack8(const v4u v, float (&f)[8]) { f[0] = bflo(v.x); f[1] = bfhi(v.x); f[2] = bflo(v.y); f[3] = bfhi(v.y); f[4] = bflo(v.z); f[5] = bfhi(v.z); f[6] = bflo(v.w); f[7] = bfhi(v.w); }
; __device__ __forceinline__ v4u pack8(const float (&f)[8]) { v4u o; o.x = cvt_pk_bf16(f[0], f[1]); o.y = cvt_pk_bf16(f[2], f[3]); o.z = cvt_pk_bf16(f[4], f[5]); o.w = cvt_pk_bf16(f[6], f[7]); return o; }
; __device__ __forceinline__ float siluf_(float x) { return x * __builtin_amdgcn_rcpf(1.f + __expf(-x)); }
; __device__ __forceinline__ void phase_conv(const Params& P, int seg) {
;     ...
;         for (int hb = 0; hb < 2; ++hb) { v4u raw[8];
; #pragma unroll
;             for (int i = 0; i < 8; ++i) raw[i] = __builtin_nontemporal_load((const GAS v4u*)(proj + (size_t)(lr0 + hb * 8 + i) * NPROJ + OFF_XBC + c));
; #pragma unroll
;             for (int i = 0; i < 8; ++i) { unpack8(raw[i], x3); float y[8];
; #pragma unroll
;                 for (int e = 0; e < 8; ++e) { y[e] = siluf_(bb[e] + w0[e] * x0[e] + w1[e] * x1[e] + w2[e] * x2[e] + w3[e] * x3[e]); x0[e] = x1[e]; x1[e] = x2[e]; x2[e] = x3[e]; }
;                 *(GAS v4u*)(xconv + (size_t)(lr0 + hb * 8 + i) * DXBC + c) = pack8(y); } }
	v_add_co_u32_e64 v250, s[14:15], s5, v246
	v_addc_co_u32_e64 v245, s[14:15], 0, v247, s[14:15]
	v_mov_b32_e32 v224, v250
	v_mov_b32_e32 v225, v245
	global_load_dwordx4 v[226:229], v[224:225], off nt
	v_or_b32_e32 v251, 11, v122
	v_mad_i64_i32 v[248:249], s[14:15], v251, s4, v[92:93]
	v_lshl_add_u64 v[246:247], v[248:249], 0, v[90:91]
	v_add_co_u32_e64 v250, s[14:15], s5, v246
	v_addc_co_u32_e64 v245, s[14:15], 0, v247, s[14:15]
	v_mov_b32_e32 v220, v250
	v_mov_b32_e32 v221, v245
	global_load_dwordx4 v[222:225], v[220:221], off nt
	v_or_b32_e32 v251, 12, v122
	v_mad_i64_i32 v[248:249], s[14:15], v251, s4, v[92:93]
	v_lshl_add_u64 v[246:247], v[248:249], 0, v[90:91]
	v_add_co_u32_e64 v250, s[14:15], s5, v246
	v_add_co_u32_e64 v250, s[14:15], s5, v246
	v_addc_co_u32_e64 v245, s[14:15], 0, v247, s[14:15]
	v_mov_b32_e32 v216, v250
	v_mov_b32_e32 v217, v245
	global_load_dwordx4 v[218:221], v[216:217], off nt
	v_or_b32_e32 v251, 13, v122
	v_mad_i64_i32 v[248:249], s[14:15], v251, s4, v[92:93]
	v_lshl_add_u64 v[246:247], v[248:249], 0, v[90:91]
	v_add_co_u32_e64 v250, s[14:15], s5, v246
	v_add_co_u32_e64 v250, s[14:15], s5, v246
	v_addc_co_u32_e64 v245, s[14:15], 0, v247, s[14:15]
	v_mov_b32_e32 v212, v250
	v_mov_b32_e32 v213, v245
	global_load_dwordx4 v[214:217], v[212:213], off nt
	v_or_b32_e32 v251, 14, v122
	v_mad_i64_i32 v[248:249], s[14:15], v251, s4, v[92:93]
	v_lshl_add_u64 v[246:247], v[248:249], 0, v[90:91]
	v_add_co_u32_e64 v250, s[14:15], s5, v246
	v_addc_co_u32_e64 v245, s[14:15], 0, v247, s[14:15]
	v_mov_b32_e32 v208, v250
	v_mov_b32_e32 v209, v245
	global_load_dwordx4 v[210:213], v[208:209], off nt
	v_or_b32_e32 v251, 15, v122
	v_mad_i64_i32 v[248:249], s[14:15], v251, s4, v[92:93]
	v_lshl_add_u64 v[246:247], v[248:249], 0, v[90:91]
	v_add_co_u32_e64 v250, s[14:15], s5, v246
	v_addc_co_u32_e64 v245, s[14:15], 0, v247, s[14:15]
	v_mov_b32_e32 v204, v250
	v_mov_b32_e32 v205, v245
	global_load_dwordx4 v[206:209], v[204:205], off nt
	v_add_u32_e32 v121, s20, v121
	v_add_u32_e32 v120, s17, v120
	v_mul_f32_e32 v104, v18, v22
	v_mov_b32_e32 v22, v67
	v_pk_mul_f32 v[64:65], v[22:23], v[102:103]
	v_mov_b32_e32 v67, v4
	v_add_f32_e32 v18, v27, v64
	v_add_f32_e32 v66, v18, v65
	v_mov_b32_e32 v18, v71
	v_pk_mul_f32 v[64:65], v[18:19], v[76:77]
	v_lshlrev_b32_e32 v71, 16, v78
	v_add_f32_e32 v64, v66, v64
	v_add_f32_e32 v64, v64, v65
	v_mul_f32_e32 v65, 0xbfb8aa3b, v64
	v_exp_f32_e32 v65, v65
	v_mov_b32_e32 v66, v60
	v_add_f32_e32 v65, 1.0, v65
	v_rcp_f32_e32 v65, v65
	s_nop 0
	v_mul_f32_e32 v102, v64, v65
	v_pk_mul_f32 v[64:65], v[68:69], v[100:101]
	s_nop 0
	v_add_f32_e32 v8, v12, v64
	v_add_f32_e32 v8, v8, v65
	v_pk_mul_f32 v[64:65], v[66:67], v[70:71]
	s_nop 0
	v_add_f32_e32 v4, v8, v64
	v_add_f32_e32 v4, v4, v65
	v_mul_f32_e32 v8, 0xbfb8aa3b, v4
	v_exp_f32_e32 v8, v8
	v_mov_b32_e32 v64, v58
	v_mov_b32_e32 v65, v10
	v_add_f32_e32 v8, 1.0, v8
	v_rcp_f32_e32 v8, v8
	s_nop 0
	v_mul_f32_e32 v100, v4, v8
	v_mov_b32_e32 v8, v57
	v_pk_mul_f32 v[56:57], v[8:9], v[98:99]
	s_nop 0
	v_add_f32_e32 v4, v13, v56
	v_add_f32_e32 v60, v4, v57
	v_mov_b32_e32 v4, v61
	v_pk_mul_f32 v[56:57], v[4:5], v[112:113]
	v_mov_b32_e32 v61, v6
	v_add_f32_e32 v56, v60, v56
	v_add_f32_e32 v56, v56, v57
	v_mul_f32_e32 v57, 0xbfb8aa3b, v56
	v_exp_f32_e32 v57, v57
	v_mov_b32_e32 v60, v62
	v_add_f32_e32 v57, 1.0, v57
	v_rcp_f32_e32 v57, v57
	s_nop 0
	v_mul_f32_e32 v74, v56, v57
	v_pk_mul_f32 v[56:57], v[64:65], v[96:97]
	s_nop 0
	v_add_f32_e32 v10, v14, v56
	v_add_f32_e32 v10, v10, v57
	v_pk_mul_f32 v[56:57], v[60:61], v[72:73]
	s_nop 0
	v_add_f32_e32 v6, v10, v56
	v_add_f32_e32 v6, v6, v57
	v_mul_f32_e32 v10, 0xbfb8aa3b, v6
	v_exp_f32_e32 v10, v10
	s_nop 0
	v_add_f32_e32 v10, 1.0, v10
	v_rcp_f32_e32 v10, v10
	s_nop 0
	v_mul_f32_e32 v62, v6, v10
	v_mov_b32_e32 v10, v59
	v_pk_mul_f32 v[56:57], v[10:11], v[94:95]
	s_nop 0
	v_add_f32_e32 v6, v15, v56
	v_add_f32_e32 v58, v6, v57
	v_mov_b32_e32 v6, v63
	v_pk_mul_f32 v[56:57], v[6:7], v[110:111]
	s_nop 0
	v_add_f32_e32 v56, v58, v56
	v_add_f32_e32 v56, v56, v57
	v_mul_f32_e32 v57, 0xbfb8aa3b, v56
	v_exp_f32_e32 v57, v57
	s_nop 0
	v_add_f32_e32 v57, 1.0, v57
	v_rcp_f32_e32 v57, v57
	s_nop 0
	v_mul_f32_e32 v59, v56, v57
	v_cvt_pk_bf16_f32 v56, v108, v106
	v_cvt_pk_bf16_f32 v57, v104, v102
	v_cvt_pk_bf16_f32 v58, v100, v74
	v_cvt_pk_bf16_f32 v59, v62, v59
	v_mad_i64_i32 v[62:63], s[0:1], v122, s6, v[80:81]
	global_store_dwordx4 v[62:63], v[56:59], off
	s_nop 1
	v_mov_b32_e32 v56, v109
	v_mov_b32_e32 v57, v118
	v_pk_mul_f32 v[56:57], v[88:89], v[56:57]
	s_waitcnt vmcnt(14)
; #define GAS __attribute__((address_space(1)))
; __device__ __forceinline__ void unpack8(const v4u v, float (&f)[8]) { f[0] = bflo(v.x); f[1] = bfhi(v.x); f[2] = bflo(v.y); f[3] = bfhi(v.y); f[4] = bflo(v.z); f[5] = bfhi(v.z); f[6] = bflo(v.w); f[7] = bfhi(v.w); }
; __device__ __forceinline__ v4u pack8(const float (&f)[8]) { v4u o; o.x = cvt_pk_bf16(f[0], f[1]); o.y = cvt_pk_bf16(f[2], f[3]); o.z = cvt_pk_bf16(f[4], f[5]); o.w = cvt_pk_bf16(f[6], f[7]); return o; }
; __device__ __forceinline__ float siluf_(float x) { return x * __builtin_amdgcn_rcpf(1.f + __expf(-x)); }
; __device__ __forceinline__ void phase_conv(const Params& P, int seg) {
;     ...
;             for (int i = 0; i < 8; ++i) { unpack8(raw[i], x3); float y[8];
; #pragma unroll
;                 for (int e = 0; e < 8; ++e) { y[e] = siluf_(bb[e] + w0[e] * x0[e] + w1[e] * x1[e] + w2[e] * x2[e] + w3[e] * x3[e]); x0[e] = x1[e]; x1[e] = x2[e]; x2[e] = x3[e]; }
;                 *(GAS v4u*)(xconv + (size_t)(lr0 + hb * 8 + i) * DXBC + c) = pack8(y); } }
	v_lshlrev_b32_e32 v59, 16, v52
	v_add_f32_e32 v56, v24, v56
	v_add_f32_e32 v74, v56, v57
	v_mov_b32_e32 v56, v107
	v_mov_b32_e32 v57, v116
	v_pk_mul_f32 v[56:57], v[20:21], v[56:57]
	v_lshlrev_b32_e32 v58, 16, v48
	v_add_f32_e32 v56, v25, v56
	v_add_f32_e32 v78, v56, v57
	v_mov_b32_e32 v56, v105
	v_mov_b32_e32 v57, v114
	v_pk_mul_f32 v[56:57], v[84:85], v[56:57]
	v_pk_mov_b32 v[62:63], v[118:119], v[58:59] op_sel:[1,0]
	v_add_f32_e32 v56, v26, v56
	v_add_f32_e32 v100, v56, v57
	v_mov_b32_e32 v56, v103
	v_mov_b32_e32 v57, v76
	v_pk_mul_f32 v[56:57], v[22:23], v[56:57]
	s_nop 0
	v_add_f32_e32 v56, v27, v56
	v_add_f32_e32 v102, v56, v57
	v_mov_b32_e32 v56, v101
	v_mov_b32_e32 v57, v70
	v_pk_mul_f32 v[56:57], v[68:69], v[56:57]
	s_nop 0
	v_add_f32_e32 v56, v12, v56
	v_add_f32_e32 v104, v56, v57
	v_mov_b32_e32 v56, v99
	v_mov_b32_e32 v57, v112
	v_pk_mul_f32 v[56:57], v[8:9], v[56:57]
	s_nop 0
	v_add_f32_e32 v56, v13, v56
	v_add_f32_e32 v106, v56, v57
	v_mov_b32_e32 v56, v97
	v_mov_b32_e32 v57, v72
	v_pk_mul_f32 v[56:57], v[64:65], v[56:57]
	s_nop 0
	v_add_f32_e32 v56, v14, v56
	v_add_f32_e32 v108, v56, v57
	v_mov_b32_e32 v56, v95
	v_mov_b32_e32 v57, v110
	v_pk_mul_f32 v[56:57], v[10:11], v[56:57]
	v_mad_i64_i32 v[94:95], s[0:1], v129, s6, v[80:81]
	v_add_f32_e32 v56, v15, v56
	v_add_f32_e32 v130, v56, v57
	v_pk_mul_f32 v[56:57], v[88:89], v[118:119]
	s_nop 0
	v_add_f32_e32 v56, v24, v56
	v_add_f32_e32 v75, v56, v57
	v_pk_mul_f32 v[56:57], v[86:87], v[62:63]
	s_nop 0
	v_add_f32_e32 v56, v74, v56
	v_add_f32_e32 v56, v56, v57
	v_mul_f32_e32 v57, 0xbfb8aa3b, v56
	v_exp_f32_e32 v57, v57
	s_nop 0
	v_add_f32_e32 v57, 1.0, v57
	v_rcp_f32_e32 v57, v57
	s_nop 0
	v_mul_f32_e32 v79, v56, v57
	v_pk_mul_f32 v[56:57], v[86:87], v[58:59]
	s_nop 0
	v_add_f32_e32 v56, v75, v56
	v_add_f32_e32 v56, v56, v57
	v_mul_f32_e32 v57, 0xbfb8aa3b, v56
	v_exp_f32_e32 v57, v57
	s_nop 0
	v_add_f32_e32 v57, 1.0, v57
	v_rcp_f32_e32 v57, v57
	s_nop 0
	v_mul_f32_e32 v118, v56, v57
	v_pk_mul_f32 v[56:57], v[20:21], v[116:117]
	s_nop 0
	v_add_f32_e32 v56, v25, v56
	v_add_f32_e32 v98, v56, v57
	v_and_b32_e32 v57, 0xffff0000, v52
	v_and_b32_e32 v56, 0xffff0000, v48
	v_pk_mov_b32 v[96:97], v[116:117], v[56:57] op_sel:[1,0]
	s_nop 0
	v_pk_mul_f32 v[74:75], v[16:17], v[96:97]
	s_nop 0
	v_add_f32_e32 v48, v78, v74
	v_add_f32_e32 v48, v48, v75
	v_mul_f32_e32 v52, 0xbfb8aa3b, v48
	v_exp_f32_e32 v52, v52
	v_pk_mul_f32 v[74:75], v[16:17], v[56:57]
	v_lshlrev_b32_e32 v78, 16, v49
	v_add_f32_e32 v52, 1.0, v52
	v_rcp_f32_e32 v52, v52
	s_nop 0
	v_mul_f32_e32 v48, v48, v52
	v_add_f32_e32 v52, v98, v74
	v_add_f32_e32 v52, v52, v75
	v_mul_f32_e32 v74, 0xbfb8aa3b, v52
	v_exp_f32_e32 v74, v74
	v_cvt_pk_bf16_f32 v48, v79, v48
	v_lshlrev_b32_e32 v79, 16, v53
	v_pk_mov_b32 v[98:99], v[114:115], v[78:79] op_sel:[1,0]
	v_add_f32_e32 v74, 1.0, v74
	v_rcp_f32_e32 v74, v74
	v_and_b32_e32 v53, 0xffff0000, v53
	v_mul_f32_e32 v116, v52, v74
	v_pk_mul_f32 v[74:75], v[84:85], v[114:115]
	s_nop 0
	v_add_f32_e32 v52, v26, v74
	v_add_f32_e32 v52, v52, v75
	v_pk_mul_f32 v[74:75], v[82:83], v[98:99]
	s_nop 0
	v_add_f32_e32 v74, v100, v74
	v_add_f32_e32 v74, v74, v75
	v_mul_f32_e32 v75, 0xbfb8aa3b, v74
	v_exp_f32_e32 v75, v75
	s_nop 0
	v_add_f32_e32 v75, 1.0, v75
	v_rcp_f32_e32 v75, v75
	s_nop 0
	v_mul_f32_e32 v103, v74, v75
	v_pk_mul_f32 v[74:75], v[82:83], v[78:79]
	s_nop 0
	v_add_f32_e32 v52, v52, v74
	v_add_f32_e32 v52, v52, v75
	v_mul_f32_e32 v74, 0xbfb8aa3b, v52
	v_exp_f32_e32 v74, v74
	s_nop 0
	v_add_f32_e32 v74, 1.0, v74
	v_rcp_f32_e32 v74, v74
	s_nop 0
	v_mul_f32_e32 v114, v52, v74
	v_pk_mul_f32 v[74:75], v[22:23], v[76:77]
	s_nop 0
	v_add_f32_e32 v52, v27, v74
	v_add_f32_e32 v105, v52, v75
	v_and_b32_e32 v52, 0xffff0000, v49
	v_pk_mov_b32 v[100:101], v[76:77], v[52:53] op_sel:[1,0]
	v_lshlrev_b32_e32 v77, 16, v54
	v_pk_mul_f32 v[74:75], v[18:19], v[100:101]
	v_lshlrev_b32_e32 v76, 16, v50
	v_add_f32_e32 v49, v102, v74
	v_add_f32_e32 v49, v49, v75
	v_mul_f32_e32 v74, 0xbfb8aa3b, v49
	v_exp_f32_e32 v74, v74
	s_nop 0
	v_add_f32_e32 v74, 1.0, v74
	v_rcp_f32_e32 v74, v74
	s_nop 0
	v_mul_f32_e32 v49, v49, v74
	v_pk_mul_f32 v[74:75], v[18:19], v[52:53]
	v_cvt_pk_bf16_f32 v49, v103, v49
	s_nop 0
	v_add_f32_e32 v74, v105, v74
	v_add_f32_e32 v74, v74, v75
	v_mul_f32_e32 v75, 0xbfb8aa3b, v74
	v_exp_f32_e32 v75, v75
	s_nop 0
	v_add_f32_e32 v75, 1.0, v75
	v_rcp_f32_e32 v75, v75
	s_nop 0
	v_mul_f32_e32 v115, v74, v75
	v_pk_mul_f32 v[74:75], v[68:69], v[70:71]
	s_nop 0
	v_add_f32_e32 v70, v12, v74
	v_pk_mov_b32 v[102:103], v[70:71], v[76:77] op_sel:[1,0]
	v_add_f32_e32 v74, v70, v75
	v_pk_mul_f32 v[70:71], v[66:67], v[102:103]
	s_nop 0
	v_add_f32_e32 v70, v104, v70
	v_add_f32_e32 v70, v70, v71
	v_mul_f32_e32 v71, 0xbfb8aa3b, v70
	v_exp_f32_e32 v71, v71
	s_nop 0
	v_add_f32_e32 v71, 1.0, v71
	v_rcp_f32_e32 v71, v71
	s_nop 0
	v_mul_f32_e32 v107, v70, v71
	v_pk_mul_f32 v[70:71], v[66:67], v[76:77]
	s_nop 0
	v_add_f32_e32 v70, v74, v70
	v_add_f32_e32 v70, v70, v71
	v_mul_f32_e32 v71, 0xbfb8aa3b, v70
	v_exp_f32_e32 v71, v71
	s_nop 0
	v_add_f32_e32 v71, 1.0, v71
	v_rcp_f32_e32 v71, v71
	s_nop 0
	v_mul_f32_e32 v117, v70, v71
	v_pk_mul_f32 v[70:71], v[8:9], v[112:113]
	s_nop 0
	v_add_f32_e32 v70, v13, v70
	v_add_f32_e32 v109, v70, v71
	v_and_b32_e32 v71, 0xffff0000, v54
	v_and_b32_e32 v70, 0xffff0000, v50
	v_pk_mov_b32 v[104:105], v[112:113], v[70:71] op_sel:[1,0]
	s_nop 0
	v_pk_mul_f32 v[74:75], v[4:5], v[104:105]
	s_nop 0
	v_add_f32_e32 v50, v106, v74
	v_add_f32_e32 v50, v50, v75
	v_mul_f32_e32 v54, 0xbfb8aa3b, v50
	v_exp_f32_e32 v54, v54
	v_pk_mul_f32 v[74:75], v[4:5], v[70:71]
	v_add_f32_e32 v54, 1.0, v54
	v_rcp_f32_e32 v54, v54
; #define GAS __attribute__((address_space(1)))
; __device__ __forceinline__ void unpack8(const v4u v, float (&f)[8]) { f[0] = bflo(v.x); f[1] = bfhi(v.x); f[2] = bflo(v.y); f[3] = bfhi(v.y); f[4] = bflo(v.z); f[5] = bfhi(v.z); f[6] = bflo(v.w); f[7] = bfhi(v.w); }
; __device__ __forceinline__ v4u pack8(const float (&f)[8]) { v4u o; o.x = cvt_pk_bf16(f[0], f[1]); o.y = cvt_pk_bf16(f[2], f[3]); o.z = cvt_pk_bf16(f[4], f[5]); o.w = cvt_pk_bf16(f[6], f[7]); return o; }
; __device__ __forceinline__ float siluf_(float x) { return x * __builtin_amdgcn_rcpf(1.f + __expf(-x)); }
; __device__ __forceinline__ void phase_conv(const Params& P, int seg) {
;     ...
;             for (int i = 0; i < 8; ++i) { unpack8(raw[i], x3); float y[8];
; #pragma unroll
;                 for (int e = 0; e < 8; ++e) { y[e] = siluf_(bb[e] + w0[e] * x0[e] + w1[e] * x1[e] + w2[e] * x2[e] + w3[e] * x3[e]); x0[e] = x1[e]; x1[e] = x2[e]; x2[e] = x3[e]; }
;                 *(GAS v4u*)(xconv + (size_t)(lr0 + hb * 8 + i) * DXBC + c) = pack8(y); } }
	s_nop 0
	v_mul_f32_e32 v50, v50, v54
	v_add_f32_e32 v54, v109, v74
	v_add_f32_e32 v54, v54, v75
	v_mul_f32_e32 v74, 0xbfb8aa3b, v54
	v_exp_f32_e32 v74, v74
	v_cvt_pk_bf16_f32 v50, v107, v50
	s_nop 0
	v_add_f32_e32 v74, 1.0, v74
	v_rcp_f32_e32 v74, v74
	s_nop 0
	v_mul_f32_e32 v112, v54, v74
	v_pk_mul_f32 v[74:75], v[64:65], v[72:73]
	s_nop 0
	v_add_f32_e32 v54, v14, v74
	v_add_f32_e32 v54, v54, v75
	v_lshlrev_b32_e32 v75, 16, v55
	v_lshlrev_b32_e32 v74, 16, v51
	v_pk_mov_b32 v[106:107], v[72:73], v[74:75] op_sel:[1,0]
	s_nop 0
	v_pk_mul_f32 v[72:73], v[60:61], v[106:107]
	s_nop 0
	v_add_f32_e32 v72, v108, v72
	v_add_f32_e32 v72, v72, v73
	v_mul_f32_e32 v73, 0xbfb8aa3b, v72
	v_exp_f32_e32 v73, v73
	s_nop 0
	v_add_f32_e32 v73, 1.0, v73
	v_rcp_f32_e32 v73, v73
	s_nop 0
	v_mul_f32_e32 v113, v72, v73
	v_pk_mul_f32 v[72:73], v[60:61], v[74:75]
	s_nop 0
	v_add_f32_e32 v54, v54, v72
	v_add_f32_e32 v54, v54, v73
	v_mul_f32_e32 v72, 0xbfb8aa3b, v54
	v_exp_f32_e32 v72, v72
	s_nop 0
	v_add_f32_e32 v72, 1.0, v72
	v_rcp_f32_e32 v72, v72
	s_nop 0
	v_mul_f32_e32 v119, v54, v72
	v_pk_mul_f32 v[72:73], v[10:11], v[110:111]
	s_nop 0
	v_add_f32_e32 v54, v15, v72
	v_add_f32_e32 v129, v54, v73
	v_and_b32_e32 v73, 0xffff0000, v55
	v_and_b32_e32 v72, 0xffff0000, v51
	v_pk_mov_b32 v[54:55], v[110:111], v[72:73] op_sel:[1,0]
	s_nop 0
	v_pk_mul_f32 v[108:109], v[6:7], v[54:55]
	s_nop 0
	v_add_f32_e32 v51, v130, v108
	v_add_f32_e32 v51, v51, v109
	v_mul_f32_e32 v108, 0xbfb8aa3b, v51
	v_exp_f32_e32 v108, v108
	s_nop 0
	v_add_f32_e32 v108, 1.0, v108
	v_rcp_f32_e32 v108, v108
	s_nop 0
	v_mul_f32_e32 v51, v51, v108
	v_cvt_pk_bf16_f32 v51, v113, v51
	global_store_dwordx4 v[94:95], v[48:51], off
	v_mad_i64_i32 v[94:95], s[0:1], v128, s6, v[80:81]
	s_nop 0
	v_pk_mul_f32 v[48:49], v[6:7], v[72:73]
	s_nop 0
	v_add_f32_e32 v48, v129, v48
	v_add_f32_e32 v48, v48, v49
	v_mul_f32_e32 v49, 0xbfb8aa3b, v48
	v_exp_f32_e32 v49, v49
	s_nop 0
	v_add_f32_e32 v49, 1.0, v49
	v_rcp_f32_e32 v49, v49
	s_nop 0
	v_mul_f32_e32 v51, v48, v49
	v_cvt_pk_bf16_f32 v48, v118, v116
	v_cvt_pk_bf16_f32 v49, v114, v115
	v_cvt_pk_bf16_f32 v50, v117, v112
	v_cvt_pk_bf16_f32 v51, v119, v51
	global_store_dwordx4 v[94:95], v[48:51], off
	v_or_b32_e32 v112, 9, v122
	s_nop 0
	v_pk_mul_f32 v[48:49], v[88:89], v[62:63]
	s_waitcnt vmcnt(14)
	v_lshlrev_b32_e32 v63, 16, v44
	v_add_f32_e32 v48, v24, v48
	v_add_f32_e32 v50, v48, v49
	v_pk_mul_f32 v[48:49], v[20:21], v[96:97]
	v_lshlrev_b32_e32 v62, 16, v40
	v_add_f32_e32 v48, v25, v48
	v_add_f32_e32 v51, v48, v49
	v_pk_mul_f32 v[48:49], v[84:85], v[98:99]
	v_pk_mov_b32 v[94:95], v[58:59], v[62:63] op_sel:[1,0]
	v_add_f32_e32 v48, v26, v48
	v_add_f32_e32 v108, v48, v49
	v_pk_mul_f32 v[48:49], v[22:23], v[100:101]
	v_mad_i64_i32 v[96:97], s[0:1], v127, s6, v[80:81]
	v_add_f32_e32 v48, v27, v48
	v_add_f32_e32 v100, v48, v49
	v_pk_mul_f32 v[48:49], v[68:69], v[102:103]
	s_nop 0
	v_add_f32_e32 v48, v12, v48
	v_add_f32_e32 v101, v48, v49
	v_pk_mul_f32 v[48:49], v[8:9], v[104:105]
	s_nop 0
	v_add_f32_e32 v48, v13, v48
	v_add_f32_e32 v102, v48, v49
	v_pk_mul_f32 v[48:49], v[64:65], v[106:107]
	s_nop 0
	v_add_f32_e32 v48, v14, v48
	v_add_f32_e32 v103, v48, v49
	v_pk_mul_f32 v[48:49], v[10:11], v[54:55]
	s_nop 0
	v_add_f32_e32 v48, v15, v48
	v_add_f32_e32 v104, v48, v49
	v_pk_mul_f32 v[48:49], v[88:89], v[58:59]
	v_and_b32_e32 v59, 0xffff0000, v44
	v_add_f32_e32 v48, v24, v48
	v_add_f32_e32 v54, v48, v49
	v_pk_mul_f32 v[48:49], v[86:87], v[94:95]
	v_and_b32_e32 v58, 0xffff0000, v40
	v_add_f32_e32 v48, v50, v48
	v_add_f32_e32 v48, v48, v49
	v_mul_f32_e32 v49, 0xbfb8aa3b, v48
	v_exp_f32_e32 v49, v49
	v_pk_mov_b32 v[98:99], v[56:57], v[58:59] op_sel:[1,0]
	v_add_f32_e32 v49, 1.0, v49
	v_rcp_f32_e32 v49, v49
	s_nop 0
	v_mul_f32_e32 v50, v48, v49
	v_pk_mul_f32 v[48:49], v[86:87], v[62:63]
	s_nop 0
	v_add_f32_e32 v48, v54, v48
	v_add_f32_e32 v48, v48, v49
	v_mul_f32_e32 v49, 0xbfb8aa3b, v48
	v_exp_f32_e32 v49, v49
	s_nop 0
	v_add_f32_e32 v49, 1.0, v49
	v_rcp_f32_e32 v49, v49
	s_nop 0
	v_mul_f32_e32 v105, v48, v49
	v_pk_mul_f32 v[48:49], v[20:21], v[56:57]
	v_lshlrev_b32_e32 v57, 16, v45
	v_add_f32_e32 v48, v25, v48
	v_add_f32_e32 v54, v48, v49
	v_pk_mul_f32 v[48:49], v[16:17], v[98:99]
	v_lshlrev_b32_e32 v56, 16, v41
	v_add_f32_e32 v40, v51, v48
	v_add_f32_e32 v40, v40, v49
	v_mul_f32_e32 v44, 0xbfb8aa3b, v40
	v_exp_f32_e32 v44, v44
	v_pk_mul_f32 v[48:49], v[16:17], v[58:59]
	v_add_f32_e32 v44, 1.0, v44
	v_rcp_f32_e32 v44, v44
	s_nop 0
	v_mul_f32_e32 v40, v40, v44
	v_add_f32_e32 v44, v54, v48
	v_add_f32_e32 v44, v44, v49
	v_mul_f32_e32 v48, 0xbfb8aa3b, v44
	v_exp_f32_e32 v48, v48
	v_cvt_pk_bf16_f32 v40, v50, v40
	s_nop 0
	v_add_f32_e32 v48, 1.0, v48
	v_rcp_f32_e32 v48, v48
	s_nop 0
	v_mul_f32_e32 v106, v44, v48
	v_pk_mul_f32 v[48:49], v[84:85], v[78:79]
	v_pk_mov_b32 v[78:79], v[78:79], v[56:57] op_sel:[1,0]
	v_add_f32_e32 v44, v26, v48
	v_add_f32_e32 v44, v44, v49
	v_pk_mul_f32 v[48:49], v[82:83], v[78:79]
	s_nop 0
	v_add_f32_e32 v48, v108, v48
	v_add_f32_e32 v48, v48, v49
	v_mul_f32_e32 v49, 0xbfb8aa3b, v48
	v_exp_f32_e32 v49, v49
	s_nop 0
	v_add_f32_e32 v49, 1.0, v49
	v_rcp_f32_e32 v49, v49
	s_nop 0
	v_mul_f32_e32 v54, v48, v49
	v_pk_mul_f32 v[48:49], v[82:83], v[56:57]
	s_nop 0
	v_add_f32_e32 v44, v44, v48
	v_add_f32_e32 v44, v44, v49
	v_mul_f32_e32 v48, 0xbfb8aa3b, v44
	v_exp_f32_e32 v48, v48
	s_nop 0
	v_add_f32_e32 v48, 1.0, v48
	v_rcp_f32_e32 v48, v48
	s_nop 0
	v_mul_f32_e32 v107, v44, v48
	v_pk_mul_f32 v[48:49], v[22:23], v[52:53]
	s_nop 0
	v_add_f32_e32 v44, v27, v48
	v_add_f32_e32 v55, v44, v49
	v_and_b32_e32 v49, 0xffff0000, v45
	v_and_b32_e32 v48, 0xffff0000, v41
; #define GAS __attribute__((address_space(1)))
; __device__ __forceinline__ void unpack8(const v4u v, float (&f)[8]) { f[0] = bflo(v.x); f[1] = bfhi(v.x); f[2] = bflo(v.y); f[3] = bfhi(v.y); f[4] = bflo(v.z); f[5] = bfhi(v.z); f[6] = bflo(v.w); f[7] = bfhi(v.w); }
; __device__ __forceinline__ v4u pack8(const float (&f)[8]) { v4u o; o.x = cvt_pk_bf16(f[0], f[1]); o.y = cvt_pk_bf16(f[2], f[3]); o.z = cvt_pk_bf16(f[4], f[5]); o.w = cvt_pk_bf16(f[6], f[7]); return o; }
; __device__ __forceinline__ float siluf_(float x) { return x * __builtin_amdgcn_rcpf(1.f + __expf(-x)); }
; __device__ __forceinline__ void phase_conv(const Params& P, int seg) {
;     ...
;             for (int i = 0; i < 8; ++i) { unpack8(raw[i], x3); float y[8];
; #pragma unroll
;                 for (int e = 0; e < 8; ++e) { y[e] = siluf_(bb[e] + w0[e] * x0[e] + w1[e] * x1[e] + w2[e] * x2[e] + w3[e] * x3[e]); x0[e] = x1[e]; x1[e] = x2[e]; x2[e] = x3[e]; }
;                 *(GAS v4u*)(xconv + (size_t)(lr0 + hb * 8 + i) * DXBC + c) = pack8(y); } }
	v_pk_mov_b32 v[44:45], v[52:53], v[48:49] op_sel:[1,0]
	v_and_b32_e32 v53, 0xffff0000, v46
	v_pk_mul_f32 v[50:51], v[18:19], v[44:45]
	s_nop 0
	v_add_f32_e32 v41, v100, v50
	v_add_f32_e32 v41, v41, v51
	v_mul_f32_e32 v50, 0xbfb8aa3b, v41
	v_exp_f32_e32 v50, v50
	s_nop 0
	v_add_f32_e32 v50, 1.0, v50
	v_rcp_f32_e32 v50, v50
	s_nop 0
	v_mul_f32_e32 v41, v41, v50
	v_pk_mul_f32 v[50:51], v[18:19], v[48:49]
	v_cvt_pk_bf16_f32 v41, v54, v41
	v_lshlrev_b32_e32 v54, 16, v42
	v_add_f32_e32 v50, v55, v50
	v_add_f32_e32 v50, v50, v51
	v_mul_f32_e32 v51, 0xbfb8aa3b, v50
	v_exp_f32_e32 v51, v51
	v_lshlrev_b32_e32 v55, 16, v46
	v_add_f32_e32 v51, 1.0, v51
	v_rcp_f32_e32 v51, v51
	s_nop 0
	v_mul_f32_e32 v108, v50, v51
	v_pk_mul_f32 v[50:51], v[68:69], v[76:77]
	v_pk_mov_b32 v[76:77], v[76:77], v[54:55] op_sel:[1,0]
	v_add_f32_e32 v50, v12, v50
	v_add_f32_e32 v52, v50, v51
	v_pk_mul_f32 v[50:51], v[66:67], v[76:77]
	s_nop 0
	v_add_f32_e32 v50, v101, v50
	v_add_f32_e32 v50, v50, v51
	v_mul_f32_e32 v51, 0xbfb8aa3b, v50
	v_exp_f32_e32 v51, v51
	s_nop 0
	v_add_f32_e32 v51, 1.0, v51
	v_rcp_f32_e32 v51, v51
	s_nop 0
	v_mul_f32_e32 v100, v50, v51
	v_pk_mul_f32 v[50:51], v[66:67], v[54:55]
	s_nop 0
	v_add_f32_e32 v50, v52, v50
	v_add_f32_e32 v50, v50, v51
	v_mul_f32_e32 v51, 0xbfb8aa3b, v50
	v_exp_f32_e32 v51, v51
	v_and_b32_e32 v52, 0xffff0000, v42
	v_add_f32_e32 v51, 1.0, v51
	v_rcp_f32_e32 v51, v51
	s_nop 0
	v_mul_f32_e32 v109, v50, v51
	v_pk_mul_f32 v[50:51], v[8:9], v[70:71]
	v_pk_mov_b32 v[70:71], v[70:71], v[52:53] op_sel:[1,0]
	v_add_f32_e32 v50, v13, v50
	v_add_f32_e32 v101, v50, v51
	v_pk_mul_f32 v[50:51], v[4:5], v[70:71]
	s_nop 0
	v_add_f32_e32 v42, v102, v50
	v_add_f32_e32 v42, v42, v51
	v_mul_f32_e32 v46, 0xbfb8aa3b, v42
	v_exp_f32_e32 v46, v46
	v_pk_mul_f32 v[50:51], v[4:5], v[52:53]
	v_add_f32_e32 v46, 1.0, v46
	v_rcp_f32_e32 v46, v46
	s_nop 0
	v_mul_f32_e32 v42, v42, v46
	v_add_f32_e32 v46, v101, v50
	v_add_f32_e32 v46, v46, v51
	v_mul_f32_e32 v50, 0xbfb8aa3b, v46
	v_exp_f32_e32 v50, v50
	v_cvt_pk_bf16_f32 v42, v100, v42
	s_nop 0
	v_add_f32_e32 v50, 1.0, v50
	v_rcp_f32_e32 v50, v50
	s_nop 0
	v_mul_f32_e32 v102, v46, v50
	v_pk_mul_f32 v[50:51], v[64:65], v[74:75]
	s_nop 0
	v_add_f32_e32 v46, v14, v50
	v_add_f32_e32 v46, v46, v51
	v_lshlrev_b32_e32 v51, 16, v47
	v_lshlrev_b32_e32 v50, 16, v43
	v_pk_mov_b32 v[74:75], v[74:75], v[50:51] op_sel:[1,0]
	v_and_b32_e32 v47, 0xffff0000, v47
	v_pk_mul_f32 v[100:101], v[60:61], v[74:75]
	s_nop 0
	v_add_f32_e32 v100, v103, v100
	v_add_f32_e32 v100, v100, v101
	v_mul_f32_e32 v101, 0xbfb8aa3b, v100
	v_exp_f32_e32 v101, v101
	s_nop 0
	v_add_f32_e32 v101, 1.0, v101
	v_rcp_f32_e32 v101, v101
	s_nop 0
	v_mul_f32_e32 v103, v100, v101
	v_pk_mul_f32 v[100:101], v[60:61], v[50:51]
	s_nop 0
	v_add_f32_e32 v46, v46, v100
	v_add_f32_e32 v46, v46, v101
	v_mul_f32_e32 v100, 0xbfb8aa3b, v46
	v_exp_f32_e32 v100, v100
	s_nop 0
	v_add_f32_e32 v100, 1.0, v100
	v_rcp_f32_e32 v100, v100
	s_nop 0
	v_mul_f32_e32 v110, v46, v100
	v_pk_mul_f32 v[100:101], v[10:11], v[72:73]
	s_nop 0
	v_add_f32_e32 v46, v15, v100
	v_add_f32_e32 v111, v46, v101
	v_and_b32_e32 v46, 0xffff0000, v43
	v_pk_mov_b32 v[72:73], v[72:73], v[46:47] op_sel:[1,0]
	s_nop 0
	v_pk_mul_f32 v[100:101], v[6:7], v[72:73]
	s_nop 0
	v_add_f32_e32 v43, v104, v100
	v_add_f32_e32 v43, v43, v101
	v_mul_f32_e32 v100, 0xbfb8aa3b, v43
	v_exp_f32_e32 v100, v100
	s_waitcnt vmcnt(12)
	v_lshlrev_b32_e32 v101, 16, v39
	v_add_f32_e32 v100, 1.0, v100
	v_rcp_f32_e32 v100, v100
	s_nop 0
	v_mul_f32_e32 v43, v43, v100
	v_cvt_pk_bf16_f32 v43, v103, v43
	global_store_dwordx4 v[96:97], v[40:43], off
	v_mad_i64_i32 v[96:97], s[0:1], v126, s6, v[80:81]
	s_nop 0
	v_pk_mul_f32 v[40:41], v[6:7], v[46:47]
	v_lshlrev_b32_e32 v100, 16, v35
	v_add_f32_e32 v40, v111, v40
	v_add_f32_e32 v40, v40, v41
	v_mul_f32_e32 v41, 0xbfb8aa3b, v40
	v_exp_f32_e32 v41, v41
	v_and_b32_e32 v103, 0xffff0000, v39
	v_or_b32_e32 v111, 10, v122
	v_add_f32_e32 v41, 1.0, v41
	v_rcp_f32_e32 v41, v41
	s_nop 0
	v_mul_f32_e32 v43, v40, v41
	v_cvt_pk_bf16_f32 v40, v105, v106
	v_cvt_pk_bf16_f32 v41, v107, v108
	v_cvt_pk_bf16_f32 v42, v109, v102
	v_cvt_pk_bf16_f32 v43, v110, v43
	global_store_dwordx4 v[96:97], v[40:43], off
	v_and_b32_e32 v102, 0xffff0000, v35
	s_waitcnt vmcnt(13)
; #define GAS __attribute__((address_space(1)))
; __device__ __forceinline__ void unpack8(const v4u v, float (&f)[8]) { f[0] = bflo(v.x); f[1] = bfhi(v.x); f[2] = bflo(v.y); f[3] = bfhi(v.y); f[4] = bflo(v.z); f[5] = bfhi(v.z); f[6] = bflo(v.w); f[7] = bfhi(v.w); }
; __device__ __forceinline__ v4u pack8(const float (&f)[8]) { v4u o; o.x = cvt_pk_bf16(f[0], f[1]); o.y = cvt_pk_bf16(f[2], f[3]); o.z = cvt_pk_bf16(f[4], f[5]); o.w = cvt_pk_bf16(f[6], f[7]); return o; }
; __device__ __forceinline__ float siluf_(float x) { return x * __builtin_amdgcn_rcpf(1.f + __expf(-x)); }
; __device__ __forceinline__ void phase_conv(const Params& P, int seg) {
;     ...
;             for (int i = 0; i < 8; ++i) { unpack8(raw[i], x3); float y[8];
; #pragma unroll
;                 for (int e = 0; e < 8; ++e) { y[e] = siluf_(bb[e] + w0[e] * x0[e] + w1[e] * x1[e] + w2[e] * x2[e] + w3[e] * x3[e]); x0[e] = x1[e]; x1[e] = x2[e]; x2[e] = x3[e]; }
;                 *(GAS v4u*)(xconv + (size_t)(lr0 + hb * 8 + i) * DXBC + c) = pack8(y); } }
	v_lshlrev_b32_e32 v97, 16, v28
	v_pk_mul_f32 v[40:41], v[88:89], v[94:95]
	v_or_b32_e32 v110, 11, v122
	v_add_f32_e32 v40, v24, v40
	v_add_f32_e32 v94, v40, v41
	v_pk_mul_f32 v[40:41], v[20:21], v[98:99]
	v_or_b32_e32 v109, 12, v122
	v_add_f32_e32 v40, v25, v40
	v_add_f32_e32 v95, v40, v41
	v_pk_mul_f32 v[40:41], v[84:85], v[78:79]
	v_or_b32_e32 v108, 13, v122
	v_add_f32_e32 v40, v26, v40
	v_add_f32_e32 v78, v40, v41
	v_pk_mul_f32 v[40:41], v[22:23], v[44:45]
	s_nop 0
	v_add_f32_e32 v40, v27, v40
	v_add_f32_e32 v79, v40, v41
	v_pk_mul_f32 v[40:41], v[68:69], v[76:77]
	s_nop 0
	v_add_f32_e32 v40, v12, v40
	v_add_f32_e32 v76, v40, v41
	v_pk_mul_f32 v[40:41], v[8:9], v[70:71]
	v_mad_i64_i32 v[70:71], s[0:1], v125, s6, v[80:81]
	v_add_f32_e32 v40, v13, v40
	v_add_f32_e32 v77, v40, v41
	v_pk_mul_f32 v[40:41], v[64:65], v[74:75]
	s_nop 0
	v_add_f32_e32 v40, v14, v40
	v_add_f32_e32 v74, v40, v41
	v_pk_mul_f32 v[40:41], v[10:11], v[72:73]
	s_nop 0
	v_add_f32_e32 v40, v15, v40
	v_add_f32_e32 v72, v40, v41
	v_pk_mul_f32 v[40:41], v[88:89], v[62:63]
	s_nop 0
	v_add_f32_e32 v40, v24, v40
	v_add_f32_e32 v44, v40, v41
	v_lshlrev_b32_e32 v40, 16, v32
	v_lshlrev_b32_e32 v41, 16, v36
	v_pk_mov_b32 v[98:99], v[62:63], v[40:41] op_sel:[1,0]
	s_nop 0
	v_pk_mul_f32 v[42:43], v[86:87], v[98:99]
	s_nop 0
	v_add_f32_e32 v42, v94, v42
	v_add_f32_e32 v42, v42, v43
	v_mul_f32_e32 v43, 0xbfb8aa3b, v42
	v_exp_f32_e32 v43, v43
	s_nop 0
	v_add_f32_e32 v43, 1.0, v43
	v_rcp_f32_e32 v43, v43
	s_nop 0
	v_mul_f32_e32 v62, v42, v43
	v_pk_mul_f32 v[42:43], v[86:87], v[40:41]
	s_nop 0
	v_add_f32_e32 v42, v44, v42
	v_add_f32_e32 v42, v42, v43
	v_mul_f32_e32 v43, 0xbfb8aa3b, v42
	v_exp_f32_e32 v43, v43
	s_nop 0
	v_add_f32_e32 v43, 1.0, v43
	v_rcp_f32_e32 v43, v43
	s_nop 0
	v_mul_f32_e32 v73, v42, v43
	v_pk_mul_f32 v[42:43], v[20:21], v[58:59]
	s_nop 0
	v_add_f32_e32 v42, v25, v42
	v_add_f32_e32 v63, v42, v43
	v_and_b32_e32 v43, 0xffff0000, v36
	v_and_b32_e32 v42, 0xffff0000, v32
	v_pk_mov_b32 v[58:59], v[58:59], v[42:43] op_sel:[1,0]
	s_nop 0
	v_pk_mul_f32 v[44:45], v[16:17], v[58:59]
	s_nop 0
	v_add_f32_e32 v32, v95, v44
	v_add_f32_e32 v32, v32, v45
	v_mul_f32_e32 v36, 0xbfb8aa3b, v32
	v_exp_f32_e32 v36, v36
	v_pk_mul_f32 v[44:45], v[16:17], v[42:43]
	v_add_f32_e32 v36, 1.0, v36
	v_rcp_f32_e32 v36, v36
	s_nop 0
	v_mul_f32_e32 v32, v32, v36
	v_add_f32_e32 v36, v63, v44
	v_add_f32_e32 v36, v36, v45
	v_mul_f32_e32 v44, 0xbfb8aa3b, v36
	v_exp_f32_e32 v44, v44
	v_cvt_pk_bf16_f32 v32, v62, v32
	s_nop 0
	v_add_f32_e32 v44, 1.0, v44
	v_rcp_f32_e32 v44, v44
	s_nop 0
	v_mul_f32_e32 v75, v36, v44
	v_pk_mul_f32 v[44:45], v[84:85], v[56:57]
	s_nop 0
	v_add_f32_e32 v36, v26, v44
	v_add_f32_e32 v36, v36, v45
	v_lshlrev_b32_e32 v44, 16, v33
	v_lshlrev_b32_e32 v45, 16, v37
	v_pk_mov_b32 v[56:57], v[56:57], v[44:45] op_sel:[1,0]
	v_and_b32_e32 v37, 0xffff0000, v37
	v_pk_mul_f32 v[62:63], v[82:83], v[56:57]
	s_nop 0
	v_add_f32_e32 v62, v78, v62
	v_add_f32_e32 v62, v62, v63
	v_mul_f32_e32 v63, 0xbfb8aa3b, v62
	v_exp_f32_e32 v63, v63
	s_nop 0
	v_add_f32_e32 v63, 1.0, v63
	v_rcp_f32_e32 v63, v63
	s_nop 0
	v_mul_f32_e32 v78, v62, v63
	v_pk_mul_f32 v[62:63], v[82:83], v[44:45]
	s_nop 0
	v_add_f32_e32 v36, v36, v62
	v_add_f32_e32 v36, v36, v63
	v_mul_f32_e32 v62, 0xbfb8aa3b, v36
	v_exp_f32_e32 v62, v62
	s_nop 0
	v_add_f32_e32 v62, 1.0, v62
	v_rcp_f32_e32 v62, v62
	s_nop 0
	v_mul_f32_e32 v94, v36, v62
	v_pk_mul_f32 v[62:63], v[22:23], v[48:49]
	s_nop 0
	v_add_f32_e32 v36, v27, v62
	v_add_f32_e32 v62, v36, v63
	v_and_b32_e32 v36, 0xffff0000, v33
	v_pk_mov_b32 v[104:105], v[48:49], v[36:37] op_sel:[1,0]
	s_nop 0
	v_pk_mul_f32 v[48:49], v[18:19], v[104:105]
	s_nop 0
	v_add_f32_e32 v33, v79, v48
	v_add_f32_e32 v33, v33, v49
	v_mul_f32_e32 v48, 0xbfb8aa3b, v33
	v_exp_f32_e32 v48, v48
	s_nop 0
	v_add_f32_e32 v48, 1.0, v48
	v_rcp_f32_e32 v48, v48
	s_nop 0
	v_mul_f32_e32 v33, v33, v48
	v_pk_mul_f32 v[48:49], v[18:19], v[36:37]
	v_cvt_pk_bf16_f32 v33, v78, v33
	s_nop 0
	v_add_f32_e32 v48, v62, v48
	v_add_f32_e32 v48, v48, v49
	v_mul_f32_e32 v49, 0xbfb8aa3b, v48
	v_exp_f32_e32 v49, v49
	s_nop 0
	v_add_f32_e32 v49, 1.0, v49
	v_rcp_f32_e32 v49, v49
	s_nop 0
	v_mul_f32_e32 v78, v48, v49
	v_pk_mul_f32 v[48:49], v[68:69], v[54:55]
	s_nop 0
	v_add_f32_e32 v48, v12, v48
	v_add_f32_e32 v62, v48, v49
	v_lshlrev_b32_e32 v48, 16, v34
	v_lshlrev_b32_e32 v49, 16, v38
	v_pk_mov_b32 v[106:107], v[54:55], v[48:49] op_sel:[1,0]
	s_nop 0
	v_pk_mul_f32 v[54:55], v[66:67], v[106:107]
	s_nop 0
	v_add_f32_e32 v54, v76, v54
	v_add_f32_e32 v54, v54, v55
	v_mul_f32_e32 v55, 0xbfb8aa3b, v54
	v_exp_f32_e32 v55, v55
	s_nop 0
	v_add_f32_e32 v55, 1.0, v55
	v_rcp_f32_e32 v55, v55
	s_nop 0
	v_mul_f32_e32 v76, v54, v55
	v_pk_mul_f32 v[54:55], v[66:67], v[48:49]
	s_nop 0
	v_add_f32_e32 v54, v62, v54
	v_add_f32_e32 v54, v54, v55
	v_mul_f32_e32 v55, 0xbfb8aa3b, v54
	v_exp_f32_e32 v55, v55
	s_nop 0
	v_add_f32_e32 v55, 1.0, v55
	v_rcp_f32_e32 v55, v55
	s_nop 0
	v_mul_f32_e32 v79, v54, v55
	v_pk_mul_f32 v[54:55], v[8:9], v[52:53]
	s_nop 0
	v_add_f32_e32 v54, v13, v54
	v_add_f32_e32 v95, v54, v55
	v_and_b32_e32 v55, 0xffff0000, v38
	v_and_b32_e32 v54, 0xffff0000, v34
	v_pk_mov_b32 v[52:53], v[52:53], v[54:55] op_sel:[1,0]
	s_nop 0
	v_pk_mul_f32 v[62:63], v[4:5], v[52:53]
	s_nop 0
	v_add_f32_e32 v34, v77, v62
	v_add_f32_e32 v34, v34, v63
	v_mul_f32_e32 v38, 0xbfb8aa3b, v34
	v_exp_f32_e32 v38, v38
	v_pk_mul_f32 v[62:63], v[4:5], v[54:55]
	v_add_f32_e32 v38, 1.0, v38
	v_rcp_f32_e32 v38, v38
	s_nop 0
	v_mul_f32_e32 v34, v34, v38
	v_add_f32_e32 v38, v95, v62
	v_add_f32_e32 v38, v38, v63
	v_mul_f32_e32 v62, 0xbfb8aa3b, v38
	v_exp_f32_e32 v62, v62
; #define GAS __attribute__((address_space(1)))
; __device__ __forceinline__ void unpack8(const v4u v, float (&f)[8]) { f[0] = bflo(v.x); f[1] = bfhi(v.x); f[2] = bflo(v.y); f[3] = bfhi(v.y); f[4] = bflo(v.z); f[5] = bfhi(v.z); f[6] = bflo(v.w); f[7] = bfhi(v.w); }
; __device__ __forceinline__ v4u pack8(const float (&f)[8]) { v4u o; o.x = cvt_pk_bf16(f[0], f[1]); o.y = cvt_pk_bf16(f[2], f[3]); o.z = cvt_pk_bf16(f[4], f[5]); o.w = cvt_pk_bf16(f[6], f[7]); return o; }
; __device__ __forceinline__ float siluf_(float x) { return x * __builtin_amdgcn_rcpf(1.f + __expf(-x)); }
; __device__ __forceinline__ void phase_conv(const Params& P, int seg) {
;     ...
;         for (int hb = 0; hb < 2; ++hb) { v4u raw[8];
; #pragma unroll
;             for (int i = 0; i < 8; ++i) raw[i] = __builtin_nontemporal_load((const GAS v4u*)(proj + (size_t)(lr0 + hb * 8 + i) * NPROJ + OFF_XBC + c));
; #pragma unroll
;             for (int i = 0; i < 8; ++i) { unpack8(raw[i], x3); float y[8];
; #pragma unroll
;                 for (int e = 0; e < 8; ++e) { y[e] = siluf_(bb[e] + w0[e] * x0[e] + w1[e] * x1[e] + w2[e] * x2[e] + w3[e] * x3[e]); x0[e] = x1[e]; x1[e] = x2[e]; x2[e] = x3[e]; }
;                 *(GAS v4u*)(xconv + (size_t)(lr0 + hb * 8 + i) * DXBC + c) = pack8(y); } }
	v_cvt_pk_bf16_f32 v34, v76, v34
	v_and_b32_e32 v95, 0xffff0000, v28
	v_add_f32_e32 v62, 1.0, v62
	v_rcp_f32_e32 v62, v62
	s_nop 0
	v_mul_f32_e32 v76, v38, v62
	v_pk_mul_f32 v[62:63], v[64:65], v[50:51]
	v_pk_mov_b32 v[50:51], v[50:51], v[100:101] op_sel:[1,0]
	v_add_f32_e32 v38, v14, v62
	v_add_f32_e32 v38, v38, v63
	v_pk_mul_f32 v[62:63], v[60:61], v[50:51]
	s_nop 0
	v_add_f32_e32 v62, v74, v62
	v_add_f32_e32 v62, v62, v63
	v_mul_f32_e32 v63, 0xbfb8aa3b, v62
	v_exp_f32_e32 v63, v63
	s_nop 0
	v_add_f32_e32 v63, 1.0, v63
	v_rcp_f32_e32 v63, v63
	s_nop 0
	v_mul_f32_e32 v74, v62, v63
	v_pk_mul_f32 v[62:63], v[60:61], v[100:101]
	s_nop 0
	v_add_f32_e32 v38, v38, v62
	v_add_f32_e32 v38, v38, v63
	v_mul_f32_e32 v62, 0xbfb8aa3b, v38
	v_exp_f32_e32 v62, v62
	s_nop 0
	v_add_f32_e32 v62, 1.0, v62
	v_rcp_f32_e32 v62, v62
	s_nop 0
	v_mul_f32_e32 v77, v38, v62
	v_pk_mul_f32 v[62:63], v[10:11], v[46:47]
	s_nop 0
	v_add_f32_e32 v38, v15, v62
	v_add_f32_e32 v62, v38, v63
	v_pk_mov_b32 v[38:39], v[46:47], v[102:103] op_sel:[1,0]
	v_and_b32_e32 v63, 0xffff0000, v31
	v_pk_mul_f32 v[46:47], v[6:7], v[38:39]
	s_nop 0
	v_add_f32_e32 v35, v72, v46
	v_add_f32_e32 v35, v35, v47
	v_mul_f32_e32 v46, 0xbfb8aa3b, v35
	v_exp_f32_e32 v46, v46
	s_nop 0
	v_add_f32_e32 v46, 1.0, v46
	v_rcp_f32_e32 v46, v46
	s_nop 0
	v_mul_f32_e32 v35, v35, v46
	v_cvt_pk_bf16_f32 v35, v74, v35
	global_store_dwordx4 v[70:71], v[32:35], off
	v_mad_i64_i32 v[46:47], s[0:1], v124, s6, v[80:81]
	s_nop 0
	v_pk_mul_f32 v[32:33], v[6:7], v[102:103]
	v_lshlrev_b32_e32 v71, 16, v31
	v_add_f32_e32 v32, v62, v32
	v_add_f32_e32 v32, v32, v33
	v_mul_f32_e32 v33, 0xbfb8aa3b, v32
	v_exp_f32_e32 v33, v33
	v_mov_b32_e32 v70, v101
	v_add_f32_e32 v33, 1.0, v33
	v_rcp_f32_e32 v33, v33
	s_nop 0
	v_mul_f32_e32 v35, v32, v33
	v_cvt_pk_bf16_f32 v32, v73, v75
	v_cvt_pk_bf16_f32 v33, v94, v78
	v_cvt_pk_bf16_f32 v34, v79, v76
	v_cvt_pk_bf16_f32 v35, v77, v35
	v_lshlrev_b32_e32 v79, 16, v29
	v_and_b32_e32 v77, 0xffff0000, v29
	v_pk_mul_f32 v[28:29], v[88:89], v[98:99]
	v_or_b32_e32 v98, 8, v122
	v_add_f32_e32 v28, v24, v28
	v_add_f32_e32 v94, v28, v29
	v_pk_mul_f32 v[28:29], v[20:21], v[58:59]
	global_store_dwordx4 v[46:47], v[32:35], off
	v_add_f32_e32 v28, v25, v28
	v_add_f32_e32 v99, v28, v29
	v_pk_mul_f32 v[28:29], v[84:85], v[56:57]
	v_pk_mul_f32 v[58:59], v[88:89], v[40:41]
	v_add_f32_e32 v28, v26, v28
	v_add_f32_e32 v76, v28, v29
	v_pk_mul_f32 v[28:29], v[22:23], v[104:105]
	v_lshlrev_b32_e32 v75, 16, v30
	v_add_f32_e32 v28, v27, v28
	v_add_f32_e32 v96, v28, v29
	v_pk_mul_f32 v[28:29], v[68:69], v[106:107]
	v_or_b32_e32 v107, 14, v122
	v_add_f32_e32 v28, v12, v28
	v_add_f32_e32 v72, v28, v29
	v_pk_mul_f32 v[28:29], v[8:9], v[52:53]
	v_or_b32_e32 v106, 15, v122
	v_add_f32_e32 v28, v13, v28
	v_add_f32_e32 v78, v28, v29
	v_pk_mul_f32 v[28:29], v[64:65], v[50:51]
	v_and_b32_e32 v73, 0xffff0000, v30
	v_add_f32_e32 v28, v14, v28
	v_add_f32_e32 v62, v28, v29
	v_pk_mul_f32 v[28:29], v[10:11], v[38:39]
	v_mad_i64_i32 v[32:33], s[0:1], v106, s4, v[92:93]
	v_add_f32_e32 v28, v15, v28
	v_add_f32_e32 v74, v28, v29
	v_mad_i64_i32 v[28:29], s[0:1], v98, s4, v[92:93]
	v_lshl_add_u64 v[56:57], v[28:29], 0, v[90:91]
	v_mad_i64_i32 v[28:29], s[0:1], v112, s4, v[92:93]
	v_lshl_add_u64 v[50:51], v[28:29], 0, v[90:91]
	v_mad_i64_i32 v[28:29], s[0:1], v111, s4, v[92:93]
	v_lshl_add_u64 v[46:47], v[28:29], 0, v[90:91]
	v_mad_i64_i32 v[28:29], s[0:1], v110, s4, v[92:93]
	v_lshl_add_u64 v[38:39], v[28:29], 0, v[90:91]
	v_mad_i64_i32 v[28:29], s[0:1], v109, s4, v[92:93]
	v_lshl_add_u64 v[34:35], v[28:29], 0, v[90:91]
	v_mad_i64_i32 v[28:29], s[0:1], v108, s4, v[92:93]
	v_lshl_add_u64 v[30:31], v[28:29], 0, v[90:91]
	v_mad_i64_i32 v[28:29], s[0:1], v107, s4, v[92:93]
	v_add_f32_e32 v40, v24, v58
	v_lshl_add_u64 v[28:29], v[28:29], 0, v[90:91]
	v_lshl_add_u64 v[32:33], v[32:33], 0, v[90:91]
	v_add_f32_e32 v90, v40, v59
	v_pk_mul_f32 v[58:59], v[20:21], v[42:43]
	v_mad_i64_i32 v[52:53], s[0:1], v123, s6, v[80:81]
	v_add_f32_e32 v40, v25, v58
	v_add_f32_e32 v92, v40, v59
	v_pk_mul_f32 v[58:59], v[84:85], v[44:45]
	s_nop 0
	v_add_f32_e32 v40, v26, v58
	v_add_f32_e32 v105, v40, v59
	v_pk_mul_f32 v[58:59], v[22:23], v[36:37]
	s_nop 0
	v_add_f32_e32 v36, v27, v58
	v_add_f32_e32 v104, v36, v59
	v_pk_mul_f32 v[58:59], v[68:69], v[48:49]
	s_nop 0
	v_add_f32_e32 v36, v12, v58
	v_add_f32_e32 v116, v36, v59
	v_pk_mul_f32 v[58:59], v[8:9], v[54:55]
	s_nop 0
	v_add_f32_e32 v36, v13, v58
	v_add_f32_e32 v114, v36, v59
	v_pk_mul_f32 v[58:59], v[64:65], v[100:101]
	v_mad_i64_i32 v[100:101], s[0:1], v98, s6, v[80:81]
	v_add_f32_e32 v36, v14, v58
	v_add_f32_e32 v113, v36, v59
	v_pk_mul_f32 v[58:59], v[60:61], v[70:71]
	s_nop 0
	v_add_f32_e32 v36, v62, v58
	v_add_f32_e32 v36, v36, v59
	v_mul_f32_e32 v40, 0xbfb8aa3b, v36
	v_exp_f32_e32 v40, v40
	v_pk_mul_f32 v[58:59], v[10:11], v[102:103]
	v_mov_b32_e32 v62, v103
	v_add_f32_e32 v40, 1.0, v40
	v_rcp_f32_e32 v40, v40
	s_nop 0
	v_mul_f32_e32 v54, v36, v40
	v_add_f32_e32 v36, v15, v58
	v_add_f32_e32 v115, v36, v59
	v_pk_mul_f32 v[58:59], v[6:7], v[62:63]
	s_nop 0
	v_add_f32_e32 v36, v74, v58
	v_add_f32_e32 v36, v36, v59
	v_mul_f32_e32 v40, 0xbfb8aa3b, v36
	v_exp_f32_e32 v40, v40
	v_mov_b32_e32 v74, v49
	v_pk_mul_f32 v[48:49], v[66:67], v[74:75]
	v_add_f32_e32 v40, 1.0, v40
	v_rcp_f32_e32 v40, v40
	s_nop 0
	v_mul_f32_e32 v58, v36, v40
	v_add_f32_e32 v36, v72, v48
	v_add_f32_e32 v36, v36, v49
	v_mul_f32_e32 v40, 0xbfb8aa3b, v36
	v_exp_f32_e32 v40, v40
	v_mov_b32_e32 v72, v55
	v_pk_mul_f32 v[48:49], v[4:5], v[72:73]
	v_add_f32_e32 v40, 1.0, v40
	v_rcp_f32_e32 v40, v40
	s_nop 0
	v_mul_f32_e32 v42, v36, v40
; #define GAS __attribute__((address_space(1)))
; __device__ __forceinline__ void unpack8(const v4u v, float (&f)[8]) { f[0] = bflo(v.x); f[1] = bfhi(v.x); f[2] = bflo(v.y); f[3] = bfhi(v.y); f[4] = bflo(v.z); f[5] = bfhi(v.z); f[6] = bflo(v.w); f[7] = bfhi(v.w); }
; __device__ __forceinline__ v4u pack8(const float (&f)[8]) { v4u o; o.x = cvt_pk_bf16(f[0], f[1]); o.y = cvt_pk_bf16(f[2], f[3]); o.z = cvt_pk_bf16(f[4], f[5]); o.w = cvt_pk_bf16(f[6], f[7]); return o; }
; __device__ __forceinline__ float siluf_(float x) { return x * __builtin_amdgcn_rcpf(1.f + __expf(-x)); }
; __device__ __forceinline__ void phase_conv(const Params& P, int seg) {
;     ...
;         for (int hb = 0; hb < 2; ++hb) { v4u raw[8];
; #pragma unroll
;             for (int i = 0; i < 8; ++i) raw[i] = __builtin_nontemporal_load((const GAS v4u*)(proj + (size_t)(lr0 + hb * 8 + i) * NPROJ + OFF_XBC + c));
; #pragma unroll
;             for (int i = 0; i < 8; ++i) { unpack8(raw[i], x3); float y[8];
; #pragma unroll
;                 for (int e = 0; e < 8; ++e) { y[e] = siluf_(bb[e] + w0[e] * x0[e] + w1[e] * x1[e] + w2[e] * x2[e] + w3[e] * x3[e]); x0[e] = x1[e]; x1[e] = x2[e]; x2[e] = x3[e]; }
;                 *(GAS v4u*)(xconv + (size_t)(lr0 + hb * 8 + i) * DXBC + c) = pack8(y); } }
	v_add_f32_e32 v36, v78, v48
	v_add_f32_e32 v36, v36, v49
	v_mul_f32_e32 v40, 0xbfb8aa3b, v36
	v_exp_f32_e32 v40, v40
	v_mov_b32_e32 v78, v45
	v_pk_mul_f32 v[44:45], v[82:83], v[78:79]
	v_add_f32_e32 v40, 1.0, v40
	v_rcp_f32_e32 v40, v40
	s_nop 0
	v_mul_f32_e32 v48, v36, v40
	v_add_f32_e32 v36, v76, v44
	v_add_f32_e32 v36, v36, v45
	v_mul_f32_e32 v40, 0xbfb8aa3b, v36
	v_exp_f32_e32 v40, v40
	v_mov_b32_e32 v76, v37
	v_add_f32_e32 v40, 1.0, v40
	v_rcp_f32_e32 v40, v40
	s_nop 0
	v_mul_f32_e32 v44, v36, v40
	v_pk_mul_f32 v[36:37], v[18:19], v[76:77]
	s_nop 0
	v_add_f32_e32 v36, v96, v36
	v_add_f32_e32 v36, v36, v37
	v_mul_f32_e32 v37, 0xbfb8aa3b, v36
	v_exp_f32_e32 v37, v37
	v_mov_b32_e32 v96, v41
	v_add_f32_e32 v37, 1.0, v37
	v_rcp_f32_e32 v37, v37
	s_nop 0
	v_mul_f32_e32 v45, v36, v37
	v_pk_mul_f32 v[36:37], v[86:87], v[96:97]
	s_nop 0
	v_add_f32_e32 v36, v94, v36
	v_add_f32_e32 v36, v36, v37
	v_mul_f32_e32 v37, 0xbfb8aa3b, v36
	v_exp_f32_e32 v37, v37
	v_mov_b32_e32 v94, v43
	v_add_f32_e32 v37, 1.0, v37
	v_rcp_f32_e32 v37, v37
	s_nop 0
	v_mul_f32_e32 v40, v36, v37
	v_pk_mul_f32 v[36:37], v[16:17], v[94:95]
	s_nop 0
	v_add_f32_e32 v36, v99, v36
	v_add_f32_e32 v36, v36, v37
	v_mul_f32_e32 v37, 0xbfb8aa3b, v36
	v_exp_f32_e32 v37, v37
	v_pk_mul_f32 v[98:99], v[88:89], v[96:97]
	v_mov_b32_e32 v96, v97
	v_add_f32_e32 v91, v24, v98
	v_add_f32_e32 v37, 1.0, v37
	v_rcp_f32_e32 v37, v37
	v_add_f32_e32 v93, v91, v99
	v_mul_f32_e32 v36, v36, v37
	v_cvt_pk_bf16_f32 v40, v40, v36
	v_add_co_u32_e32 v36, vcc, s5, v56
	v_cvt_pk_bf16_f32 v41, v44, v45
	v_cvt_pk_bf16_f32 v42, v42, v48
	v_cvt_pk_bf16_f32 v43, v54, v58
	global_store_dwordx4 v[52:53], v[40:43], off
	s_nop 0
	v_addc_co_u32_e32 v37, vcc, 0, v57, vcc
	s_nop 0
	v_add_co_u32_e32 v36, vcc, s5, v50
	s_waitcnt vmcnt(15)
	v_lshlrev_b32_e32 v98, 16, v234
	v_addc_co_u32_e32 v37, vcc, 0, v51, vcc
	s_nop 0
	v_mov_b32_e32 v97, v98
	v_pk_mul_f32 v[102:103], v[86:87], v[96:97]
	v_add_co_u32_e32 v36, vcc, s5, v46
	v_add_f32_e32 v90, v90, v102
	v_add_f32_e32 v90, v90, v103
	v_mul_f32_e32 v91, 0xbfb8aa3b, v90
	v_exp_f32_e32 v91, v91
	v_addc_co_u32_e32 v37, vcc, 0, v47, vcc
	s_nop 0
	v_add_f32_e32 v91, 1.0, v91
	v_rcp_f32_e32 v91, v91
	v_add_co_u32_e32 v36, vcc, s5, v38
	v_mul_f32_e32 v117, v90, v91
	s_nop 0
	v_addc_co_u32_e32 v37, vcc, 0, v39, vcc
	v_add_co_u32_e32 v34, vcc, s5, v34
	s_nop 0
	s_nop 0
	v_addc_co_u32_e32 v35, vcc, 0, v35, vcc
	v_add_co_u32_e32 v30, vcc, s5, v30
	s_nop 0
	s_nop 0
	v_addc_co_u32_e32 v31, vcc, 0, v31, vcc
	v_add_co_u32_e32 v28, vcc, s5, v28
	s_nop 0
	s_nop 0
	v_addc_co_u32_e32 v29, vcc, 0, v29, vcc
	v_add_co_u32_e32 v32, vcc, s5, v32
	s_nop 0
	s_nop 0
	v_addc_co_u32_e32 v33, vcc, 0, v33, vcc
	s_nop 0
	v_cmp_le_i32_e32 vcc, s16, v121
	s_or_b64 s[56:57], vcc, s[56:57]
	s_waitcnt vmcnt(14)
	v_lshlrev_b32_e32 v99, 16, v230
	v_pk_mul_f32 v[90:91], v[86:87], v[98:99]
	s_nop 0
	v_add_f32_e32 v90, v93, v90
	v_add_f32_e32 v90, v90, v91
	v_mul_f32_e32 v91, 0xbfb8aa3b, v90
	v_exp_f32_e32 v91, v91
	s_nop 0
	v_add_f32_e32 v91, 1.0, v91
	v_rcp_f32_e32 v91, v91
	s_nop 0
	v_mul_f32_e32 v122, v90, v91
	v_pk_mul_f32 v[90:91], v[20:21], v[94:95]
	v_mov_b32_e32 v94, v95
	v_add_f32_e32 v90, v25, v90
	v_add_f32_e32 v118, v90, v91
	v_and_b32_e32 v90, 0xffff0000, v234
	v_mov_b32_e32 v95, v90
	v_pk_mul_f32 v[102:103], v[16:17], v[94:95]
	v_and_b32_e32 v91, 0xffff0000, v230
	v_add_f32_e32 v52, v92, v102
	v_add_f32_e32 v52, v52, v103
	v_mul_f32_e32 v56, 0xbfb8aa3b, v52
	v_exp_f32_e32 v56, v56
	v_pk_mul_f32 v[92:93], v[16:17], v[90:91]
	v_add_f32_e32 v56, 1.0, v56
	v_rcp_f32_e32 v56, v56
	s_nop 0
	v_mul_f32_e32 v52, v52, v56
	v_add_f32_e32 v56, v118, v92
	v_add_f32_e32 v56, v56, v93
	v_mul_f32_e32 v92, 0xbfb8aa3b, v56
	v_exp_f32_e32 v92, v92
	v_cvt_pk_bf16_f32 v52, v117, v52
	s_nop 0
	v_add_f32_e32 v92, 1.0, v92
	v_rcp_f32_e32 v92, v92
	s_nop 0
	v_mul_f32_e32 v123, v56, v92
	v_pk_mul_f32 v[92:93], v[84:85], v[78:79]
	v_mov_b32_e32 v78, v79
	v_add_f32_e32 v56, v26, v92
	v_lshlrev_b32_e32 v92, 16, v235
	v_mov_b32_e32 v79, v92
	v_pk_mul_f32 v[102:103], v[82:83], v[78:79]
	v_add_f32_e32 v56, v56, v93
	v_add_f32_e32 v102, v105, v102
	v_add_f32_e32 v102, v102, v103
	v_mul_f32_e32 v103, 0xbfb8aa3b, v102
	v_exp_f32_e32 v103, v103
	v_lshlrev_b32_e32 v93, 16, v231
	v_and_b32_e32 v57, 0xffff0000, v231
	v_add_f32_e32 v103, 1.0, v103
	v_rcp_f32_e32 v103, v103
	s_nop 0
	v_mul_f32_e32 v105, v102, v103
	v_pk_mul_f32 v[102:103], v[82:83], v[92:93]
	s_nop 0
	v_add_f32_e32 v56, v56, v102
	v_add_f32_e32 v56, v56, v103
	v_mul_f32_e32 v102, 0xbfb8aa3b, v56
	v_exp_f32_e32 v102, v102
	s_nop 0
	v_add_f32_e32 v102, 1.0, v102
	v_rcp_f32_e32 v102, v102
	s_nop 0
	v_mul_f32_e32 v124, v56, v102
	v_pk_mul_f32 v[102:103], v[22:23], v[76:77]
	s_nop 0
	v_add_f32_e32 v56, v27, v102
	v_add_f32_e32 v117, v56, v103
	v_and_b32_e32 v56, 0xffff0000, v235
	v_mov_b32_e32 v102, v77
	v_mov_b32_e32 v103, v56
	v_pk_mul_f32 v[76:77], v[18:19], v[102:103]
	s_nop 0
	v_add_f32_e32 v53, v104, v76
	v_add_f32_e32 v53, v53, v77
	v_mul_f32_e32 v76, 0xbfb8aa3b, v53
	v_exp_f32_e32 v76, v76
	v_mov_b32_e32 v104, v75
	v_add_f32_e32 v76, 1.0, v76
	v_rcp_f32_e32 v76, v76
	s_nop 0
	v_mul_f32_e32 v53, v53, v76
	v_pk_mul_f32 v[76:77], v[18:19], v[56:57]
	v_cvt_pk_bf16_f32 v53, v105, v53
	s_nop 0
	v_add_f32_e32 v76, v117, v76
	v_add_f32_e32 v76, v76, v77
	v_mul_f32_e32 v77, 0xbfb8aa3b, v76
	v_exp_f32_e32 v77, v77
	s_nop 0
	v_add_f32_e32 v77, 1.0, v77
	v_rcp_f32_e32 v77, v77
	s_nop 0
	v_mul_f32_e32 v125, v76, v77
	v_pk_mul_f32 v[76:77], v[68:69], v[74:75]
	s_nop 0
	v_add_f32_e32 v74, v12, v76
	v_lshlrev_b32_e32 v76, 16, v236
	v_mov_b32_e32 v105, v76
	v_add_f32_e32 v117, v74, v77
; #define GAS __attribute__((address_space(1)))
; __device__ __forceinline__ void unpack8(const v4u v, float (&f)[8]) { f[0] = bflo(v.x); f[1] = bfhi(v.x); f[2] = bflo(v.y); f[3] = bfhi(v.y); f[4] = bflo(v.z); f[5] = bfhi(v.z); f[6] = bflo(v.w); f[7] = bfhi(v.w); }
; __device__ __forceinline__ v4u pack8(const float (&f)[8]) { v4u o; o.x = cvt_pk_bf16(f[0], f[1]); o.y = cvt_pk_bf16(f[2], f[3]); o.z = cvt_pk_bf16(f[4], f[5]); o.w = cvt_pk_bf16(f[6], f[7]); return o; }
; __device__ __forceinline__ float siluf_(float x) { return x * __builtin_amdgcn_rcpf(1.f + __expf(-x)); }
; __device__ __forceinline__ void phase_conv(const Params& P, int seg) {
;     ...
;             for (int i = 0; i < 8; ++i) { unpack8(raw[i], x3); float y[8];
; #pragma unroll
;                 for (int e = 0; e < 8; ++e) { y[e] = siluf_(bb[e] + w0[e] * x0[e] + w1[e] * x1[e] + w2[e] * x2[e] + w3[e] * x3[e]); x0[e] = x1[e]; x1[e] = x2[e]; x2[e] = x3[e]; }
;                 *(GAS v4u*)(xconv + (size_t)(lr0 + hb * 8 + i) * DXBC + c) = pack8(y); } }
	v_pk_mul_f32 v[74:75], v[66:67], v[104:105]
	v_lshlrev_b32_e32 v77, 16, v232
	v_add_f32_e32 v74, v116, v74
	v_add_f32_e32 v74, v74, v75
	v_mul_f32_e32 v75, 0xbfb8aa3b, v74
	v_exp_f32_e32 v75, v75
	v_mov_b32_e32 v116, v73
	v_add_f32_e32 v75, 1.0, v75
	v_rcp_f32_e32 v75, v75
	s_nop 0
	v_mul_f32_e32 v118, v74, v75
	v_pk_mul_f32 v[74:75], v[66:67], v[76:77]
	s_nop 0
	v_add_f32_e32 v74, v117, v74
	v_add_f32_e32 v74, v74, v75
	v_mul_f32_e32 v75, 0xbfb8aa3b, v74
	v_exp_f32_e32 v75, v75
	s_nop 0
	v_add_f32_e32 v75, 1.0, v75
	v_rcp_f32_e32 v75, v75
	s_nop 0
	v_mul_f32_e32 v126, v74, v75
	v_pk_mul_f32 v[74:75], v[8:9], v[72:73]
	s_nop 0
	v_add_f32_e32 v72, v13, v74
	v_and_b32_e32 v74, 0xffff0000, v236
	v_mov_b32_e32 v117, v74
	v_add_f32_e32 v119, v72, v75
	v_pk_mul_f32 v[72:73], v[4:5], v[116:117]
	v_and_b32_e32 v75, 0xffff0000, v232
	v_add_f32_e32 v54, v114, v72
	v_add_f32_e32 v54, v54, v73
	v_mul_f32_e32 v58, 0xbfb8aa3b, v54
	v_exp_f32_e32 v58, v58
	v_pk_mul_f32 v[72:73], v[4:5], v[74:75]
	v_add_f32_e32 v58, 1.0, v58
	v_rcp_f32_e32 v58, v58
	s_nop 0
	v_mul_f32_e32 v54, v54, v58
	v_add_f32_e32 v58, v119, v72
	v_add_f32_e32 v58, v58, v73
	v_mul_f32_e32 v72, 0xbfb8aa3b, v58
	v_exp_f32_e32 v72, v72
	v_cvt_pk_bf16_f32 v54, v118, v54
	s_nop 0
	v_add_f32_e32 v72, 1.0, v72
	v_rcp_f32_e32 v72, v72
	s_nop 0
	v_mul_f32_e32 v114, v58, v72
	v_pk_mul_f32 v[72:73], v[64:65], v[70:71]
	v_mov_b32_e32 v70, v71
	v_add_f32_e32 v58, v14, v72
	v_lshlrev_b32_e32 v72, 16, v237
	v_mov_b32_e32 v71, v72
	v_pk_mul_f32 v[118:119], v[60:61], v[70:71]
	v_add_f32_e32 v58, v58, v73
	v_add_f32_e32 v113, v113, v118
	v_add_f32_e32 v113, v113, v119
	v_mul_f32_e32 v118, 0xbfb8aa3b, v113
	v_exp_f32_e32 v118, v118
	v_lshlrev_b32_e32 v73, 16, v233
	v_and_b32_e32 v59, 0xffff0000, v233
	v_add_f32_e32 v118, 1.0, v118
	v_rcp_f32_e32 v118, v118
	s_nop 0
	v_mul_f32_e32 v113, v113, v118
	v_pk_mul_f32 v[118:119], v[60:61], v[72:73]
	s_nop 0
	v_add_f32_e32 v58, v58, v118
	v_add_f32_e32 v58, v58, v119
	v_mul_f32_e32 v118, 0xbfb8aa3b, v58
	v_exp_f32_e32 v118, v118
	s_nop 0
	v_add_f32_e32 v118, 1.0, v118
	v_rcp_f32_e32 v118, v118
	s_nop 0
	v_mul_f32_e32 v127, v58, v118
	v_pk_mul_f32 v[118:119], v[10:11], v[62:63]
	v_mov_b32_e32 v62, v63
	v_add_f32_e32 v58, v15, v118
	v_add_f32_e32 v128, v58, v119
	v_and_b32_e32 v58, 0xffff0000, v237
	v_mov_b32_e32 v63, v58
	v_pk_mul_f32 v[118:119], v[6:7], v[62:63]
	s_nop 0
	v_add_f32_e32 v55, v115, v118
	v_add_f32_e32 v55, v55, v119
	v_mul_f32_e32 v115, 0xbfb8aa3b, v55
	v_exp_f32_e32 v115, v115
	s_nop 0
	v_add_f32_e32 v115, 1.0, v115
	v_rcp_f32_e32 v115, v115
	s_nop 0
	v_mul_f32_e32 v55, v55, v115
	v_cvt_pk_bf16_f32 v55, v113, v55
	global_store_dwordx4 v[100:101], v[52:55], off
	v_mad_i64_i32 v[100:101], s[0:1], v112, s6, v[80:81]
	s_nop 0
	v_pk_mul_f32 v[52:53], v[6:7], v[58:59]
	s_nop 0
	v_add_f32_e32 v52, v128, v52
	v_add_f32_e32 v52, v52, v53
	v_mul_f32_e32 v53, 0xbfb8aa3b, v52
	v_exp_f32_e32 v53, v53
	s_nop 0
	v_add_f32_e32 v53, 1.0, v53
	v_rcp_f32_e32 v53, v53
	s_nop 0
	v_mul_f32_e32 v55, v52, v53
	v_cvt_pk_bf16_f32 v52, v122, v123
	v_cvt_pk_bf16_f32 v53, v124, v125
	v_cvt_pk_bf16_f32 v54, v126, v114
	v_cvt_pk_bf16_f32 v55, v127, v55
	global_store_dwordx4 v[100:101], v[52:55], off
	s_nop 1
	v_pk_mul_f32 v[52:53], v[88:89], v[96:97]
	s_waitcnt vmcnt(14)
	v_lshlrev_b32_e32 v55, 16, v222
	v_add_f32_e32 v52, v24, v52
	v_add_f32_e32 v100, v52, v53
	v_pk_mul_f32 v[52:53], v[20:21], v[94:95]
	v_lshlrev_b32_e32 v54, 16, v226
	v_add_f32_e32 v52, v25, v52
	v_add_f32_e32 v101, v52, v53
	v_pk_mul_f32 v[52:53], v[84:85], v[78:79]
	v_pk_mov_b32 v[94:95], v[98:99], v[54:55] op_sel:[1,0]
	v_add_f32_e32 v52, v26, v52
	v_add_f32_e32 v78, v52, v53
	v_pk_mul_f32 v[52:53], v[22:23], v[102:103]
	v_mad_i64_i32 v[96:97], s[0:1], v111, s6, v[80:81]
	v_add_f32_e32 v52, v27, v52
	v_add_f32_e32 v79, v52, v53
	v_pk_mul_f32 v[52:53], v[68:69], v[104:105]
	s_nop 0
	v_add_f32_e32 v52, v12, v52
	v_add_f32_e32 v102, v52, v53
	v_pk_mul_f32 v[52:53], v[8:9], v[116:117]
	s_nop 0
	v_add_f32_e32 v52, v13, v52
	v_add_f32_e32 v103, v52, v53
	v_pk_mul_f32 v[52:53], v[64:65], v[70:71]
	s_nop 0
	v_add_f32_e32 v52, v14, v52
	v_add_f32_e32 v104, v52, v53
	v_pk_mul_f32 v[52:53], v[10:11], v[62:63]
	s_nop 0
	v_add_f32_e32 v52, v15, v52
	v_add_f32_e32 v105, v52, v53
	v_pk_mul_f32 v[52:53], v[88:89], v[98:99]
	s_nop 0
	v_add_f32_e32 v52, v24, v52
	v_add_f32_e32 v62, v52, v53
	v_pk_mul_f32 v[52:53], v[86:87], v[94:95]
	s_nop 0
	v_add_f32_e32 v52, v100, v52
	v_add_f32_e32 v52, v52, v53
	v_mul_f32_e32 v53, 0xbfb8aa3b, v52
	v_exp_f32_e32 v53, v53
	s_nop 0
	v_add_f32_e32 v53, 1.0, v53
	v_rcp_f32_e32 v53, v53
	s_nop 0
	v_mul_f32_e32 v70, v52, v53
	v_pk_mul_f32 v[52:53], v[86:87], v[54:55]
	s_nop 0
	v_add_f32_e32 v52, v62, v52
	v_add_f32_e32 v52, v52, v53
	v_mul_f32_e32 v53, 0xbfb8aa3b, v52
	v_exp_f32_e32 v53, v53
	s_nop 0
	v_add_f32_e32 v53, 1.0, v53
	v_rcp_f32_e32 v53, v53
	s_nop 0
	v_mul_f32_e32 v111, v52, v53
	v_pk_mul_f32 v[52:53], v[20:21], v[90:91]
	s_nop 0
	v_add_f32_e32 v52, v25, v52
	v_add_f32_e32 v71, v52, v53
	v_and_b32_e32 v53, 0xffff0000, v222
	v_and_b32_e32 v52, 0xffff0000, v226
	v_pk_mov_b32 v[98:99], v[90:91], v[52:53] op_sel:[1,0]
	v_lshlrev_b32_e32 v91, 16, v223
	v_pk_mul_f32 v[62:63], v[16:17], v[98:99]
	v_lshlrev_b32_e32 v90, 16, v227
	v_add_f32_e32 v44, v101, v62
	v_add_f32_e32 v44, v44, v63
	v_mul_f32_e32 v48, 0xbfb8aa3b, v44
	v_exp_f32_e32 v48, v48
	v_pk_mul_f32 v[62:63], v[16:17], v[52:53]
	v_and_b32_e32 v49, 0xffff0000, v223
	v_add_f32_e32 v48, 1.0, v48
	v_rcp_f32_e32 v48, v48
	s_nop 0
	v_mul_f32_e32 v44, v44, v48
	v_add_f32_e32 v48, v71, v62
	v_add_f32_e32 v48, v48, v63
; #define GAS __attribute__((address_space(1)))
; __device__ __forceinline__ void unpack8(const v4u v, float (&f)[8]) { f[0] = bflo(v.x); f[1] = bfhi(v.x); f[2] = bflo(v.y); f[3] = bfhi(v.y); f[4] = bflo(v.z); f[5] = bfhi(v.z); f[6] = bflo(v.w); f[7] = bfhi(v.w); }
; __device__ __forceinline__ v4u pack8(const float (&f)[8]) { v4u o; o.x = cvt_pk_bf16(f[0], f[1]); o.y = cvt_pk_bf16(f[2], f[3]); o.z = cvt_pk_bf16(f[4], f[5]); o.w = cvt_pk_bf16(f[6], f[7]); return o; }
; __device__ __forceinline__ float siluf_(float x) { return x * __builtin_amdgcn_rcpf(1.f + __expf(-x)); }
; __device__ __forceinline__ void phase_conv(const Params& P, int seg) {
;     ...
;             for (int i = 0; i < 8; ++i) { unpack8(raw[i], x3); float y[8];
; #pragma unroll
;                 for (int e = 0; e < 8; ++e) { y[e] = siluf_(bb[e] + w0[e] * x0[e] + w1[e] * x1[e] + w2[e] * x2[e] + w3[e] * x3[e]); x0[e] = x1[e]; x1[e] = x2[e]; x2[e] = x3[e]; }
;                 *(GAS v4u*)(xconv + (size_t)(lr0 + hb * 8 + i) * DXBC + c) = pack8(y); } }
	v_mul_f32_e32 v62, 0xbfb8aa3b, v48
	v_exp_f32_e32 v62, v62
	v_cvt_pk_bf16_f32 v44, v70, v44
	s_nop 0
	v_add_f32_e32 v62, 1.0, v62
	v_rcp_f32_e32 v62, v62
	s_nop 0
	v_mul_f32_e32 v112, v48, v62
	v_pk_mul_f32 v[62:63], v[84:85], v[92:93]
	v_pk_mov_b32 v[92:93], v[92:93], v[90:91] op_sel:[1,0]
	v_add_f32_e32 v48, v26, v62
	v_add_f32_e32 v48, v48, v63
	v_pk_mul_f32 v[62:63], v[82:83], v[92:93]
	s_nop 0
	v_add_f32_e32 v62, v78, v62
	v_add_f32_e32 v62, v62, v63
	v_mul_f32_e32 v63, 0xbfb8aa3b, v62
	v_exp_f32_e32 v63, v63
	v_lshlrev_b32_e32 v78, 16, v228
	v_add_f32_e32 v63, 1.0, v63
	v_rcp_f32_e32 v63, v63
	s_nop 0
	v_mul_f32_e32 v70, v62, v63
	v_pk_mul_f32 v[62:63], v[82:83], v[90:91]
	s_nop 0
	v_add_f32_e32 v48, v48, v62
	v_add_f32_e32 v48, v48, v63
	v_mul_f32_e32 v62, 0xbfb8aa3b, v48
	v_exp_f32_e32 v62, v62
	s_nop 0
	v_add_f32_e32 v62, 1.0, v62
	v_rcp_f32_e32 v62, v62
	s_nop 0
	v_mul_f32_e32 v113, v48, v62
	v_pk_mul_f32 v[62:63], v[22:23], v[56:57]
	s_nop 0
	v_add_f32_e32 v48, v27, v62
	v_add_f32_e32 v71, v48, v63
	v_and_b32_e32 v48, 0xffff0000, v227
	v_pk_mov_b32 v[56:57], v[56:57], v[48:49] op_sel:[1,0]
	s_nop 0
	v_pk_mul_f32 v[62:63], v[18:19], v[56:57]
	s_nop 0
	v_add_f32_e32 v45, v79, v62
	v_add_f32_e32 v45, v45, v63
	v_mul_f32_e32 v62, 0xbfb8aa3b, v45
	v_exp_f32_e32 v62, v62
	v_lshlrev_b32_e32 v79, 16, v224
	v_add_f32_e32 v62, 1.0, v62
	v_rcp_f32_e32 v62, v62
	s_nop 0
	v_mul_f32_e32 v45, v45, v62
	v_pk_mul_f32 v[62:63], v[18:19], v[48:49]
	v_cvt_pk_bf16_f32 v45, v70, v45
	s_nop 0
	v_add_f32_e32 v62, v71, v62
	v_add_f32_e32 v62, v62, v63
	v_mul_f32_e32 v63, 0xbfb8aa3b, v62
	v_exp_f32_e32 v63, v63
	s_nop 0
	v_add_f32_e32 v63, 1.0, v63
	v_rcp_f32_e32 v63, v63
	s_nop 0
	v_mul_f32_e32 v114, v62, v63
	v_pk_mul_f32 v[62:63], v[68:69], v[76:77]
	v_pk_mov_b32 v[76:77], v[76:77], v[78:79] op_sel:[1,0]
	v_add_f32_e32 v62, v12, v62
	v_add_f32_e32 v70, v62, v63
	v_pk_mul_f32 v[62:63], v[66:67], v[76:77]
	s_nop 0
	v_add_f32_e32 v62, v102, v62
	v_add_f32_e32 v62, v62, v63
	v_mul_f32_e32 v63, 0xbfb8aa3b, v62
	v_exp_f32_e32 v63, v63
	s_nop 0
	v_add_f32_e32 v63, 1.0, v63
	v_rcp_f32_e32 v63, v63
	s_nop 0
	v_mul_f32_e32 v102, v62, v63
	v_pk_mul_f32 v[62:63], v[66:67], v[78:79]
	s_nop 0
	v_add_f32_e32 v62, v70, v62
	v_add_f32_e32 v62, v62, v63
	v_mul_f32_e32 v63, 0xbfb8aa3b, v62
	v_exp_f32_e32 v63, v63
	s_nop 0
	v_add_f32_e32 v63, 1.0, v63
	v_rcp_f32_e32 v63, v63
	s_nop 0
	v_mul_f32_e32 v115, v62, v63
	v_pk_mul_f32 v[62:63], v[8:9], v[74:75]
	s_nop 0
	v_add_f32_e32 v62, v13, v62
	v_add_f32_e32 v116, v62, v63
	v_and_b32_e32 v63, 0xffff0000, v224
	v_and_b32_e32 v62, 0xffff0000, v228
	v_pk_mov_b32 v[100:101], v[74:75], v[62:63] op_sel:[1,0]
	v_lshlrev_b32_e32 v75, 16, v225
	v_pk_mul_f32 v[70:71], v[4:5], v[100:101]
	v_lshlrev_b32_e32 v74, 16, v229
	v_add_f32_e32 v46, v103, v70
	v_add_f32_e32 v46, v46, v71
	v_mul_f32_e32 v50, 0xbfb8aa3b, v46
	v_exp_f32_e32 v50, v50
	v_pk_mul_f32 v[70:71], v[4:5], v[62:63]
	v_add_f32_e32 v50, 1.0, v50
	v_rcp_f32_e32 v50, v50
	s_nop 0
	v_mul_f32_e32 v46, v46, v50
	v_add_f32_e32 v50, v116, v70
	v_add_f32_e32 v50, v50, v71
	v_mul_f32_e32 v70, 0xbfb8aa3b, v50
	v_exp_f32_e32 v70, v70
	v_cvt_pk_bf16_f32 v46, v102, v46
	s_nop 0
	v_add_f32_e32 v70, 1.0, v70
	v_rcp_f32_e32 v70, v70
	s_nop 0
	v_mul_f32_e32 v102, v50, v70
	v_pk_mul_f32 v[70:71], v[64:65], v[72:73]
	v_pk_mov_b32 v[72:73], v[72:73], v[74:75] op_sel:[1,0]
	v_add_f32_e32 v50, v14, v70
	v_add_f32_e32 v50, v50, v71
	v_pk_mul_f32 v[70:71], v[60:61], v[72:73]
	s_nop 0
	v_add_f32_e32 v70, v104, v70
	v_add_f32_e32 v70, v70, v71
	v_mul_f32_e32 v71, 0xbfb8aa3b, v70
	v_exp_f32_e32 v71, v71
	s_nop 0
	v_add_f32_e32 v71, 1.0, v71
	v_rcp_f32_e32 v71, v71
	s_nop 0
	v_mul_f32_e32 v103, v70, v71
	v_pk_mul_f32 v[70:71], v[60:61], v[74:75]
	s_nop 0
	v_add_f32_e32 v50, v50, v70
	v_add_f32_e32 v50, v50, v71
	v_mul_f32_e32 v70, 0xbfb8aa3b, v50
	v_exp_f32_e32 v70, v70
	s_nop 0
	v_add_f32_e32 v70, 1.0, v70
	v_rcp_f32_e32 v70, v70
	s_nop 0
	v_mul_f32_e32 v104, v50, v70
	v_pk_mul_f32 v[70:71], v[10:11], v[58:59]
	s_nop 0
	v_add_f32_e32 v50, v15, v70
	v_add_f32_e32 v116, v50, v71
	v_and_b32_e32 v71, 0xffff0000, v225
	v_and_b32_e32 v70, 0xffff0000, v229
	v_pk_mov_b32 v[50:51], v[58:59], v[70:71] op_sel:[1,0]
	s_nop 0
	v_pk_mul_f32 v[58:59], v[6:7], v[50:51]
	s_nop 0
	v_add_f32_e32 v47, v105, v58
	v_add_f32_e32 v47, v47, v59
	v_mul_f32_e32 v58, 0xbfb8aa3b, v47
	v_exp_f32_e32 v58, v58
	s_nop 0
	v_add_f32_e32 v58, 1.0, v58
	v_rcp_f32_e32 v58, v58
	s_nop 0
	v_mul_f32_e32 v47, v47, v58
	v_cvt_pk_bf16_f32 v47, v103, v47
	global_store_dwordx4 v[96:97], v[44:47], off
	v_mad_i64_i32 v[58:59], s[0:1], v110, s6, v[80:81]
	s_nop 0
	v_pk_mul_f32 v[44:45], v[6:7], v[70:71]
	s_nop 0
	v_add_f32_e32 v44, v116, v44
	v_add_f32_e32 v44, v44, v45
	v_mul_f32_e32 v45, 0xbfb8aa3b, v44
	v_exp_f32_e32 v45, v45
	s_nop 0
	v_add_f32_e32 v45, 1.0, v45
	v_rcp_f32_e32 v45, v45
	s_nop 0
	v_mul_f32_e32 v47, v44, v45
	v_cvt_pk_bf16_f32 v44, v111, v112
	v_cvt_pk_bf16_f32 v45, v113, v114
	v_cvt_pk_bf16_f32 v46, v115, v102
	v_cvt_pk_bf16_f32 v47, v104, v47
	global_store_dwordx4 v[58:59], v[44:47], off
	s_nop 1
	v_pk_mul_f32 v[44:45], v[88:89], v[94:95]
	s_nop 0
	v_add_f32_e32 v44, v24, v44
	v_add_f32_e32 v46, v44, v45
	v_pk_mul_f32 v[44:45], v[20:21], v[98:99]
	s_nop 0
	v_add_f32_e32 v44, v25, v44
	v_add_f32_e32 v47, v44, v45
	v_pk_mul_f32 v[44:45], v[84:85], v[92:93]
	s_nop 0
	v_add_f32_e32 v44, v26, v44
	v_add_f32_e32 v92, v44, v45
	v_pk_mul_f32 v[44:45], v[22:23], v[56:57]
	s_waitcnt vmcnt(14)
; #define GAS __attribute__((address_space(1)))
; __device__ __forceinline__ void unpack8(const v4u v, float (&f)[8]) { f[0] = bflo(v.x); f[1] = bfhi(v.x); f[2] = bflo(v.y); f[3] = bfhi(v.y); f[4] = bflo(v.z); f[5] = bfhi(v.z); f[6] = bflo(v.w); f[7] = bfhi(v.w); }
; __device__ __forceinline__ v4u pack8(const float (&f)[8]) { v4u o; o.x = cvt_pk_bf16(f[0], f[1]); o.y = cvt_pk_bf16(f[2], f[3]); o.z = cvt_pk_bf16(f[4], f[5]); o.w = cvt_pk_bf16(f[6], f[7]); return o; }
; __device__ __forceinline__ float siluf_(float x) { return x * __builtin_amdgcn_rcpf(1.f + __expf(-x)); }
; __device__ __forceinline__ void phase_conv(const Params& P, int seg) {
;     ...
;             for (int i = 0; i < 8; ++i) { unpack8(raw[i], x3); float y[8];
; #pragma unroll
;                 for (int e = 0; e < 8; ++e) { y[e] = siluf_(bb[e] + w0[e] * x0[e] + w1[e] * x1[e] + w2[e] * x2[e] + w3[e] * x3[e]); x0[e] = x1[e]; x1[e] = x2[e]; x2[e] = x3[e]; }
;                 *(GAS v4u*)(xconv + (size_t)(lr0 + hb * 8 + i) * DXBC + c) = pack8(y); } }
	v_lshlrev_b32_e32 v57, 16, v214
	v_add_f32_e32 v44, v27, v44
	v_add_f32_e32 v94, v44, v45
	v_pk_mul_f32 v[44:45], v[68:69], v[76:77]
	v_lshlrev_b32_e32 v56, 16, v218
	v_add_f32_e32 v44, v12, v44
	v_add_f32_e32 v95, v44, v45
	v_pk_mul_f32 v[44:45], v[8:9], v[100:101]
	v_pk_mov_b32 v[58:59], v[54:55], v[56:57] op_sel:[1,0]
	v_add_f32_e32 v44, v13, v44
	v_add_f32_e32 v96, v44, v45
	v_pk_mul_f32 v[44:45], v[64:65], v[72:73]
	v_mad_i64_i32 v[72:73], s[0:1], v109, s6, v[80:81]
	v_add_f32_e32 v44, v14, v44
	v_add_f32_e32 v97, v44, v45
	v_pk_mul_f32 v[44:45], v[10:11], v[50:51]
	v_and_b32_e32 v51, 0xffff0000, v215
	v_add_f32_e32 v44, v15, v44
	v_add_f32_e32 v98, v44, v45
	v_pk_mul_f32 v[44:45], v[88:89], v[54:55]
	v_and_b32_e32 v55, 0xffff0000, v214
	v_add_f32_e32 v44, v24, v44
	v_add_f32_e32 v50, v44, v45
	v_pk_mul_f32 v[44:45], v[86:87], v[58:59]
	v_and_b32_e32 v54, 0xffff0000, v218
	v_add_f32_e32 v44, v46, v44
	v_add_f32_e32 v44, v44, v45
	v_mul_f32_e32 v45, 0xbfb8aa3b, v44
	v_exp_f32_e32 v45, v45
	v_pk_mov_b32 v[76:77], v[52:53], v[54:55] op_sel:[1,0]
	v_add_f32_e32 v45, 1.0, v45
	v_rcp_f32_e32 v45, v45
	s_nop 0
	v_mul_f32_e32 v46, v44, v45
	v_pk_mul_f32 v[44:45], v[86:87], v[56:57]
	s_nop 0
	v_add_f32_e32 v44, v50, v44
	v_add_f32_e32 v44, v44, v45
	v_mul_f32_e32 v45, 0xbfb8aa3b, v44
	v_exp_f32_e32 v45, v45
	s_nop 0
	v_add_f32_e32 v45, 1.0, v45
	v_rcp_f32_e32 v45, v45
	s_nop 0
	v_mul_f32_e32 v99, v44, v45
	v_pk_mul_f32 v[44:45], v[20:21], v[52:53]
	v_lshlrev_b32_e32 v53, 16, v215
	v_add_f32_e32 v44, v25, v44
	v_add_f32_e32 v50, v44, v45
	v_pk_mul_f32 v[44:45], v[16:17], v[76:77]
	v_lshlrev_b32_e32 v52, 16, v219
	v_add_f32_e32 v36, v47, v44
	v_add_f32_e32 v36, v36, v45
	v_mul_f32_e32 v40, 0xbfb8aa3b, v36
	v_exp_f32_e32 v40, v40
	v_pk_mul_f32 v[44:45], v[16:17], v[54:55]
	v_and_b32_e32 v47, 0xffff0000, v216
	v_add_f32_e32 v40, 1.0, v40
	v_rcp_f32_e32 v40, v40
	s_nop 0
	v_mul_f32_e32 v36, v36, v40
	v_add_f32_e32 v40, v50, v44
	v_add_f32_e32 v40, v40, v45
	v_mul_f32_e32 v44, 0xbfb8aa3b, v40
	v_exp_f32_e32 v44, v44
	v_cvt_pk_bf16_f32 v36, v46, v36
	v_and_b32_e32 v50, 0xffff0000, v219
	v_add_f32_e32 v44, 1.0, v44
	v_rcp_f32_e32 v44, v44
	s_nop 0
	v_mul_f32_e32 v100, v40, v44
	v_pk_mul_f32 v[44:45], v[84:85], v[90:91]
	v_pk_mov_b32 v[90:91], v[90:91], v[52:53] op_sel:[1,0]
	v_add_f32_e32 v40, v26, v44
	v_add_f32_e32 v40, v40, v45
	v_pk_mul_f32 v[44:45], v[82:83], v[90:91]
	s_nop 0
	v_add_f32_e32 v44, v92, v44
	v_add_f32_e32 v44, v44, v45
	v_mul_f32_e32 v45, 0xbfb8aa3b, v44
	v_exp_f32_e32 v45, v45
	v_pk_mov_b32 v[92:93], v[48:49], v[50:51] op_sel:[1,0]
	v_add_f32_e32 v45, 1.0, v45
	v_rcp_f32_e32 v45, v45
	s_nop 0
	v_mul_f32_e32 v46, v44, v45
	v_pk_mul_f32 v[44:45], v[82:83], v[52:53]
	s_nop 0
	v_add_f32_e32 v40, v40, v44
	v_add_f32_e32 v40, v40, v45
	v_mul_f32_e32 v44, 0xbfb8aa3b, v40
	v_exp_f32_e32 v44, v44
	s_nop 0
	v_add_f32_e32 v44, 1.0, v44
	v_rcp_f32_e32 v44, v44
	s_nop 0
	v_mul_f32_e32 v101, v40, v44
	v_pk_mul_f32 v[44:45], v[22:23], v[48:49]
	v_lshlrev_b32_e32 v49, 16, v216
	v_add_f32_e32 v40, v27, v44
	v_add_f32_e32 v44, v40, v45
	v_pk_mul_f32 v[40:41], v[18:19], v[92:93]
	v_lshlrev_b32_e32 v48, 16, v220
	v_add_f32_e32 v37, v94, v40
	v_add_f32_e32 v37, v37, v41
	v_mul_f32_e32 v40, 0xbfb8aa3b, v37
	v_exp_f32_e32 v40, v40
	s_nop 0
	v_add_f32_e32 v40, 1.0, v40
	v_rcp_f32_e32 v40, v40
	s_nop 0
	v_mul_f32_e32 v37, v37, v40
	v_pk_mul_f32 v[40:41], v[18:19], v[50:51]
	v_cvt_pk_bf16_f32 v37, v46, v37
	v_and_b32_e32 v46, 0xffff0000, v220
	v_add_f32_e32 v40, v44, v40
	v_add_f32_e32 v40, v40, v41
	v_mul_f32_e32 v41, 0xbfb8aa3b, v40
	v_exp_f32_e32 v41, v41
	s_nop 0
	v_add_f32_e32 v41, 1.0, v41
	v_rcp_f32_e32 v41, v41
	s_nop 0
	v_mul_f32_e32 v94, v40, v41
	v_pk_mul_f32 v[40:41], v[68:69], v[78:79]
	v_pk_mov_b32 v[78:79], v[78:79], v[48:49] op_sel:[1,0]
	v_add_f32_e32 v40, v12, v40
	v_add_f32_e32 v44, v40, v41
	v_pk_mul_f32 v[40:41], v[66:67], v[78:79]
	s_nop 0
	v_add_f32_e32 v40, v95, v40
	v_add_f32_e32 v40, v40, v41
	v_mul_f32_e32 v41, 0xbfb8aa3b, v40
	v_exp_f32_e32 v41, v41
	s_nop 0
	v_add_f32_e32 v41, 1.0, v41
	v_rcp_f32_e32 v41, v41
	s_nop 0
	v_mul_f32_e32 v45, v40, v41
	v_pk_mul_f32 v[40:41], v[66:67], v[48:49]
	s_nop 0
	v_add_f32_e32 v40, v44, v40
	v_add_f32_e32 v40, v40, v41
	v_mul_f32_e32 v41, 0xbfb8aa3b, v40
	v_exp_f32_e32 v41, v41
	s_nop 0
	v_add_f32_e32 v41, 1.0, v41
	v_rcp_f32_e32 v41, v41
	s_nop 0
	v_mul_f32_e32 v95, v40, v41
	v_pk_mul_f32 v[40:41], v[8:9], v[62:63]
	v_pk_mov_b32 v[62:63], v[62:63], v[46:47] op_sel:[1,0]
	v_add_f32_e32 v40, v13, v40
	v_add_f32_e32 v44, v40, v41
	v_pk_mul_f32 v[40:41], v[4:5], v[62:63]
	s_nop 0
	v_add_f32_e32 v38, v96, v40
	v_add_f32_e32 v38, v38, v41
	v_mul_f32_e32 v40, 0xbfb8aa3b, v38
	v_exp_f32_e32 v40, v40
	s_nop 0
	v_add_f32_e32 v40, 1.0, v40
	v_rcp_f32_e32 v40, v40
	s_nop 0
	v_mul_f32_e32 v38, v38, v40
	v_pk_mul_f32 v[40:41], v[4:5], v[46:47]
	v_cvt_pk_bf16_f32 v38, v45, v38
	v_lshlrev_b32_e32 v45, 16, v217
	v_add_f32_e32 v40, v44, v40
	v_add_f32_e32 v40, v40, v41
	v_mul_f32_e32 v41, 0xbfb8aa3b, v40
	v_exp_f32_e32 v41, v41
	v_lshlrev_b32_e32 v44, 16, v221
	v_add_f32_e32 v41, 1.0, v41
	v_rcp_f32_e32 v41, v41
	s_nop 0
	v_mul_f32_e32 v96, v40, v41
	v_pk_mul_f32 v[40:41], v[64:65], v[74:75]
	v_pk_mov_b32 v[74:75], v[74:75], v[44:45] op_sel:[1,0]
	v_add_f32_e32 v40, v14, v40
	v_add_f32_e32 v42, v40, v41
	v_pk_mul_f32 v[40:41], v[60:61], v[74:75]
	s_nop 0
	v_add_f32_e32 v40, v97, v40
	v_add_f32_e32 v40, v40, v41
	v_mul_f32_e32 v41, 0xbfb8aa3b, v40
	v_exp_f32_e32 v41, v41
	s_nop 0
	v_add_f32_e32 v41, 1.0, v41
	v_rcp_f32_e32 v41, v41
	s_nop 0
	v_mul_f32_e32 v97, v40, v41
	v_pk_mul_f32 v[40:41], v[60:61], v[44:45]
; #define GAS __attribute__((address_space(1)))
; __device__ __forceinline__ void unpack8(const v4u v, float (&f)[8]) { f[0] = bflo(v.x); f[1] = bfhi(v.x); f[2] = bflo(v.y); f[3] = bfhi(v.y); f[4] = bflo(v.z); f[5] = bfhi(v.z); f[6] = bflo(v.w); f[7] = bfhi(v.w); }
; __device__ __forceinline__ v4u pack8(const float (&f)[8]) { v4u o; o.x = cvt_pk_bf16(f[0], f[1]); o.y = cvt_pk_bf16(f[2], f[3]); o.z = cvt_pk_bf16(f[4], f[5]); o.w = cvt_pk_bf16(f[6], f[7]); return o; }
; __device__ __forceinline__ float siluf_(float x) { return x * __builtin_amdgcn_rcpf(1.f + __expf(-x)); }
; __device__ __forceinline__ void phase_conv(const Params& P, int seg) {
;     ...
;             for (int i = 0; i < 8; ++i) { unpack8(raw[i], x3); float y[8];
; #pragma unroll
;                 for (int e = 0; e < 8; ++e) { y[e] = siluf_(bb[e] + w0[e] * x0[e] + w1[e] * x1[e] + w2[e] * x2[e] + w3[e] * x3[e]); x0[e] = x1[e]; x1[e] = x2[e]; x2[e] = x3[e]; }
;                 *(GAS v4u*)(xconv + (size_t)(lr0 + hb * 8 + i) * DXBC + c) = pack8(y); } }
	s_nop 0
	v_add_f32_e32 v40, v42, v40
	v_add_f32_e32 v40, v40, v41
	v_mul_f32_e32 v41, 0xbfb8aa3b, v40
	v_exp_f32_e32 v41, v41
	s_nop 0
	v_add_f32_e32 v41, 1.0, v41
	v_rcp_f32_e32 v41, v41
	s_nop 0
	v_mul_f32_e32 v102, v40, v41
	v_pk_mul_f32 v[40:41], v[10:11], v[70:71]
	s_nop 0
	v_add_f32_e32 v40, v15, v40
	v_add_f32_e32 v103, v40, v41
	v_and_b32_e32 v41, 0xffff0000, v217
	v_and_b32_e32 v40, 0xffff0000, v221
	v_pk_mov_b32 v[42:43], v[70:71], v[40:41] op_sel:[1,0]
	s_nop 0
	v_pk_mul_f32 v[70:71], v[6:7], v[42:43]
	s_nop 0
	v_add_f32_e32 v39, v98, v70
	v_add_f32_e32 v39, v39, v71
	v_mul_f32_e32 v70, 0xbfb8aa3b, v39
	v_exp_f32_e32 v70, v70
	s_nop 0
	v_add_f32_e32 v70, 1.0, v70
	v_rcp_f32_e32 v70, v70
	s_nop 0
	v_mul_f32_e32 v39, v39, v70
	v_cvt_pk_bf16_f32 v39, v97, v39
	global_store_dwordx4 v[72:73], v[36:39], off
	v_mad_i64_i32 v[70:71], s[0:1], v108, s6, v[80:81]
	s_nop 0
	v_pk_mul_f32 v[36:37], v[6:7], v[40:41]
	s_nop 0
	v_add_f32_e32 v36, v103, v36
	v_add_f32_e32 v36, v36, v37
	v_mul_f32_e32 v37, 0xbfb8aa3b, v36
	v_exp_f32_e32 v37, v37
	s_nop 0
	v_add_f32_e32 v37, 1.0, v37
	v_rcp_f32_e32 v37, v37
	s_nop 0
	v_mul_f32_e32 v39, v36, v37
	v_cvt_pk_bf16_f32 v36, v99, v100
	v_cvt_pk_bf16_f32 v37, v101, v94
	v_cvt_pk_bf16_f32 v38, v95, v96
	v_cvt_pk_bf16_f32 v39, v102, v39
	global_store_dwordx4 v[70:71], v[36:39], off
	s_nop 1
	v_pk_mul_f32 v[36:37], v[88:89], v[58:59]
	v_pk_mul_f32 v[38:39], v[88:89], v[56:57]
	v_add_f32_e32 v36, v24, v36
	v_add_f32_e32 v58, v36, v37
	v_pk_mul_f32 v[36:37], v[20:21], v[76:77]
	v_add_f32_e32 v24, v24, v38
	v_add_f32_e32 v36, v25, v36
	v_add_f32_e32 v59, v36, v37
	v_pk_mul_f32 v[36:37], v[84:85], v[90:91]
	v_add_f32_e32 v24, v24, v39
	v_add_f32_e32 v36, v26, v36
	v_add_f32_e32 v70, v36, v37
	v_pk_mul_f32 v[36:37], v[22:23], v[92:93]
	s_waitcnt vmcnt(15)
	v_lshlrev_b32_e32 v38, 16, v210
	v_add_f32_e32 v36, v27, v36
	v_add_f32_e32 v71, v36, v37
	v_pk_mul_f32 v[36:37], v[68:69], v[78:79]
	s_waitcnt vmcnt(14)
; #define GAS __attribute__((address_space(1)))
; __device__ __forceinline__ void unpack8(const v4u v, float (&f)[8]) { f[0] = bflo(v.x); f[1] = bfhi(v.x); f[2] = bflo(v.y); f[3] = bfhi(v.y); f[4] = bflo(v.z); f[5] = bfhi(v.z); f[6] = bflo(v.w); f[7] = bfhi(v.w); }
; __device__ __forceinline__ v4u pack8(const float (&f)[8]) { v4u o; o.x = cvt_pk_bf16(f[0], f[1]); o.y = cvt_pk_bf16(f[2], f[3]); o.z = cvt_pk_bf16(f[4], f[5]); o.w = cvt_pk_bf16(f[6], f[7]); return o; }
; __device__ __forceinline__ float siluf_(float x) { return x * __builtin_amdgcn_rcpf(1.f + __expf(-x)); }
; __device__ __forceinline__ void phase_conv(const Params& P, int seg) {
;     ...
;             for (int i = 0; i < 8; ++i) { unpack8(raw[i], x3); float y[8];
; #pragma unroll
;                 for (int e = 0; e < 8; ++e) { y[e] = siluf_(bb[e] + w0[e] * x0[e] + w1[e] * x1[e] + w2[e] * x2[e] + w3[e] * x3[e]); x0[e] = x1[e]; x1[e] = x2[e]; x2[e] = x3[e]; }
;                 *(GAS v4u*)(xconv + (size_t)(lr0 + hb * 8 + i) * DXBC + c) = pack8(y); } }
;     }
	v_lshlrev_b32_e32 v39, 16, v206
	v_add_f32_e32 v36, v12, v36
	v_add_f32_e32 v72, v36, v37
	v_pk_mul_f32 v[36:37], v[8:9], v[62:63]
	v_pk_mul_f32 v[20:21], v[20:21], v[54:55]
	v_add_f32_e32 v36, v13, v36
	v_add_f32_e32 v62, v36, v37
	v_pk_mul_f32 v[36:37], v[64:65], v[74:75]
	v_add_f32_e32 v20, v25, v20
	v_add_f32_e32 v36, v14, v36
	v_add_f32_e32 v63, v36, v37
	v_pk_mul_f32 v[36:37], v[10:11], v[42:43]
	v_pk_mov_b32 v[42:43], v[56:57], v[38:39] op_sel:[1,0]
	v_pk_mul_f32 v[38:39], v[86:87], v[38:39]
	v_and_b32_e32 v25, 0xffff0000, v206
	v_add_f32_e32 v24, v24, v38
	v_add_f32_e32 v24, v24, v39
	v_mul_f32_e32 v38, 0xbfb8aa3b, v24
	v_exp_f32_e32 v38, v38
	v_add_f32_e32 v39, v20, v21
	v_pk_mul_f32 v[42:43], v[86:87], v[42:43]
	v_pk_mul_f32 v[8:9], v[8:9], v[46:47]
	v_add_f32_e32 v38, 1.0, v38
	v_rcp_f32_e32 v38, v38
	v_add_f32_e32 v42, v58, v42
	v_add_f32_e32 v42, v42, v43
	v_mul_f32_e32 v43, 0xbfb8aa3b, v42
	v_mul_f32_e32 v38, v24, v38
	v_and_b32_e32 v24, 0xffff0000, v210
	v_pk_mov_b32 v[20:21], v[54:55], v[24:25] op_sel:[1,0]
	v_exp_f32_e32 v43, v43
	v_pk_mul_f32 v[20:21], v[16:17], v[20:21]
	v_pk_mul_f32 v[16:17], v[16:17], v[24:25]
	v_add_f32_e32 v20, v59, v20
	v_add_f32_e32 v16, v39, v16
	v_add_f32_e32 v16, v16, v17
	v_mul_f32_e32 v17, 0xbfb8aa3b, v16
	v_add_f32_e32 v20, v20, v21
	v_exp_f32_e32 v17, v17
	v_mul_f32_e32 v21, 0xbfb8aa3b, v20
	v_exp_f32_e32 v21, v21
	v_add_f32_e32 v43, 1.0, v43
	v_add_f32_e32 v17, 1.0, v17
	v_rcp_f32_e32 v17, v17
	v_add_f32_e32 v21, 1.0, v21
	v_rcp_f32_e32 v21, v21
	v_rcp_f32_e32 v43, v43
	v_mul_f32_e32 v28, v16, v17
	v_pk_mul_f32 v[16:17], v[84:85], v[52:53]
	v_mul_f32_e32 v20, v20, v21
	v_add_f32_e32 v16, v26, v16
	v_add_f32_e32 v21, v16, v17
	v_lshlrev_b32_e32 v16, 16, v211
	v_lshlrev_b32_e32 v17, 16, v207
	v_pk_mov_b32 v[24:25], v[52:53], v[16:17] op_sel:[1,0]
	v_pk_mul_f32 v[16:17], v[82:83], v[16:17]
	v_pk_mul_f32 v[24:25], v[82:83], v[24:25]
	v_add_f32_e32 v16, v21, v16
	v_add_f32_e32 v24, v70, v24
	v_add_f32_e32 v24, v24, v25
	v_add_f32_e32 v16, v16, v17
	v_mul_f32_e32 v25, 0xbfb8aa3b, v24
	v_mul_f32_e32 v17, 0xbfb8aa3b, v16
	v_exp_f32_e32 v25, v25
	v_exp_f32_e32 v17, v17
	v_mul_f32_e32 v42, v42, v43
	v_cvt_pk_bf16_f32 v20, v42, v20
	v_add_f32_e32 v25, 1.0, v25
	v_add_f32_e32 v17, 1.0, v17
	v_rcp_f32_e32 v25, v25
	v_rcp_f32_e32 v17, v17
	v_add_f32_e32 v8, v13, v8
	v_add_f32_e32 v36, v15, v36
	v_mul_f32_e32 v24, v24, v25
	v_mul_f32_e32 v25, v16, v17
	v_pk_mul_f32 v[16:17], v[22:23], v[50:51]
	v_add_f32_e32 v73, v36, v37
	v_add_f32_e32 v16, v27, v16
	v_add_f32_e32 v26, v16, v17
	v_and_b32_e32 v17, 0xffff0000, v207
	v_and_b32_e32 v16, 0xffff0000, v211
	v_pk_mov_b32 v[22:23], v[50:51], v[16:17] op_sel:[1,0]
	v_pk_mul_f32 v[16:17], v[18:19], v[16:17]
	v_pk_mul_f32 v[22:23], v[18:19], v[22:23]
	v_add_f32_e32 v16, v26, v16
	v_add_f32_e32 v21, v71, v22
	v_add_f32_e32 v21, v21, v23
	v_mul_f32_e32 v22, 0xbfb8aa3b, v21
	v_add_f32_e32 v16, v16, v17
	v_exp_f32_e32 v22, v22
	v_mul_f32_e32 v17, 0xbfb8aa3b, v16
	v_exp_f32_e32 v17, v17
	v_mad_i64_i32 v[36:37], s[0:1], v107, s6, v[80:81]
	v_add_f32_e32 v22, 1.0, v22
	v_rcp_f32_e32 v22, v22
	v_add_f32_e32 v17, 1.0, v17
	v_rcp_f32_e32 v17, v17
	v_mul_f32_e32 v21, v21, v22
	v_cvt_pk_bf16_f32 v21, v24, v21
	v_mul_f32_e32 v24, v16, v17
	v_pk_mul_f32 v[16:17], v[68:69], v[48:49]
	s_nop 0
	v_add_f32_e32 v12, v12, v16
	v_add_f32_e32 v12, v12, v17
	v_lshlrev_b32_e32 v16, 16, v212
	v_lshlrev_b32_e32 v17, 16, v208
	v_pk_mov_b32 v[18:19], v[48:49], v[16:17] op_sel:[1,0]
	v_pk_mul_f32 v[16:17], v[66:67], v[16:17]
	v_pk_mul_f32 v[18:19], v[66:67], v[18:19]
	v_add_f32_e32 v12, v12, v16
	v_add_f32_e32 v12, v12, v17
	v_mul_f32_e32 v16, 0xbfb8aa3b, v12
	v_exp_f32_e32 v16, v16
	v_add_f32_e32 v17, v8, v9
	v_and_b32_e32 v9, 0xffff0000, v208
	v_and_b32_e32 v8, 0xffff0000, v212
	v_add_f32_e32 v16, 1.0, v16
	v_rcp_f32_e32 v16, v16
	v_add_f32_e32 v18, v72, v18
	v_add_f32_e32 v18, v18, v19
	v_mul_f32_e32 v19, 0xbfb8aa3b, v18
	v_mul_f32_e32 v16, v12, v16
	v_pk_mov_b32 v[12:13], v[46:47], v[8:9] op_sel:[1,0]
	v_exp_f32_e32 v19, v19
	v_pk_mul_f32 v[12:13], v[4:5], v[12:13]
	v_pk_mul_f32 v[4:5], v[4:5], v[8:9]
	v_add_f32_e32 v12, v62, v12
	v_add_f32_e32 v12, v12, v13
	v_add_f32_e32 v4, v17, v4
	v_mul_f32_e32 v13, 0xbfb8aa3b, v12
	v_add_f32_e32 v4, v4, v5
	v_exp_f32_e32 v13, v13
	v_mul_f32_e32 v5, 0xbfb8aa3b, v4
	v_exp_f32_e32 v5, v5
	v_add_f32_e32 v19, 1.0, v19
	v_add_f32_e32 v13, 1.0, v13
	v_rcp_f32_e32 v13, v13
	v_add_f32_e32 v5, 1.0, v5
	v_rcp_f32_e32 v19, v19
	v_rcp_f32_e32 v5, v5
	v_mul_f32_e32 v12, v12, v13
	v_mul_f32_e32 v18, v18, v19
	v_cvt_pk_bf16_f32 v22, v18, v12
	v_mul_f32_e32 v12, v4, v5
	v_pk_mul_f32 v[4:5], v[64:65], v[44:45]
	s_nop 0
	v_add_f32_e32 v4, v14, v4
	v_add_f32_e32 v13, v4, v5
	v_lshlrev_b32_e32 v4, 16, v213
	v_lshlrev_b32_e32 v5, 16, v209
	v_pk_mov_b32 v[8:9], v[44:45], v[4:5] op_sel:[1,0]
	v_pk_mul_f32 v[4:5], v[60:61], v[4:5]
	v_pk_mul_f32 v[8:9], v[60:61], v[8:9]
	v_add_f32_e32 v4, v13, v4
	v_add_f32_e32 v4, v4, v5
	v_mul_f32_e32 v5, 0xbfb8aa3b, v4
	v_add_f32_e32 v8, v63, v8
	v_exp_f32_e32 v5, v5
	v_add_f32_e32 v8, v8, v9
	v_mul_f32_e32 v9, 0xbfb8aa3b, v8
	v_exp_f32_e32 v9, v9
	v_add_f32_e32 v5, 1.0, v5
	v_rcp_f32_e32 v5, v5
	v_add_f32_e32 v9, 1.0, v9
	v_rcp_f32_e32 v9, v9
	v_mul_f32_e32 v13, v4, v5
	v_pk_mul_f32 v[4:5], v[10:11], v[40:41]
	v_mul_f32_e32 v14, v8, v9
	v_add_f32_e32 v4, v15, v4
	v_add_f32_e32 v10, v4, v5
	v_and_b32_e32 v5, 0xffff0000, v209
	v_and_b32_e32 v4, 0xffff0000, v213
	v_pk_mov_b32 v[8:9], v[40:41], v[4:5] op_sel:[1,0]
	v_pk_mul_f32 v[4:5], v[6:7], v[4:5]
	v_pk_mul_f32 v[8:9], v[6:7], v[8:9]
	v_add_f32_e32 v4, v10, v4
	v_add_f32_e32 v8, v73, v8
	v_add_f32_e32 v8, v8, v9
	v_mul_f32_e32 v9, 0xbfb8aa3b, v8
	v_add_f32_e32 v4, v4, v5
	v_exp_f32_e32 v9, v9
	v_mul_f32_e32 v5, 0xbfb8aa3b, v4
	v_exp_f32_e32 v5, v5
	v_add_f32_e32 v9, 1.0, v9
	v_rcp_f32_e32 v9, v9
	v_add_f32_e32 v5, 1.0, v5
	v_rcp_f32_e32 v5, v5
	v_mul_f32_e32 v8, v8, v9
	v_cvt_pk_bf16_f32 v23, v14, v8
	v_mul_f32_e32 v7, v4, v5
	v_mad_i64_i32 v[8:9], s[0:1], v106, s6, v[80:81]
	global_store_dwordx4 v[36:37], v[20:23], off
	v_cvt_pk_bf16_f32 v4, v38, v28
	v_cvt_pk_bf16_f32 v5, v25, v24
	v_cvt_pk_bf16_f32 v6, v16, v12
	v_cvt_pk_bf16_f32 v7, v13, v7
	global_store_dwordx4 v[8:9], v[4:7], off
	s_andn2_b64 exec, exec, s[56:57]
	s_cbranch_execz .LBB0_205

; #define GAS __attribute__((address_space(1)))
; __device__ __forceinline__ void unpack8(const v4u v, float (&f)[8]) { f[0] = bflo(v.x); f[1] = bfhi(v.x); f[2] = bflo(v.y); f[3] = bfhi(v.y); f[4] = bflo(v.z); f[5] = bfhi(v.z); f[6] = bflo(v.w); f[7] = bfhi(v.w); }
; __device__ __forceinline__ void phase_conv(const Params& P, int seg) {
;     ...
;     for (int idx = gtid; idx < nruns * (DM / 8); idx += NT) {
;         const int r = idx / (DM / 8), c = (idx % (DM / 8)) * 8, lr0 = (r < RS / 16) ? r * 16 : RS + 48;
;         float w0[8], w1[8], w2[8];
; #pragma unroll
;         for (int e = 0; e < 8; ++e) { w0[e] = P.sc_conv_w[0 * DM + c + e]; w1[e] = P.sc_conv_w[1 * DM + c + e]; w2[e] = P.sc_conv_w[2 * DM + c + e]; }
;         float p0[8], p1[8], p2[8], t0[8], t1[8];
;         { const GAS bf16* q = prow(lr0, 2); unpack8(*(const GAS v4u*)(q + OFF_SCC + c), t0); unpack8(*(const GAS v4u*)(q + OFF_SCH + c), t1);
; #pragma unroll
;           for (int e = 0; e < 8; ++e) p0[e] = t0[e] * t1[e]; }
;         { const GAS bf16* q = prow(lr0, 1); unpack8(*(const GAS v4u*)(q + OFF_SCC + c), t0); unpack8(*(const GAS v4u*)(q + OFF_SCH + c), t1);
; #pragma unroll
;           for (int e = 0; e < 8; ++e) p1[e] = t0[e] * t1[e]; }
; #pragma unroll
;         for (int hb = 0; hb < 4; ++hb) { v4u rc[4], rh[4], rb[4];
; #pragma unroll
;             for (int i = 0; i < 4; ++i) { const GAS bf16* q = proj + (size_t)(lr0 + hb * 4 + i) * NPROJ; rc[i] = __builtin_nontemporal_load((const GAS v4u*)(q + OFF_SCC + c)); rh[i] = __builtin_nontemporal_load((const GAS v4u*)(q + OFF_SCH + c)); rb[i] = __builtin_nontemporal_load((const GAS v4u*)(q + OFF_SCB + c)); }
.LBB0_207:
	s_or_b64 exec, exec, s[26:27]
	v_lshlrev_b64 v[60:61], 1, v[36:37]
	v_lshl_add_u64 v[36:37], v[38:39], 0, v[60:61]
	v_mov_b64_e32 v[62:63], s[40:41]
	v_mad_i64_i32 v[38:39], s[24:25], v42, s4, v[62:63]
	v_add_co_u32_e32 v36, vcc, s33, v36
	v_lshl_add_u64 v[38:39], v[38:39], 0, v[60:61]
	s_nop 0
	v_addc_co_u32_e32 v37, vcc, 0, v37, vcc
	global_load_dwordx4 v[44:47], v[38:39], off nt
	v_add_co_u32_e32 v38, vcc, s33, v38
	s_waitcnt vmcnt(1)
	v_lshlrev_b32_e32 v40, 16, v28
	v_addc_co_u32_e32 v39, vcc, 0, v39, vcc
	global_load_dwordx4 v[52:55], v[38:39], off offset:-4096 nt
	global_load_dwordx4 v[64:67], v[36:37], off offset:-4096
	global_load_dwordx4 v[68:71], v[38:39], off nt
	global_load_dwordx4 v[72:75], v[36:37], off
	v_lshlrev_b32_e32 v36, 16, v32
	v_and_b32_e32 v32, 0xffff0000, v32
	v_lshlrev_b32_e32 v37, 16, v33
	v_and_b32_e32 v33, 0xffff0000, v33
	v_and_b32_e32 v28, 0xffff0000, v28
	v_lshlrev_b32_e32 v41, 16, v29
	v_and_b32_e32 v29, 0xffff0000, v29
	v_or_b32_e32 v82, 1, v42
	v_mul_f32_e32 v51, v32, v28
	v_mul_f32_e32 v57, v33, v29
	v_mad_i64_i32 v[28:29], s[24:25], v82, s4, v[62:63]
	v_lshlrev_b32_e32 v38, 16, v34
	v_and_b32_e32 v34, 0xffff0000, v34
	v_lshlrev_b32_e32 v39, 16, v35
	v_and_b32_e32 v35, 0xffff0000, v35
	v_lshlrev_b32_e32 v48, 16, v30
	v_and_b32_e32 v30, 0xffff0000, v30
	v_lshlrev_b32_e32 v49, 16, v31
	v_and_b32_e32 v31, 0xffff0000, v31
	v_or_b32_e32 v98, 2, v42
	v_lshl_add_u64 v[28:29], v[28:29], 0, v[60:61]
	v_mul_f32_e32 v96, v34, v30
	v_mul_f32_e32 v124, v35, v31
	v_mad_i64_i32 v[30:31], s[24:25], v98, s4, v[62:63]
	v_add_co_u32_e32 v34, vcc, s33, v28
	v_or_b32_e32 v80, 3, v42
	v_lshl_add_u64 v[30:31], v[30:31], 0, v[60:61]
	v_addc_co_u32_e32 v35, vcc, 0, v29, vcc
	v_mad_i64_i32 v[32:33], s[24:25], v80, s4, v[62:63]
	global_load_dwordx4 v[76:79], v[28:29], off nt
	v_add_co_u32_e32 v28, vcc, s33, v30
	v_lshl_add_u64 v[32:33], v[32:33], 0, v[60:61]
	s_nop 0
	v_addc_co_u32_e32 v29, vcc, 0, v31, vcc
	v_mul_f32_e32 v58, v38, v48
	v_add_co_u32_e32 v48, vcc, s33, v32
	v_mul_f32_e32 v50, v36, v40
	v_mul_f32_e32 v56, v37, v41
	v_mul_f32_e32 v97, v39, v49
	v_addc_co_u32_e32 v49, vcc, 0, v33, vcc
	global_load_dwordx4 v[84:87], v[30:31], off nt
	global_load_dwordx4 v[36:39], v[32:33], off nt
	global_load_dwordx4 v[88:91], v[34:35], off offset:-4096 nt
	global_load_dwordx4 v[92:95], v[34:35], off nt
	global_load_dwordx4 v[100:103], v[28:29], off offset:-4096 nt
	global_load_dwordx4 v[104:107], v[28:29], off nt
	s_nop 0
	global_load_dwordx4 v[28:31], v[48:49], off offset:-4096 nt
	global_load_dwordx4 v[32:35], v[48:49], off nt
	s_nop 1
	v_or_b32_e32 v251, 4, v42
	v_mad_i64_i32 v[248:249], s[48:49], v251, s4, v[62:63]
	v_lshl_add_u64 v[246:247], v[248:249], 0, v[60:61]
	v_add_co_u32_e64 v250, s[48:49], s33, v246
	v_addc_co_u32_e64 v245, s[48:49], 0, v247, s[48:49]
	v_mov_b32_e32 v232, v250
	v_mov_b32_e32 v233, v245
	global_load_dwordx4 v[234:237], v[232:233], off nt
	v_ashrrev_i32_e32 v43, 31, v42
	v_lshl_add_u64 v[40:41], s[14:15], 0, v[60:61]
	v_ashrrev_i32_e32 v83, 31, v82
	v_lshlrev_b64 v[82:83], 12, v[82:83]
	v_lshl_add_u64 v[156:157], v[40:41], 0, v[82:83]
	v_ashrrev_i32_e32 v99, 31, v98
	v_lshlrev_b64 v[98:99], 12, v[98:99]
	v_lshl_add_u64 v[98:99], v[40:41], 0, v[98:99]
	v_ashrrev_i32_e32 v81, 31, v80
	v_or_b32_e32 v170, 6, v42
	v_mov_b32_e32 v190, v12
	v_mov_b32_e32 v191, v16
	v_mov_b32_e32 v224, v13
	v_mov_b32_e32 v225, v17
	v_ashrrev_i32_e32 v171, 31, v170
	v_add_u32_e32 v140, s20, v140
	v_add_u32_e32 v139, s22, v139
	s_waitcnt vmcnt(14)
	v_lshlrev_b32_e32 v48, 16, v44
	v_and_b32_e32 v59, 0xffff0000, v44
	v_lshlrev_b32_e32 v114, 16, v45
	v_and_b32_e32 v116, 0xffff0000, v45
	v_lshlrev_b32_e32 v118, 16, v46
	v_and_b32_e32 v120, 0xffff0000, v46
	v_lshlrev_b32_e32 v122, 16, v47
	v_and_b32_e32 v125, 0xffff0000, v47
	s_waitcnt vmcnt(13)
	v_lshlrev_b32_e32 v45, 16, v52
	s_waitcnt vmcnt(12)
	v_lshlrev_b32_e32 v44, 16, v64
	s_waitcnt vmcnt(11)
	v_lshlrev_b32_e32 v47, 16, v68
	s_waitcnt vmcnt(10)
	v_lshlrev_b32_e32 v46, 16, v72
	v_pk_mul_f32 v[108:109], v[44:45], v[46:47]
	v_mov_b32_e32 v44, v24
	v_mov_b32_e32 v45, v16
	v_pk_mul_f32 v[46:47], v[44:45], v[108:109]
	v_and_b32_e32 v49, 0xffff0000, v68
	v_fma_f32 v46, v12, v50, v46
	v_add_f32_e32 v46, v46, v47
	v_mul_f32_e32 v126, v46, v48
	v_and_b32_e32 v47, 0xffff0000, v52
	v_and_b32_e32 v46, 0xffff0000, v64
	v_and_b32_e32 v48, 0xffff0000, v72
	v_pk_mul_f32 v[110:111], v[46:47], v[48:49]
	v_mov_b32_e32 v46, v25
	v_mov_b32_e32 v47, v17
	v_pk_mul_f32 v[48:49], v[46:47], v[110:111]
	v_lshlrev_b32_e32 v50, 16, v73
	v_fma_f32 v48, v13, v51, v48
	v_add_f32_e32 v48, v48, v49
	v_mul_f32_e32 v68, v48, v59
	v_lshlrev_b32_e32 v49, 16, v53
	v_lshlrev_b32_e32 v48, 16, v65
	v_lshlrev_b32_e32 v51, 16, v69
	v_pk_mul_f32 v[112:113], v[48:49], v[50:51]
	v_mov_b32_e32 v48, v26
	v_mov_b32_e32 v49, v18
	v_pk_mul_f32 v[50:51], v[48:49], v[112:113]
	v_and_b32_e32 v52, 0xffff0000, v73
	v_fma_f32 v50, v14, v56, v50
	v_add_f32_e32 v50, v50, v51
	v_mul_f32_e32 v72, v50, v114
	v_and_b32_e32 v51, 0xffff0000, v53
	v_and_b32_e32 v50, 0xffff0000, v65
	v_and_b32_e32 v53, 0xffff0000, v69
	v_pk_mul_f32 v[114:115], v[50:51], v[52:53]
	v_mov_b32_e32 v50, v27
	v_mov_b32_e32 v51, v19
	v_pk_mul_f32 v[52:53], v[50:51], v[114:115]
	v_lshlrev_b32_e32 v56, 16, v74
	v_fma_f32 v52, v15, v57, v52
	v_add_f32_e32 v52, v52, v53
	v_mul_f32_e32 v69, v52, v116
	v_lshlrev_b32_e32 v53, 16, v54
	v_lshlrev_b32_e32 v52, 16, v66
	v_lshlrev_b32_e32 v57, 16, v70
	v_pk_mul_f32 v[116:117], v[52:53], v[56:57]
	v_mov_b32_e32 v52, v20
	v_mov_b32_e32 v53, v8
	v_pk_mul_f32 v[56:57], v[52:53], v[116:117]
	v_and_b32_e32 v59, 0xffff0000, v70
	v_fma_f32 v56, v4, v58, v56
	v_add_f32_e32 v56, v56, v57
	v_mul_f32_e32 v73, v56, v118
	v_and_b32_e32 v57, 0xffff0000, v54
	v_and_b32_e32 v56, 0xffff0000, v66
	v_and_b32_e32 v58, 0xffff0000, v74
	v_pk_mul_f32 v[118:119], v[56:57], v[58:59]
	v_mov_b32_e32 v56, v21
	v_mov_b32_e32 v57, v9
	v_pk_mul_f32 v[58:59], v[56:57], v[118:119]
	v_lshlrev_b32_e32 v65, 16, v71
	v_fma_f32 v54, v5, v96, v58
	v_add_f32_e32 v54, v54, v59
	v_lshlrev_b32_e32 v59, 16, v55
	v_lshlrev_b32_e32 v58, 16, v67
	v_lshlrev_b32_e32 v64, 16, v75
	v_mul_f32_e32 v66, v54, v120
	v_pk_mul_f32 v[120:121], v[58:59], v[64:65]
	v_mov_b32_e32 v58, v22
	v_mov_b32_e32 v59, v10
	v_pk_mul_f32 v[64:65], v[58:59], v[120:121]
	v_and_b32_e32 v55, 0xffff0000, v55
	v_fma_f32 v54, v6, v97, v64
	v_add_f32_e32 v54, v54, v65
	v_mul_f32_e32 v70, v54, v122
	v_and_b32_e32 v54, 0xffff0000, v67
	v_and_b32_e32 v65, 0xffff0000, v71
	v_and_b32_e32 v64, 0xffff0000, v75
	v_pk_mul_f32 v[122:123], v[54:55], v[64:65]
	v_mov_b32_e32 v54, v23
	v_mov_b32_e32 v55, v11
	v_pk_mul_f32 v[64:65], v[54:55], v[122:123]
	s_waitcnt vmcnt(9)
; #define GAS __attribute__((address_space(1)))
; __device__ __forceinline__ void unpack8(const v4u v, float (&f)[8]) { f[0] = bflo(v.x); f[1] = bfhi(v.x); f[2] = bflo(v.y); f[3] = bfhi(v.y); f[4] = bflo(v.z); f[5] = bfhi(v.z); f[6] = bflo(v.w); f[7] = bfhi(v.w); }
; __device__ __forceinline__ v4u pack8(const float (&f)[8]) { v4u o; o.x = cvt_pk_bf16(f[0], f[1]); o.y = cvt_pk_bf16(f[2], f[3]); o.z = cvt_pk_bf16(f[4], f[5]); o.w = cvt_pk_bf16(f[6], f[7]); return o; }
; __device__ __forceinline__ void phase_conv(const Params& P, int seg) {
;     ...
; #pragma unroll
;         for (int hb = 0; hb < 4; ++hb) { v4u rc[4], rh[4], rb[4];
; #pragma unroll
;             for (int i = 0; i < 4; ++i) { const GAS bf16* q = proj + (size_t)(lr0 + hb * 4 + i) * NPROJ; rc[i] = __builtin_nontemporal_load((const GAS v4u*)(q + OFF_SCC + c)); rh[i] = __builtin_nontemporal_load((const GAS v4u*)(q + OFF_SCH + c)); rb[i] = __builtin_nontemporal_load((const GAS v4u*)(q + OFF_SCB + c)); }
; #pragma unroll
;             for (int i = 0; i < 4; ++i) { float bv[8], y[8]; unpack8(rc[i], t0); unpack8(rh[i], t1); unpack8(rb[i], bv);
; #pragma unroll
;                 for (int e = 0; e < 8; ++e) { p2[e] = t0[e] * t1[e]; y[e] = bv[e] * (w0[e] * p0[e] + w1[e] * p1[e] + w2[e] * p2[e]); p0[e] = p1[e]; p1[e] = p2[e]; }
;                 *(GAS v4u*)(ya + (size_t)(lr0 + hb * 4 + i) * DM + c) = pack8(y); } }
	v_and_b32_e32 v141, 0xffff0000, v76
	v_fma_f32 v64, v7, v124, v64
	v_add_f32_e32 v64, v64, v65
	v_mul_f32_e32 v67, v64, v125
	v_cvt_pk_bf16_f32 v64, v126, v68
	v_cvt_pk_bf16_f32 v65, v72, v69
	v_lshlrev_b64 v[68:69], 12, v[42:43]
	v_lshl_add_u64 v[68:69], v[40:41], 0, v[68:69]
	v_cvt_pk_bf16_f32 v66, v73, v66
	v_cvt_pk_bf16_f32 v67, v70, v67
	global_store_dwordx4 v[68:69], v[64:67], off
	v_lshlrev_b32_e32 v43, 16, v76
	v_lshlrev_b32_e32 v158, 16, v77
	v_mov_b32_e32 v64, v12
	v_mov_b32_e32 v65, v24
	v_pk_mul_f32 v[66:67], v[64:65], v[108:109]
	v_and_b32_e32 v159, 0xffff0000, v77
	v_add_f32_e32 v108, v66, v67
	v_mov_b32_e32 v66, v13
	v_mov_b32_e32 v67, v25
	v_pk_mul_f32 v[68:69], v[66:67], v[110:111]
	s_waitcnt vmcnt(6)
	v_lshlrev_b32_e32 v96, 16, v92
	v_add_f32_e32 v110, v68, v69
	v_mov_b32_e32 v68, v14
	v_mov_b32_e32 v69, v26
	v_pk_mul_f32 v[70:71], v[68:69], v[112:113]
	v_lshlrev_b32_e32 v124, 16, v88
	v_add_f32_e32 v112, v70, v71
	v_mov_b32_e32 v70, v15
	v_mov_b32_e32 v71, v27
	v_pk_mul_f32 v[72:73], v[70:71], v[114:115]
	s_waitcnt vmcnt(5)
	v_lshlrev_b32_e32 v125, 16, v100
	v_add_f32_e32 v114, v72, v73
	v_mov_b32_e32 v72, v4
	v_mov_b32_e32 v73, v20
	v_pk_mul_f32 v[74:75], v[72:73], v[116:117]
	s_waitcnt vmcnt(4)
	v_lshlrev_b32_e32 v97, 16, v104
	v_add_f32_e32 v116, v74, v75
	v_mov_b32_e32 v74, v5
	v_mov_b32_e32 v75, v21
	v_pk_mul_f32 v[76:77], v[74:75], v[118:119]
	v_lshlrev_b32_e32 v160, 16, v78
	v_add_f32_e32 v118, v76, v77
	v_mov_b32_e32 v76, v6
	v_mov_b32_e32 v77, v22
	v_and_b32_e32 v161, 0xffff0000, v78
	v_lshlrev_b32_e32 v162, 16, v79
	v_and_b32_e32 v163, 0xffff0000, v79
	v_pk_mul_f32 v[78:79], v[76:77], v[120:121]
	v_pk_mul_f32 v[96:97], v[96:97], v[124:125]
	v_and_b32_e32 v92, 0xffff0000, v92
	v_and_b32_e32 v88, 0xffff0000, v88
	v_lshlrev_b32_e32 v126, 16, v93
	v_lshlrev_b32_e32 v128, 16, v89
	v_and_b32_e32 v130, 0xffff0000, v93
	v_and_b32_e32 v132, 0xffff0000, v89
	v_add_f32_e32 v120, v78, v79
	v_mov_b32_e32 v78, v7
	v_mov_b32_e32 v79, v23
	v_and_b32_e32 v89, 0xffff0000, v100
	v_and_b32_e32 v93, 0xffff0000, v104
	v_pk_mul_f32 v[82:83], v[44:45], v[96:97]
	v_lshlrev_b32_e32 v134, 16, v94
	v_lshlrev_b32_e32 v142, 16, v90
	v_and_b32_e32 v144, 0xffff0000, v94
	v_and_b32_e32 v146, 0xffff0000, v90
	v_lshlrev_b32_e32 v148, 16, v95
	v_lshlrev_b32_e32 v150, 16, v91
	v_and_b32_e32 v152, 0xffff0000, v95
	v_and_b32_e32 v154, 0xffff0000, v91
	v_pk_mul_f32 v[90:91], v[78:79], v[122:123]
	v_fma_f32 v82, v12, v109, v82
	v_pk_mul_f32 v[94:95], v[92:93], v[88:89]
	v_add_f32_e32 v122, v90, v91
	v_lshlrev_b32_e32 v90, 16, v84
	v_add_f32_e32 v82, v82, v83
	v_fmac_f32_e32 v110, v17, v94
	v_lshlrev_b32_e32 v135, 16, v106
	v_and_b32_e32 v145, 0xffff0000, v106
	v_fmac_f32_e32 v108, v16, v96
	v_mul_f32_e32 v106, v82, v90
	v_mul_f32_e32 v82, v110, v141
	v_lshlrev_b32_e32 v129, 16, v101
	v_lshlrev_b32_e32 v127, 16, v105
	v_mul_f32_e32 v43, v108, v43
	v_cvt_pk_bf16_f32 v100, v43, v82
	v_pk_mul_f32 v[82:83], v[46:47], v[94:95]
	v_pk_mul_f32 v[92:93], v[126:127], v[128:129]
	v_fma_f32 v43, v13, v111, v82
	v_add_f32_e32 v43, v43, v83
	v_pk_mul_f32 v[82:83], v[48:49], v[92:93]
	v_and_b32_e32 v133, 0xffff0000, v101
	v_fma_f32 v82, v14, v113, v82
	v_and_b32_e32 v131, 0xffff0000, v105
	v_lshlrev_b32_e32 v91, 16, v85
	v_add_f32_e32 v82, v82, v83
	v_lshlrev_b32_e32 v149, 16, v107
	v_and_b32_e32 v153, 0xffff0000, v107
	v_mul_f32_e32 v107, v82, v91
	v_pk_mul_f32 v[90:91], v[130:131], v[132:133]
	v_and_b32_e32 v84, 0xffff0000, v84
	v_fmac_f32_e32 v114, v19, v90
	v_fmac_f32_e32 v112, v18, v92
	v_mul_f32_e32 v82, v114, v159
	v_mul_f32_e32 v43, v43, v84
	v_mul_f32_e32 v84, v112, v158
	v_cvt_pk_bf16_f32 v101, v84, v82
	v_pk_mul_f32 v[82:83], v[50:51], v[90:91]
	v_lshlrev_b32_e32 v143, 16, v102
	v_fma_f32 v82, v15, v115, v82
	v_and_b32_e32 v85, 0xffff0000, v85
	v_add_f32_e32 v82, v82, v83
	v_pk_mul_f32 v[88:89], v[134:135], v[142:143]
	v_and_b32_e32 v147, 0xffff0000, v102
	v_mul_f32_e32 v108, v82, v85
	v_pk_mul_f32 v[82:83], v[52:53], v[88:89]
	v_lshlrev_b32_e32 v151, 16, v103
	v_and_b32_e32 v155, 0xffff0000, v103
	v_lshlrev_b32_e32 v102, 16, v86
	v_and_b32_e32 v103, 0xffff0000, v86
	v_lshlrev_b32_e32 v104, 16, v87
	v_and_b32_e32 v105, 0xffff0000, v87
	v_fma_f32 v82, v4, v117, v82
	v_pk_mul_f32 v[86:87], v[144:145], v[146:147]
	v_add_f32_e32 v82, v82, v83
	v_fmac_f32_e32 v118, v9, v86
	v_fmac_f32_e32 v116, v8, v88
	v_mul_f32_e32 v109, v82, v102
	v_mul_f32_e32 v82, v118, v161
	v_mul_f32_e32 v84, v116, v160
	v_cvt_pk_bf16_f32 v102, v84, v82
	v_pk_mul_f32 v[82:83], v[56:57], v[86:87]
	v_pk_mul_f32 v[84:85], v[148:149], v[150:151]
	v_fma_f32 v82, v5, v119, v82
	v_add_f32_e32 v82, v82, v83
	v_mul_f32_e32 v110, v82, v103
	v_pk_mul_f32 v[82:83], v[58:59], v[84:85]
	v_fmac_f32_e32 v120, v10, v84
	v_fma_f32 v82, v6, v121, v82
	v_add_f32_e32 v82, v82, v83
	v_mul_f32_e32 v104, v82, v104
	v_pk_mul_f32 v[82:83], v[152:153], v[154:155]
	v_mul_f32_e32 v103, v120, v162
	v_fmac_f32_e32 v122, v11, v82
	v_mul_f32_e32 v111, v122, v163
	v_cvt_pk_bf16_f32 v103, v103, v111
	global_store_dwordx4 v[156:157], v[100:103], off
	v_lshlrev_b32_e32 v111, 16, v39
	v_and_b32_e32 v112, 0xffff0000, v39
	v_pk_mul_f32 v[100:101], v[54:55], v[82:83]
	s_waitcnt vmcnt(3)
; #define GAS __attribute__((address_space(1)))
; __device__ __forceinline__ void unpack8(const v4u v, float (&f)[8]) { f[0] = bflo(v.x); f[1] = bfhi(v.x); f[2] = bflo(v.y); f[3] = bfhi(v.y); f[4] = bflo(v.z); f[5] = bfhi(v.z); f[6] = bflo(v.w); f[7] = bfhi(v.w); }
; __device__ __forceinline__ v4u pack8(const float (&f)[8]) { v4u o; o.x = cvt_pk_bf16(f[0], f[1]); o.y = cvt_pk_bf16(f[2], f[3]); o.z = cvt_pk_bf16(f[4], f[5]); o.w = cvt_pk_bf16(f[6], f[7]); return o; }
; __device__ __forceinline__ void phase_conv(const Params& P, int seg) {
;     ...
;         for (int hb = 0; hb < 4; ++hb) { v4u rc[4], rh[4], rb[4];
; #pragma unroll
;             for (int i = 0; i < 4; ++i) { const GAS bf16* q = proj + (size_t)(lr0 + hb * 4 + i) * NPROJ; rc[i] = __builtin_nontemporal_load((const GAS v4u*)(q + OFF_SCC + c)); rh[i] = __builtin_nontemporal_load((const GAS v4u*)(q + OFF_SCH + c)); rb[i] = __builtin_nontemporal_load((const GAS v4u*)(q + OFF_SCB + c)); }
; #pragma unroll
;             for (int i = 0; i < 4; ++i) { float bv[8], y[8]; unpack8(rc[i], t0); unpack8(rh[i], t1); unpack8(rb[i], bv);
; #pragma unroll
;                 for (int e = 0; e < 8; ++e) { p2[e] = t0[e] * t1[e]; y[e] = bv[e] * (w0[e] * p0[e] + w1[e] * p1[e] + w2[e] * p2[e]); p0[e] = p1[e]; p1[e] = p2[e]; }
;                 *(GAS v4u*)(ya + (size_t)(lr0 + hb * 4 + i) * DM + c) = pack8(y); } }
	v_lshlrev_b32_e32 v39, 16, v32
	v_fma_f32 v100, v7, v123, v100
	v_add_f32_e32 v100, v100, v101
	v_mul_f32_e32 v103, v100, v105
	v_cvt_pk_bf16_f32 v100, v106, v43
	v_cvt_pk_bf16_f32 v101, v107, v108
	v_cvt_pk_bf16_f32 v102, v109, v110
	v_cvt_pk_bf16_f32 v103, v104, v103
	global_store_dwordx4 v[98:99], v[100:103], off
	v_lshlrev_b32_e32 v43, 16, v36
	v_and_b32_e32 v106, 0xffff0000, v36
	v_lshlrev_b32_e32 v107, 16, v37
	v_and_b32_e32 v108, 0xffff0000, v37
	v_lshlrev_b32_e32 v109, 16, v38
	v_and_b32_e32 v110, 0xffff0000, v38
	v_lshlrev_b32_e32 v38, 16, v28
	v_pk_mul_f32 v[36:37], v[64:65], v[96:97]
	v_and_b32_e32 v101, 0xffff0000, v32
	v_and_b32_e32 v100, 0xffff0000, v28
	v_lshlrev_b32_e32 v98, 16, v29
	v_and_b32_e32 v32, 0xffff0000, v29
	v_pk_mul_f32 v[28:29], v[70:71], v[90:91]
	v_add_f32_e32 v96, v36, v37
	v_pk_mul_f32 v[36:37], v[66:67], v[94:95]
	v_add_f32_e32 v90, v28, v29
	v_pk_mul_f32 v[28:29], v[72:73], v[88:89]
	v_add_f32_e32 v94, v36, v37
	v_pk_mul_f32 v[36:37], v[68:69], v[92:93]
	v_add_f32_e32 v88, v28, v29
	v_pk_mul_f32 v[28:29], v[74:75], v[86:87]
	v_add_f32_e32 v92, v36, v37
	v_lshlrev_b32_e32 v37, 16, v34
	v_lshlrev_b32_e32 v36, 16, v30
	v_and_b32_e32 v103, 0xffff0000, v34
	v_and_b32_e32 v102, 0xffff0000, v30
	v_add_f32_e32 v86, v28, v29
	v_lshlrev_b32_e32 v28, 16, v31
	v_and_b32_e32 v34, 0xffff0000, v31
	v_pk_mul_f32 v[30:31], v[78:79], v[82:83]
	v_or_b32_e32 v124, 4, v42
	v_add_f32_e32 v82, v30, v31
	v_lshlrev_b64 v[30:31], 12, v[80:81]
	v_lshlrev_b32_e32 v29, 16, v35
	v_lshl_add_u64 v[80:81], v[40:41], 0, v[30:31]
	v_mad_i64_i32 v[30:31], s[24:25], v124, s4, v[62:63]
	v_and_b32_e32 v35, 0xffff0000, v35
	v_lshl_add_u64 v[120:121], v[30:31], 0, v[60:61]
	v_mov_b32_e32 v30, v29
	v_pk_mul_f32 v[30:31], v[30:31], v[28:29]
	v_pk_mul_f32 v[28:29], v[34:35], v[34:35] op_sel:[1,0] op_sel_hi:[0,1]
	v_lshlrev_b32_e32 v99, 16, v33
	v_fmac_f32_e32 v82, v11, v28
	v_and_b32_e32 v33, 0xffff0000, v33
	v_mul_f32_e32 v29, v82, v112
	v_mov_b32_e32 v34, v37
	v_mov_b32_e32 v82, v99
	v_pk_mul_f32 v[36:37], v[34:35], v[36:37]
	v_pk_mul_f32 v[34:35], v[102:103], v[102:103] op_sel:[1,0] op_sel_hi:[0,1]
	v_pk_mul_f32 v[102:103], v[82:83], v[98:99]
	v_pk_mul_f32 v[98:99], v[32:33], v[32:33] op_sel:[1,0] op_sel_hi:[0,1]
	v_fmac_f32_e32 v90, v19, v98
	v_mul_f32_e32 v33, v90, v108
	v_mov_b32_e32 v32, v39
	v_fmac_f32_e32 v88, v8, v36
	v_pk_mul_f32 v[114:115], v[32:33], v[38:39]
	v_pk_mul_f32 v[104:105], v[76:77], v[84:85]
	v_mul_f32_e32 v37, v88, v109
	v_fmac_f32_e32 v96, v16, v114
	v_pk_mul_f32 v[108:109], v[100:101], v[100:101] op_sel:[1,0] op_sel_hi:[0,1]
	v_add_f32_e32 v84, v104, v105
	v_mul_f32_e32 v32, v96, v43
	v_fmac_f32_e32 v94, v17, v108
	v_fmac_f32_e32 v84, v10, v30
	v_fmac_f32_e32 v86, v9, v34
	v_fmac_f32_e32 v92, v18, v102
	v_mul_f32_e32 v38, v94, v106
	v_cvt_pk_bf16_f32 v104, v32, v38
	v_add_co_u32_e32 v32, vcc, s33, v120
	v_mul_f32_e32 v31, v84, v111
	v_mul_f32_e32 v35, v86, v110
	v_mul_f32_e32 v82, v92, v107
	v_cvt_pk_bf16_f32 v105, v82, v33
	v_cvt_pk_bf16_f32 v106, v37, v35
	v_cvt_pk_bf16_f32 v107, v31, v29
	global_store_dwordx4 v[80:81], v[104:107], off
	v_add_co_u32_e64 v251, s[48:49], s33, v120
	v_addc_co_u32_e64 v250, s[48:49], 0, v121, s[48:49]
	v_mov_b32_e32 v248, v32
	v_mov_b32_e32 v249, v250
	global_load_dwordx4 v[244:247], v[248:249], off offset:-4096 nt
	v_addc_co_u32_e32 v33, vcc, 0, v121, vcc
	v_or_b32_e32 v38, 5, v42
	s_nop 0
	s_nop 0
	s_nop 0
	global_load_dwordx4 v[120:123], v[120:121], off nt
	v_mad_i64_i32 v[32:33], s[24:25], v38, s4, v[62:63]
	v_lshl_add_u64 v[32:33], v[32:33], 0, v[60:61]
	global_load_dwordx4 v[126:129], v[32:33], off nt
	v_add_co_u32_e64 v251, s[48:49], s33, v32
	v_addc_co_u32_e64 v250, s[48:49], 0, v33, s[48:49]
	v_mov_b32_e32 v248, v251
	v_mov_b32_e32 v249, v250
	global_load_dwordx4 v[218:221], v[248:249], off nt
	v_add_co_u32_e32 v32, vcc, s33, v32
	v_ashrrev_i32_e32 v39, 31, v38
	s_nop 0
	v_addc_co_u32_e32 v33, vcc, 0, v33, vcc
	s_nop 0
	global_load_dwordx4 v[146:149], v[32:33], off offset:-4096 nt
	v_mad_i64_i32 v[32:33], s[24:25], v170, s4, v[62:63]
	v_lshl_add_u64 v[80:81], v[32:33], 0, v[60:61]
	v_add_co_u32_e32 v104, vcc, s33, v80
	global_load_dwordx4 v[158:161], v[80:81], off nt
	s_nop 0
	v_addc_co_u32_e32 v105, vcc, 0, v81, vcc
	global_load_dwordx4 v[150:153], v[104:105], off offset:-4096 nt
	global_load_dwordx4 v[154:157], v[104:105], off nt
	v_or_b32_e32 v32, 7, v42
	v_mad_i64_i32 v[100:101], s[24:25], v32, s4, v[62:63]
	v_lshl_add_u64 v[130:131], v[100:101], 0, v[60:61]
	v_add_co_u32_e32 v104, vcc, s33, v130
	v_lshlrev_b64 v[38:39], 12, v[38:39]
	s_nop 0
	v_addc_co_u32_e32 v105, vcc, 0, v131, vcc
	global_load_dwordx4 v[162:165], v[104:105], off offset:-4096 nt
	global_load_dwordx4 v[166:169], v[104:105], off nt
	global_load_dwordx4 v[184:187], v[130:131], off nt
	v_ashrrev_i32_e32 v125, 31, v124
	v_lshlrev_b64 v[100:101], 12, v[124:125]
	v_mov_b32_e32 v124, v14
	v_mov_b32_e32 v125, v18
	v_lshl_add_u64 v[188:189], v[40:41], 0, v[100:101]
	v_mov_b32_e32 v134, v15
	v_mov_b32_e32 v135, v19
	v_mov_b32_e32 v106, v4
	v_mov_b32_e32 v107, v8
	v_mov_b32_e32 v100, v6
	v_mov_b32_e32 v101, v10
	v_mov_b32_e32 v104, v7
	v_mov_b32_e32 v105, v11
	v_ashrrev_i32_e32 v33, 31, v32
	s_waitcnt vmcnt(15)
	v_lshlrev_b32_e32 v80, 16, v234
	s_waitcnt vmcnt(10)
	v_lshlrev_b32_e32 v196, 16, v244
	v_and_b32_e32 v192, 0xffff0000, v234
	v_and_b32_e32 v198, 0xffff0000, v235
	v_lshlrev_b32_e32 v202, 16, v235
	v_lshl_add_u64 v[110:111], v[40:41], 0, v[38:39]
	v_and_b32_e32 v194, 0xffff0000, v244
	s_waitcnt vmcnt(9)
	v_lshlrev_b32_e32 v29, 16, v120
	v_lshlrev_b32_e32 v204, 16, v245
	v_and_b32_e32 v200, 0xffff0000, v245
	v_and_b32_e32 v206, 0xffff0000, v236
	s_waitcnt vmcnt(7)
; #define GAS __attribute__((address_space(1)))
; __device__ __forceinline__ void unpack8(const v4u v, float (&f)[8]) { f[0] = bflo(v.x); f[1] = bfhi(v.x); f[2] = bflo(v.y); f[3] = bfhi(v.y); f[4] = bflo(v.z); f[5] = bfhi(v.z); f[6] = bflo(v.w); f[7] = bfhi(v.w); }
; __device__ __forceinline__ v4u pack8(const float (&f)[8]) { v4u o; o.x = cvt_pk_bf16(f[0], f[1]); o.y = cvt_pk_bf16(f[2], f[3]); o.z = cvt_pk_bf16(f[4], f[5]); o.w = cvt_pk_bf16(f[6], f[7]); return o; }
; __device__ __forceinline__ void phase_conv(const Params& P, int seg) {
;     ...
;             for (int i = 0; i < 4; ++i) { float bv[8], y[8]; unpack8(rc[i], t0); unpack8(rh[i], t1); unpack8(rb[i], bv);
; #pragma unroll
;                 for (int e = 0; e < 8; ++e) { p2[e] = t0[e] * t1[e]; y[e] = bv[e] * (w0[e] * p0[e] + w1[e] * p1[e] + w2[e] * p2[e]); p0[e] = p1[e]; p1[e] = p2[e]; }
;                 *(GAS v4u*)(ya + (size_t)(lr0 + hb * 4 + i) * DM + c) = pack8(y); } }
	v_lshlrev_b32_e32 v82, 16, v218
	v_and_b32_e32 v222, 0xffff0000, v218
	v_lshlrev_b32_e32 v226, 16, v219
	v_and_b32_e32 v230, 0xffff0000, v219
	v_and_b32_e32 v208, 0xffff0000, v246
	v_lshlrev_b32_e32 v210, 16, v236
	v_lshlrev_b32_e32 v212, 16, v246
	v_and_b32_e32 v31, 0xffff0000, v120
	v_lshlrev_b32_e32 v141, 16, v126
	v_and_b32_e32 v174, 0xffff0000, v126
	s_waitcnt vmcnt(4)
	v_lshlrev_b32_e32 v197, 16, v150
	s_waitcnt vmcnt(3)
	v_lshlrev_b32_e32 v81, 16, v154
	v_pk_mul_f32 v[38:39], v[80:81], v[196:197]
	v_and_b32_e32 v195, 0xffff0000, v150
	v_mov_b32_e32 v115, v38
	v_pk_mul_f32 v[80:81], v[44:45], v[114:115]
	v_and_b32_e32 v193, 0xffff0000, v154
	v_fma_f32 v80, v12, v97, v80
	v_add_f32_e32 v80, v80, v81
	v_mul_f32_e32 v29, v80, v29
	v_pk_mul_f32 v[80:81], v[192:193], v[194:195]
	v_lshlrev_b32_e32 v205, 16, v151
	v_mov_b32_e32 v109, v80
	v_lshlrev_b32_e32 v203, 16, v155
	v_pk_mul_f32 v[142:143], v[46:47], v[108:109]
	v_lshlrev_b32_e32 v130, 16, v220
	v_fma_f32 v86, v13, v95, v142
	v_pk_mul_f32 v[94:95], v[202:203], v[204:205]
	v_and_b32_e32 v126, 0xffff0000, v220
	v_mov_b32_e32 v103, v94
	v_lshlrev_b32_e32 v118, 16, v221
	v_and_b32_e32 v112, 0xffff0000, v221
	v_and_b32_e32 v201, 0xffff0000, v151
	v_and_b32_e32 v199, 0xffff0000, v155
	v_add_f32_e32 v86, v86, v143
	v_pk_mul_f32 v[144:145], v[48:49], v[102:103]
	v_mul_f32_e32 v31, v86, v31
	v_cvt_pk_bf16_f32 v142, v29, v31
	v_fma_f32 v29, v14, v93, v144
	v_pk_mul_f32 v[92:93], v[198:199], v[200:201]
	v_add_f32_e32 v29, v29, v145
	v_mov_b32_e32 v99, v92
	v_pk_mul_f32 v[144:145], v[50:51], v[98:99]
	v_lshlrev_b32_e32 v213, 16, v152
	v_lshlrev_b32_e32 v211, 16, v156
	v_fma_f32 v31, v15, v91, v144
	v_and_b32_e32 v37, 0xffff0000, v121
	v_add_f32_e32 v31, v31, v145
	v_pk_mul_f32 v[90:91], v[210:211], v[212:213]
	v_lshlrev_b32_e32 v35, 16, v121
	v_mul_f32_e32 v31, v31, v37
	v_mov_b32_e32 v37, v90
	v_and_b32_e32 v209, 0xffff0000, v152
	v_and_b32_e32 v207, 0xffff0000, v156
	v_mul_f32_e32 v29, v29, v35
	v_pk_mul_f32 v[144:145], v[52:53], v[36:37]
	v_cvt_pk_bf16_f32 v143, v29, v31
	v_and_b32_e32 v84, 0xffff0000, v122
	v_fma_f32 v29, v4, v89, v144
	v_pk_mul_f32 v[88:89], v[206:207], v[208:209]
	v_add_f32_e32 v29, v29, v145
	v_mov_b32_e32 v35, v88
	v_pk_mul_f32 v[144:145], v[56:57], v[34:35]
	v_lshlrev_b32_e32 v214, 16, v237
	v_fma_f32 v31, v5, v87, v144
	v_lshlrev_b32_e32 v216, 16, v247
	v_lshlrev_b32_e32 v217, 16, v153
	v_lshlrev_b32_e32 v215, 16, v157
	v_add_f32_e32 v31, v31, v145
	v_lshlrev_b32_e32 v43, 16, v122
	v_mul_f32_e32 v31, v31, v84
	v_pk_mul_f32 v[86:87], v[214:215], v[216:217]
	v_mul_f32_e32 v29, v29, v43
	v_cvt_pk_bf16_f32 v144, v29, v31
	v_mov_b32_e32 v31, v86
	v_lshlrev_b32_e32 v248, 16, v160
	v_and_b32_e32 v249, 0xffff0000, v160
	v_lshlrev_b32_e32 v250, 16, v161
	v_and_b32_e32 v251, 0xffff0000, v161
	v_pk_mul_f32 v[160:161], v[58:59], v[30:31]
	v_and_b32_e32 v218, 0xffff0000, v237
	v_and_b32_e32 v220, 0xffff0000, v247
	v_and_b32_e32 v221, 0xffff0000, v153
	v_and_b32_e32 v219, 0xffff0000, v157
	v_fma_f32 v29, v6, v85, v160
	v_lshlrev_b32_e32 v117, 16, v123
	v_add_f32_e32 v29, v29, v161
	v_pk_mul_f32 v[84:85], v[218:219], v[220:221]
	v_mul_f32_e32 v31, v29, v117
	v_mov_b32_e32 v29, v84
	v_pk_mul_f32 v[192:193], v[54:55], v[28:29]
	v_lshlrev_b32_e32 v96, 16, v146
	v_fma_f32 v29, v7, v83, v192
	s_waitcnt vmcnt(2)
	v_lshlrev_b32_e32 v97, 16, v162
	s_waitcnt vmcnt(1)
	v_lshlrev_b32_e32 v83, 16, v166
	v_pk_mul_f32 v[82:83], v[82:83], v[96:97]
	v_lshlrev_b32_e32 v235, 16, v128
	v_mov_b32_e32 v115, v82
	v_and_b32_e32 v236, 0xffff0000, v128
	v_lshlrev_b32_e32 v132, 16, v148
	v_and_b32_e32 v128, 0xffff0000, v148
	v_lshlrev_b32_e32 v120, 16, v149
	v_and_b32_e32 v116, 0xffff0000, v149
	v_pk_mul_f32 v[148:149], v[190:191], v[38:39]
	v_pk_mul_f32 v[96:97], v[190:191], v[114:115]
	v_lshlrev_b32_e32 v244, 16, v158
	v_fma_f32 v38, v24, v38, v96
	v_fma_f32 v96, v24, v82, v148
	v_add_f32_e32 v38, v38, v97
	v_add_f32_e32 v96, v96, v149
	v_mul_f32_e32 v38, v38, v141
	v_mul_f32_e32 v141, v96, v244
	v_pk_mul_f32 v[96:97], v[190:191], v[82:83]
	v_and_b32_e32 v146, 0xffff0000, v146
	v_lshlrev_b32_e32 v228, 16, v147
	v_and_b32_e32 v232, 0xffff0000, v147
	v_and_b32_e32 v147, 0xffff0000, v162
	v_and_b32_e32 v223, 0xffff0000, v166
	v_fma_f32 v24, v24, v39, v96
	v_and_b32_e32 v121, 0xffff0000, v123
	v_add_f32_e32 v29, v29, v193
	v_add_f32_e32 v24, v24, v97
	v_pk_mul_f32 v[96:97], v[222:223], v[146:147]
	v_mul_f32_e32 v29, v29, v121
	v_mov_b32_e32 v109, v96
	v_cvt_pk_bf16_f32 v145, v31, v29
	s_waitcnt vmcnt(0)
; #define GAS __attribute__((address_space(1)))
; __device__ __forceinline__ void unpack8(const v4u v, float (&f)[8]) { f[0] = bflo(v.x); f[1] = bfhi(v.x); f[2] = bflo(v.y); f[3] = bfhi(v.y); f[4] = bflo(v.z); f[5] = bfhi(v.z); f[6] = bflo(v.w); f[7] = bfhi(v.w); }
; __device__ __forceinline__ v4u pack8(const float (&f)[8]) { v4u o; o.x = cvt_pk_bf16(f[0], f[1]); o.y = cvt_pk_bf16(f[2], f[3]); o.z = cvt_pk_bf16(f[4], f[5]); o.w = cvt_pk_bf16(f[6], f[7]); return o; }
; __device__ __forceinline__ void phase_conv(const Params& P, int seg) {
;     ...
;         for (int hb = 0; hb < 4; ++hb) { v4u rc[4], rh[4], rb[4];
; #pragma unroll
;             for (int i = 0; i < 4; ++i) { const GAS bf16* q = proj + (size_t)(lr0 + hb * 4 + i) * NPROJ; rc[i] = __builtin_nontemporal_load((const GAS v4u*)(q + OFF_SCC + c)); rh[i] = __builtin_nontemporal_load((const GAS v4u*)(q + OFF_SCH + c)); rb[i] = __builtin_nontemporal_load((const GAS v4u*)(q + OFF_SCB + c)); }
; #pragma unroll
;             for (int i = 0; i < 4; ++i) { float bv[8], y[8]; unpack8(rc[i], t0); unpack8(rh[i], t1); unpack8(rb[i], bv);
; #pragma unroll
;                 for (int e = 0; e < 8; ++e) { p2[e] = t0[e] * t1[e]; y[e] = bv[e] * (w0[e] * p0[e] + w1[e] * p1[e] + w2[e] * p2[e]); p0[e] = p1[e]; p1[e] = p2[e]; }
;                 *(GAS v4u*)(ya + (size_t)(lr0 + hb * 4 + i) * DM + c) = pack8(y); } }
	v_lshlrev_b32_e32 v29, 16, v184
	v_pk_mul_f32 v[108:109], v[224:225], v[108:109]
	v_mul_f32_e32 v82, v24, v29
	v_fma_f32 v24, v25, v80, v108
	v_pk_mul_f32 v[150:151], v[224:225], v[80:81]
	v_add_f32_e32 v24, v24, v109
	v_pk_mul_f32 v[108:109], v[224:225], v[96:97]
	v_lshlrev_b32_e32 v229, 16, v163
	v_lshlrev_b32_e32 v227, 16, v167
	v_fma_f32 v29, v25, v96, v150
	v_fma_f32 v25, v25, v81, v108
	v_add_f32_e32 v25, v25, v109
	v_pk_mul_f32 v[108:109], v[226:227], v[228:229]
	v_and_b32_e32 v31, 0xffff0000, v184
	v_mov_b32_e32 v103, v108
	v_mul_f32_e32 v24, v24, v174
	v_pk_mul_f32 v[102:103], v[124:125], v[102:103]
	global_store_dwordx4 v[188:189], v[142:145], off
	v_or_b32_e32 v247, 8, v42
	v_mad_i64_i32 v[244:245], s[48:49], v247, s4, v[62:63]
	v_lshl_add_u64 v[228:229], v[244:245], 0, v[60:61]
	global_load_dwordx4 v[224:227], v[228:229], off nt
	v_or_b32_e32 v247, 8, v42
	v_mad_i64_i32 v[244:245], s[48:49], v247, s4, v[62:63]
	v_lshl_add_u64 v[228:229], v[244:245], 0, v[60:61]
	v_add_co_u32_e64 v246, s[48:49], s33, v228
	v_addc_co_u32_e64 v243, s[48:49], 0, v229, s[48:49]
	v_mov_b32_e32 v218, v246
	v_mov_b32_e32 v219, v243
	global_load_dwordx4 v[220:223], v[218:219], off nt
	v_or_b32_e32 v247, 8, v42
	v_mad_i64_i32 v[244:245], s[48:49], v247, s4, v[62:63]
	v_lshl_add_u64 v[228:229], v[244:245], 0, v[60:61]
	v_add_co_u32_e64 v246, s[48:49], s33, v228
	v_addc_co_u32_e64 v243, s[48:49], 0, v229, s[48:49]
	v_mov_b32_e32 v214, v246
	v_mov_b32_e32 v215, v243
	global_load_dwordx4 v[216:219], v[214:215], off offset:-4096 nt
	v_or_b32_e32 v247, 9, v42
	v_mad_i64_i32 v[244:245], s[48:49], v247, s4, v[62:63]
	v_lshl_add_u64 v[228:229], v[244:245], 0, v[60:61]
	v_add_co_u32_e64 v246, s[48:49], s33, v228
	v_add_co_u32_e64 v246, s[48:49], s33, v228
	v_addc_co_u32_e64 v243, s[48:49], 0, v229, s[48:49]
	v_mov_b32_e32 v210, v246
	v_mov_b32_e32 v211, v243
	global_load_dwordx4 v[212:215], v[210:211], off offset:-4096 nt
	v_or_b32_e32 v247, 9, v42
	v_mad_i64_i32 v[244:245], s[48:49], v247, s4, v[62:63]
	v_lshl_add_u64 v[228:229], v[244:245], 0, v[60:61]
	v_add_co_u32_e64 v246, s[48:49], s33, v228
	v_add_co_u32_e64 v246, s[48:49], s33, v228
	v_addc_co_u32_e64 v243, s[48:49], 0, v229, s[48:49]
	v_mov_b32_e32 v206, v246
	v_mov_b32_e32 v207, v243
	global_load_dwordx4 v[208:211], v[206:207], off nt
	v_or_b32_e32 v247, 9, v42
	v_mad_i64_i32 v[244:245], s[48:49], v247, s4, v[62:63]
	v_lshl_add_u64 v[228:229], v[244:245], 0, v[60:61]
	global_load_dwordx4 v[204:207], v[228:229], off nt
	v_or_b32_e32 v247, 10, v42
	v_mad_i64_i32 v[244:245], s[48:49], v247, s4, v[62:63]
	v_lshl_add_u64 v[228:229], v[244:245], 0, v[60:61]
	v_add_co_u32_e64 v246, s[48:49], s33, v228
	v_add_co_u32_e64 v246, s[48:49], s33, v228
	v_addc_co_u32_e64 v243, s[48:49], 0, v229, s[48:49]
	v_mov_b32_e32 v198, v246
	v_mov_b32_e32 v199, v243
	global_load_dwordx4 v[200:203], v[198:199], off offset:-4096 nt
	v_or_b32_e32 v247, 10, v42
	v_mad_i64_i32 v[244:245], s[48:49], v247, s4, v[62:63]
	v_lshl_add_u64 v[228:229], v[244:245], 0, v[60:61]
	v_add_co_u32_e64 v246, s[48:49], s33, v228
	v_add_co_u32_e64 v246, s[48:49], s33, v228
	v_addc_co_u32_e64 v243, s[48:49], 0, v229, s[48:49]
	v_mov_b32_e32 v194, v246
	v_mov_b32_e32 v195, v243
	global_load_dwordx4 v[196:199], v[194:195], off nt
	v_or_b32_e32 v247, 11, v42
	v_mad_i64_i32 v[244:245], s[48:49], v247, s4, v[62:63]
	v_lshl_add_u64 v[228:229], v[244:245], 0, v[60:61]
	v_add_co_u32_e64 v246, s[48:49], s33, v228
	v_add_co_u32_e64 v246, s[48:49], s33, v228
	v_addc_co_u32_e64 v243, s[48:49], 0, v229, s[48:49]
	v_mov_b32_e32 v190, v246
	v_mov_b32_e32 v191, v243
	global_load_dwordx4 v[192:195], v[190:191], off offset:-4096 nt
	v_or_b32_e32 v247, 11, v42
	v_mad_i64_i32 v[244:245], s[48:49], v247, s4, v[62:63]
	v_lshl_add_u64 v[228:229], v[244:245], 0, v[60:61]
	v_add_co_u32_e64 v246, s[48:49], s33, v228
	v_add_co_u32_e64 v246, s[48:49], s33, v228
	v_addc_co_u32_e64 v243, s[48:49], 0, v229, s[48:49]
	v_mov_b32_e32 v160, v246
	v_mov_b32_e32 v161, v243
	global_load_dwordx4 v[188:191], v[160:161], off nt
	v_cvt_pk_bf16_f32 v24, v38, v24
	v_mul_f32_e32 v38, v25, v31
	v_fma_f32 v25, v26, v94, v102
	v_and_b32_e32 v245, 0xffff0000, v158
	v_pk_mul_f32 v[152:153], v[124:125], v[94:95]
	v_add_f32_e32 v29, v29, v151
	v_add_f32_e32 v25, v25, v103
	v_pk_mul_f32 v[102:103], v[124:125], v[108:109]
	v_and_b32_e32 v233, 0xffff0000, v163
	v_and_b32_e32 v231, 0xffff0000, v167
	v_mul_f32_e32 v80, v29, v245
	v_fma_f32 v29, v26, v108, v152
	v_fma_f32 v26, v26, v95, v102
	v_add_f32_e32 v26, v26, v103
	v_pk_mul_f32 v[102:103], v[230:231], v[232:233]
	v_lshlrev_b32_e32 v35, 16, v185
	v_mov_b32_e32 v99, v102
	v_pk_mul_f32 v[98:99], v[134:135], v[98:99]
	v_mul_f32_e32 v96, v26, v35
	v_fma_f32 v26, v27, v92, v98
	v_lshlrev_b32_e32 v179, 16, v127
	v_and_b32_e32 v234, 0xffff0000, v127
	v_add_f32_e32 v26, v26, v99
	v_mul_f32_e32 v25, v25, v179
	v_mul_f32_e32 v26, v26, v234
	v_pk_mul_f32 v[98:99], v[134:135], v[102:103]
	v_lshlrev_b32_e32 v133, 16, v164
	v_lshlrev_b32_e32 v131, 16, v168
	v_cvt_pk_bf16_f32 v25, v25, v26
	v_fma_f32 v26, v27, v93, v98
	v_lshlrev_b32_e32 v246, 16, v159
	v_pk_mul_f32 v[154:155], v[134:135], v[92:93]
	v_and_b32_e32 v37, 0xffff0000, v185
	v_add_f32_e32 v29, v29, v153
	v_add_f32_e32 v26, v26, v99
	v_pk_mul_f32 v[98:99], v[130:131], v[132:133]
	v_mul_f32_e32 v94, v29, v246
	v_fma_f32 v29, v27, v102, v154
	v_mul_f32_e32 v102, v26, v37
	v_mov_b32_e32 v37, v98
	v_pk_mul_f32 v[26:27], v[106:107], v[36:37]
	v_and_b32_e32 v247, 0xffff0000, v159
	v_fma_f32 v26, v20, v90, v26
	v_pk_mul_f32 v[156:157], v[106:107], v[90:91]
	v_add_f32_e32 v29, v29, v155
	v_add_f32_e32 v26, v26, v27
; #define GAS __attribute__((address_space(1)))
; __device__ __forceinline__ void unpack8(const v4u v, float (&f)[8]) { f[0] = bflo(v.x); f[1] = bfhi(v.x); f[2] = bflo(v.y); f[3] = bfhi(v.y); f[4] = bflo(v.z); f[5] = bfhi(v.z); f[6] = bflo(v.w); f[7] = bfhi(v.w); }
; __device__ __forceinline__ v4u pack8(const float (&f)[8]) { v4u o; o.x = cvt_pk_bf16(f[0], f[1]); o.y = cvt_pk_bf16(f[2], f[3]); o.z = cvt_pk_bf16(f[4], f[5]); o.w = cvt_pk_bf16(f[6], f[7]); return o; }
; __device__ __forceinline__ void phase_conv(const Params& P, int seg) {
;     ...
;         for (int hb = 0; hb < 4; ++hb) { v4u rc[4], rh[4], rb[4];
; #pragma unroll
;             for (int i = 0; i < 4; ++i) { const GAS bf16* q = proj + (size_t)(lr0 + hb * 4 + i) * NPROJ; rc[i] = __builtin_nontemporal_load((const GAS v4u*)(q + OFF_SCC + c)); rh[i] = __builtin_nontemporal_load((const GAS v4u*)(q + OFF_SCH + c)); rb[i] = __builtin_nontemporal_load((const GAS v4u*)(q + OFF_SCB + c)); }
; #pragma unroll
;             for (int i = 0; i < 4; ++i) { float bv[8], y[8]; unpack8(rc[i], t0); unpack8(rh[i], t1); unpack8(rb[i], bv);
; #pragma unroll
;                 for (int e = 0; e < 8; ++e) { p2[e] = t0[e] * t1[e]; y[e] = bv[e] * (w0[e] * p0[e] + w1[e] * p1[e] + w2[e] * p2[e]); p0[e] = p1[e]; p1[e] = p2[e]; }
;                 *(GAS v4u*)(ya + (size_t)(lr0 + hb * 4 + i) * DM + c) = pack8(y); } }
	v_mul_f32_e32 v92, v29, v247
	v_mul_f32_e32 v29, v26, v235
	v_fma_f32 v26, v20, v98, v156
	v_lshlrev_b32_e32 v237, 16, v129
	v_and_b32_e32 v243, 0xffff0000, v129
	v_and_b32_e32 v129, 0xffff0000, v164
	v_and_b32_e32 v127, 0xffff0000, v168
	v_add_f32_e32 v26, v26, v157
	v_mul_f32_e32 v36, v26, v248
	v_pk_mul_f32 v[26:27], v[106:107], v[98:99]
	v_pk_mul_f32 v[106:107], v[126:127], v[128:129]
	v_mov_b32_e32 v122, v5
	v_mov_b32_e32 v123, v9
	v_fma_f32 v20, v20, v91, v26
	v_mov_b32_e32 v35, v106
	v_lshlrev_b32_e32 v43, 16, v186
	v_add_f32_e32 v20, v20, v27
	v_pk_mul_f32 v[26:27], v[122:123], v[34:35]
	v_pk_mul_f32 v[158:159], v[122:123], v[88:89]
	v_mul_f32_e32 v37, v20, v43
	v_fma_f32 v20, v21, v88, v26
	v_add_f32_e32 v20, v20, v27
	v_fma_f32 v26, v21, v106, v158
	v_lshlrev_b32_e32 v121, 16, v165
	v_lshlrev_b32_e32 v119, 16, v169
	v_mul_f32_e32 v20, v20, v236
	v_add_f32_e32 v26, v26, v159
	v_pk_mul_f32 v[34:35], v[122:123], v[106:107]
	v_mul_f32_e32 v43, v26, v249
	v_cvt_pk_bf16_f32 v26, v29, v20
	v_fma_f32 v20, v21, v89, v34
	v_pk_mul_f32 v[114:115], v[118:119], v[120:121]
	v_and_b32_e32 v162, 0xffff0000, v186
	v_add_f32_e32 v20, v20, v35
	v_mov_b32_e32 v31, v114
	v_mul_f32_e32 v34, v20, v162
	v_pk_mul_f32 v[20:21], v[100:101], v[30:31]
	v_pk_mul_f32 v[160:161], v[100:101], v[86:87]
	v_fma_f32 v20, v22, v86, v20
	v_add_f32_e32 v20, v20, v21
	v_mul_f32_e32 v27, v20, v237
	v_fma_f32 v20, v22, v114, v160
	v_add_f32_e32 v20, v20, v161
	v_and_b32_e32 v117, 0xffff0000, v165
	v_and_b32_e32 v113, 0xffff0000, v169
	v_mul_f32_e32 v30, v20, v250
	v_pk_mul_f32 v[20:21], v[100:101], v[114:115]
	v_pk_mul_f32 v[100:101], v[112:113], v[116:117]
	v_fma_f32 v20, v22, v87, v20
	v_lshlrev_b32_e32 v163, 16, v187
	v_add_f32_e32 v20, v20, v21
	v_mov_b32_e32 v29, v100
	v_mul_f32_e32 v31, v20, v163
	v_pk_mul_f32 v[20:21], v[104:105], v[28:29]
	v_pk_mul_f32 v[142:143], v[104:105], v[84:85]
	v_fma_f32 v20, v23, v84, v20
	v_add_f32_e32 v20, v20, v21
	v_fma_f32 v21, v23, v100, v142
	v_add_f32_e32 v21, v21, v143
	v_mul_f32_e32 v20, v20, v243
	v_mul_f32_e32 v21, v21, v251
	v_cvt_pk_bf16_f32 v27, v27, v20
	v_lshlrev_b64 v[144:145], 12, v[170:171]
	global_store_dwordx4 v[110:111], v[24:27], off
	v_or_b32_e32 v251, 10, v42
	v_mad_i64_i32 v[248:249], s[48:49], v251, s4, v[62:63]
	v_lshl_add_u64 v[246:247], v[248:249], 0, v[60:61]
	global_load_dwordx4 v[234:237], v[246:247], off nt
	v_or_b32_e32 v251, 11, v42
	v_mad_i64_i32 v[248:249], s[48:49], v251, s4, v[62:63]
	v_lshl_add_u64 v[246:247], v[248:249], 0, v[60:61]
	global_load_dwordx4 v[230:233], v[246:247], off nt
	v_or_b32_e32 v251, 12, v42
	v_mad_i64_i32 v[248:249], s[48:49], v251, s4, v[62:63]
	v_lshl_add_u64 v[246:247], v[248:249], 0, v[60:61]
	global_load_dwordx4 v[168:171], v[246:247], off nt
	v_lshl_add_u64 v[144:145], v[40:41], 0, v[144:145]
	v_and_b32_e32 v164, 0xffff0000, v187
	v_cvt_pk_bf16_f32 v24, v141, v80
	v_cvt_pk_bf16_f32 v25, v94, v92
	v_cvt_pk_bf16_f32 v26, v36, v43
	v_cvt_pk_bf16_f32 v27, v30, v21
	v_pk_mul_f32 v[20:21], v[104:105], v[100:101]
	global_store_dwordx4 v[144:145], v[24:27], off
	v_or_b32_e32 v251, 12, v42
	v_mad_i64_i32 v[248:249], s[48:49], v251, s4, v[62:63]
	v_lshl_add_u64 v[246:247], v[248:249], 0, v[60:61]
	v_add_co_u32_e64 v250, s[48:49], s33, v246
	v_addc_co_u32_e64 v245, s[48:49], 0, v247, s[48:49]
	v_mov_b32_e32 v228, v250
	v_mov_b32_e32 v229, v245
	global_load_dwordx4 v[184:187], v[228:229], off nt
	v_fma_f32 v20, v23, v85, v20
	v_add_f32_e32 v20, v20, v21
	v_lshlrev_b64 v[24:25], 12, v[32:33]
	v_mul_f32_e32 v23, v20, v164
	v_cvt_pk_bf16_f32 v20, v82, v38
	v_cvt_pk_bf16_f32 v21, v96, v102
	v_lshl_add_u64 v[24:25], v[40:41], 0, v[24:25]
	v_or_b32_e32 v150, 8, v42
	v_cvt_pk_bf16_f32 v22, v37, v34
	v_cvt_pk_bf16_f32 v23, v31, v23
	global_store_dwordx4 v[24:25], v[20:23], off
	v_or_b32_e32 v152, 9, v42
	v_or_b32_e32 v104, 10, v42
	v_mad_i64_i32 v[20:21], s[24:25], v150, s4, v[62:63]
	v_lshl_add_u64 v[20:21], v[20:21], 0, v[60:61]
	s_nop 0
	v_add_co_u32_e32 v20, vcc, s33, v20
	v_or_b32_e32 v36, 11, v42
	s_nop 0
	v_addc_co_u32_e32 v21, vcc, 0, v21, vcc
	s_nop 0
	s_nop 0
	v_mad_i64_i32 v[20:21], s[24:25], v152, s4, v[62:63]
	v_lshl_add_u64 v[20:21], v[20:21], 0, v[60:61]
	v_add_co_u32_e32 v22, vcc, s33, v20
	v_mov_b32_e32 v82, v39
	s_nop 0
	v_addc_co_u32_e32 v23, vcc, 0, v21, vcc
	s_nop 0
	s_nop 0
	s_nop 0
	v_mad_i64_i32 v[20:21], s[24:25], v104, s4, v[62:63]
	v_lshl_add_u64 v[20:21], v[20:21], 0, v[60:61]
	v_add_co_u32_e32 v22, vcc, s33, v20
	v_mov_b32_e32 v96, v81
	s_nop 0
	v_addc_co_u32_e32 v23, vcc, 0, v21, vcc
	s_nop 0
	s_nop 0
	v_mad_i64_i32 v[22:23], s[24:25], v36, s4, v[62:63]
	v_lshl_add_u64 v[22:23], v[22:23], 0, v[60:61]
	v_add_co_u32_e32 v24, vcc, s33, v22
	v_mov_b32_e32 v114, v87
	s_nop 0
	v_addc_co_u32_e32 v25, vcc, 0, v23, vcc
	s_nop 0
	s_nop 0
	s_nop 0
	s_nop 0
	s_nop 0
	s_nop 0
	s_nop 0
	v_mov_b32_e32 v100, v85
	v_mov_b32_e32 v108, v95
	v_mov_b32_e32 v98, v91
	v_mov_b32_e32 v106, v89
	v_pk_mul_f32 v[94:95], v[68:69], v[108:109]
	v_mov_b32_e32 v102, v93
	v_add_f32_e32 v108, v94, v95
	v_pk_mul_f32 v[154:155], v[76:77], v[114:115]
	v_ashrrev_i32_e32 v151, 31, v150
	v_add_f32_e32 v114, v154, v155
	v_pk_mul_f32 v[158:159], v[78:79], v[100:101]
	v_lshlrev_b64 v[150:151], 12, v[150:151]
	v_add_f32_e32 v100, v158, v159
	v_lshl_add_u64 v[150:151], v[40:41], 0, v[150:151]
	v_ashrrev_i32_e32 v153, 31, v152
	v_ashrrev_i32_e32 v105, 31, v104
	v_lshlrev_b64 v[104:105], 12, v[104:105]
	v_lshl_add_u64 v[104:105], v[40:41], 0, v[104:105]
	v_ashrrev_i32_e32 v37, 31, v36
	s_waitcnt vmcnt(16)
; #define GAS __attribute__((address_space(1)))
; __device__ __forceinline__ void unpack8(const v4u v, float (&f)[8]) { f[0] = bflo(v.x); f[1] = bfhi(v.x); f[2] = bflo(v.y); f[3] = bfhi(v.y); f[4] = bflo(v.z); f[5] = bfhi(v.z); f[6] = bflo(v.w); f[7] = bfhi(v.w); }
; __device__ __forceinline__ v4u pack8(const float (&f)[8]) { v4u o; o.x = cvt_pk_bf16(f[0], f[1]); o.y = cvt_pk_bf16(f[2], f[3]); o.z = cvt_pk_bf16(f[4], f[5]); o.w = cvt_pk_bf16(f[6], f[7]); return o; }
; __device__ __forceinline__ void phase_conv(const Params& P, int seg) {
;     ...
;         for (int hb = 0; hb < 4; ++hb) { v4u rc[4], rh[4], rb[4];
; #pragma unroll
;             for (int i = 0; i < 4; ++i) { const GAS bf16* q = proj + (size_t)(lr0 + hb * 4 + i) * NPROJ; rc[i] = __builtin_nontemporal_load((const GAS v4u*)(q + OFF_SCC + c)); rh[i] = __builtin_nontemporal_load((const GAS v4u*)(q + OFF_SCH + c)); rb[i] = __builtin_nontemporal_load((const GAS v4u*)(q + OFF_SCB + c)); }
; #pragma unroll
;             for (int i = 0; i < 4; ++i) { float bv[8], y[8]; unpack8(rc[i], t0); unpack8(rh[i], t1); unpack8(rb[i], bv);
; #pragma unroll
;                 for (int e = 0; e < 8; ++e) { p2[e] = t0[e] * t1[e]; y[e] = bv[e] * (w0[e] * p0[e] + w1[e] * p1[e] + w2[e] * p2[e]); p0[e] = p1[e]; p1[e] = p2[e]; }
;                 *(GAS v4u*)(ya + (size_t)(lr0 + hb * 4 + i) * DM + c) = pack8(y); } }
	v_lshlrev_b32_e32 v43, 16, v224
	v_and_b32_e32 v141, 0xffff0000, v224
	v_lshlrev_b32_e32 v160, 16, v225
	v_and_b32_e32 v161, 0xffff0000, v225
	v_pk_mul_f32 v[110:111], v[64:65], v[82:83]
	s_waitcnt vmcnt(15)
	v_lshlrev_b32_e32 v38, 16, v220
	s_waitcnt vmcnt(14)
	v_lshlrev_b32_e32 v80, 16, v216
	v_add_f32_e32 v82, v110, v111
	v_and_b32_e32 v84, 0xffff0000, v220
	v_and_b32_e32 v86, 0xffff0000, v216
	v_pk_mul_f32 v[110:111], v[66:67], v[96:97]
	v_lshlrev_b32_e32 v88, 16, v221
	v_add_f32_e32 v96, v110, v111
	v_lshlrev_b32_e32 v90, 16, v217
	v_and_b32_e32 v92, 0xffff0000, v221
	s_waitcnt vmcnt(13)
	v_lshlrev_b32_e32 v81, 16, v212
	s_waitcnt vmcnt(12)
	v_lshlrev_b32_e32 v39, 16, v208
	v_pk_mul_f32 v[38:39], v[38:39], v[80:81]
	v_and_b32_e32 v87, 0xffff0000, v212
	v_and_b32_e32 v85, 0xffff0000, v208
	v_pk_mul_f32 v[80:81], v[44:45], v[38:39]
	v_pk_mul_f32 v[84:85], v[84:85], v[86:87]
	v_fma_f32 v80, v12, v83, v80
	s_waitcnt vmcnt(11)
	v_lshlrev_b32_e32 v124, 16, v204
	v_fmac_f32_e32 v82, v16, v38
	v_add_f32_e32 v80, v80, v81
	v_fmac_f32_e32 v96, v17, v84
	v_lshlrev_b32_e32 v91, 16, v213
	v_lshlrev_b32_e32 v89, 16, v209
	v_mul_f32_e32 v43, v82, v43
	v_mul_f32_e32 v124, v80, v124
	v_mul_f32_e32 v80, v96, v141
	v_pk_mul_f32 v[82:83], v[46:47], v[84:85]
	v_cvt_pk_bf16_f32 v80, v43, v80
	v_pk_mul_f32 v[86:87], v[88:89], v[90:91]
	v_fma_f32 v43, v13, v97, v82
	v_and_b32_e32 v94, 0xffff0000, v217
	v_pk_mul_f32 v[110:111], v[70:71], v[102:103]
	v_and_b32_e32 v95, 0xffff0000, v213
	v_and_b32_e32 v93, 0xffff0000, v209
	v_add_f32_e32 v43, v43, v83
	v_pk_mul_f32 v[82:83], v[48:49], v[86:87]
	v_add_f32_e32 v102, v110, v111
	v_pk_mul_f32 v[120:121], v[74:75], v[106:107]
	v_fma_f32 v82, v14, v109, v82
	v_pk_mul_f32 v[88:89], v[92:93], v[94:95]
	v_lshlrev_b32_e32 v164, 16, v227
	v_and_b32_e32 v165, 0xffff0000, v227
	v_add_f32_e32 v106, v120, v121
	v_lshlrev_b32_e32 v120, 16, v223
	v_and_b32_e32 v154, 0xffff0000, v223
	v_lshlrev_b32_e32 v113, 16, v214
	v_and_b32_e32 v119, 0xffff0000, v214
	v_lshlrev_b32_e32 v126, 16, v205
	v_fmac_f32_e32 v108, v18, v86
	v_add_f32_e32 v82, v82, v83
	v_fmac_f32_e32 v102, v19, v88
	v_mul_f32_e32 v81, v108, v160
	v_mul_f32_e32 v108, v82, v126
	v_mul_f32_e32 v82, v102, v161
	v_cvt_pk_bf16_f32 v81, v81, v82
	v_pk_mul_f32 v[82:83], v[50:51], v[88:89]
	v_lshlrev_b32_e32 v162, 16, v226
	v_and_b32_e32 v163, 0xffff0000, v226
	v_lshlrev_b32_e32 v110, 16, v222
	v_lshlrev_b32_e32 v112, 16, v218
	v_pk_mul_f32 v[116:117], v[72:73], v[98:99]
	v_lshlrev_b32_e32 v111, 16, v210
	v_fma_f32 v82, v15, v103, v82
	v_add_f32_e32 v98, v116, v117
	v_and_b32_e32 v116, 0xffff0000, v222
	v_and_b32_e32 v118, 0xffff0000, v218
	v_lshlrev_b32_e32 v122, 16, v219
	v_and_b32_e32 v156, 0xffff0000, v219
	v_lshlrev_b32_e32 v123, 16, v215
	v_and_b32_e32 v157, 0xffff0000, v215
	v_and_b32_e32 v127, 0xffff0000, v205
	v_add_f32_e32 v82, v82, v83
	v_pk_mul_f32 v[90:91], v[110:111], v[112:113]
	v_and_b32_e32 v117, 0xffff0000, v210
	v_mul_f32_e32 v102, v82, v127
	v_pk_mul_f32 v[82:83], v[52:53], v[90:91]
	v_pk_mul_f32 v[92:93], v[116:117], v[118:119]
	v_fma_f32 v82, v4, v99, v82
	v_lshlrev_b32_e32 v128, 16, v206
	v_fmac_f32_e32 v98, v8, v90
	v_add_f32_e32 v82, v82, v83
	v_fmac_f32_e32 v106, v9, v92
	v_mul_f32_e32 v94, v98, v162
	v_mul_f32_e32 v98, v82, v128
	v_mul_f32_e32 v82, v106, v163
	v_cvt_pk_bf16_f32 v82, v94, v82
	v_pk_mul_f32 v[94:95], v[56:57], v[92:93]
	v_lshlrev_b32_e32 v121, 16, v211
	v_fma_f32 v83, v5, v107, v94
	v_add_f32_e32 v83, v83, v95
	v_pk_mul_f32 v[94:95], v[120:121], v[122:123]
	v_and_b32_e32 v155, 0xffff0000, v211
	v_pk_mul_f32 v[96:97], v[58:59], v[94:95]
	v_lshlrev_b32_e32 v130, 16, v207
	v_fma_f32 v96, v6, v115, v96
	v_add_f32_e32 v96, v96, v97
	v_and_b32_e32 v129, 0xffff0000, v206
	v_fmac_f32_e32 v114, v10, v94
	v_mul_f32_e32 v103, v96, v130
	v_pk_mul_f32 v[96:97], v[154:155], v[156:157]
	v_mul_f32_e32 v99, v83, v129
	v_mul_f32_e32 v83, v114, v164
	v_fmac_f32_e32 v100, v11, v96
	v_mul_f32_e32 v100, v100, v165
	v_cvt_pk_bf16_f32 v83, v83, v100
	global_store_dwordx4 v[150:151], v[80:83], off
	v_or_b32_e32 v251, 12, v42
	v_mad_i64_i32 v[248:249], s[48:49], v251, s4, v[62:63]
	v_lshl_add_u64 v[246:247], v[248:249], 0, v[60:61]
	v_add_co_u32_e64 v250, s[48:49], s33, v246
	v_addc_co_u32_e64 v245, s[48:49], 0, v247, s[48:49]
	v_mov_b32_e32 v224, v250
	v_mov_b32_e32 v225, v245
	global_load_dwordx4 v[226:229], v[224:225], off offset:-4096 nt
	v_or_b32_e32 v251, 13, v42
	v_mad_i64_i32 v[248:249], s[48:49], v251, s4, v[62:63]
	v_lshl_add_u64 v[246:247], v[248:249], 0, v[60:61]
	v_add_co_u32_e64 v250, s[48:49], s33, v246
	v_addc_co_u32_e64 v245, s[48:49], 0, v247, s[48:49]
	v_mov_b32_e32 v220, v250
	v_mov_b32_e32 v221, v245
	global_load_dwordx4 v[222:225], v[220:221], off offset:-4096 nt
	v_or_b32_e32 v251, 13, v42
	v_mad_i64_i32 v[248:249], s[48:49], v251, s4, v[62:63]
	v_lshl_add_u64 v[246:247], v[248:249], 0, v[60:61]
	v_add_co_u32_e64 v250, s[48:49], s33, v246
	v_addc_co_u32_e64 v245, s[48:49], 0, v247, s[48:49]
	v_mov_b32_e32 v216, v250
	v_mov_b32_e32 v217, v245
	global_load_dwordx4 v[218:221], v[216:217], off nt
	v_or_b32_e32 v251, 13, v42
	v_mad_i64_i32 v[248:249], s[48:49], v251, s4, v[62:63]
	v_lshl_add_u64 v[246:247], v[248:249], 0, v[60:61]
	global_load_dwordx4 v[214:217], v[246:247], off nt
	v_or_b32_e32 v251, 14, v42
	v_mad_i64_i32 v[248:249], s[48:49], v251, s4, v[62:63]
	v_lshl_add_u64 v[246:247], v[248:249], 0, v[60:61]
	v_add_co_u32_e64 v250, s[48:49], s33, v246
	v_addc_co_u32_e64 v245, s[48:49], 0, v247, s[48:49]
	v_mov_b32_e32 v208, v250
	v_mov_b32_e32 v209, v245
	global_load_dwordx4 v[210:213], v[208:209], off offset:-4096 nt
	v_or_b32_e32 v251, 14, v42
	v_mad_i64_i32 v[248:249], s[48:49], v251, s4, v[62:63]
	v_lshl_add_u64 v[246:247], v[248:249], 0, v[60:61]
	v_add_co_u32_e64 v250, s[48:49], s33, v246
	v_addc_co_u32_e64 v245, s[48:49], 0, v247, s[48:49]
	v_mov_b32_e32 v208, v250
	v_mov_b32_e32 v209, v245
	global_load_dwordx4 v[164:167], v[208:209], off nt
	v_and_b32_e32 v125, 0xffff0000, v204
	v_and_b32_e32 v131, 0xffff0000, v207
	v_pk_mul_f32 v[80:81], v[54:55], v[96:97]
	v_mul_f32_e32 v43, v43, v125
	v_fma_f32 v80, v7, v101, v80
	v_add_f32_e32 v80, v80, v81
	v_mul_f32_e32 v83, v80, v131
	v_cvt_pk_bf16_f32 v80, v124, v43
	v_cvt_pk_bf16_f32 v81, v108, v102
	v_cvt_pk_bf16_f32 v82, v98, v99
	v_lshlrev_b64 v[98:99], 12, v[152:153]
	v_cvt_pk_bf16_f32 v83, v103, v83
	v_lshl_add_u64 v[98:99], v[40:41], 0, v[98:99]
	global_store_dwordx4 v[98:99], v[80:83], off
	v_or_b32_e32 v251, 15, v42
	v_mad_i64_i32 v[248:249], s[48:49], v251, s4, v[62:63]
	v_lshl_add_u64 v[246:247], v[248:249], 0, v[60:61]
	v_add_co_u32_e64 v250, s[48:49], s33, v246
	v_addc_co_u32_e64 v245, s[48:49], 0, v247, s[48:49]
	v_mov_b32_e32 v204, v250
	v_mov_b32_e32 v205, v245
	global_load_dwordx4 v[206:209], v[204:205], off offset:-4096 nt
	v_pk_mul_f32 v[98:99], v[64:65], v[38:39]
	v_pk_mul_f32 v[124:125], v[78:79], v[96:97]
	s_waitcnt vmcnt(18)
; #define GAS __attribute__((address_space(1)))
; __device__ __forceinline__ void unpack8(const v4u v, float (&f)[8]) { f[0] = bflo(v.x); f[1] = bfhi(v.x); f[2] = bflo(v.y); f[3] = bfhi(v.y); f[4] = bflo(v.z); f[5] = bfhi(v.z); f[6] = bflo(v.w); f[7] = bfhi(v.w); }
; __device__ __forceinline__ v4u pack8(const float (&f)[8]) { v4u o; o.x = cvt_pk_bf16(f[0], f[1]); o.y = cvt_pk_bf16(f[2], f[3]); o.z = cvt_pk_bf16(f[4], f[5]); o.w = cvt_pk_bf16(f[6], f[7]); return o; }
; __device__ __forceinline__ void phase_conv(const Params& P, int seg) {
;     ...
;         for (int hb = 0; hb < 4; ++hb) { v4u rc[4], rh[4], rb[4];
; #pragma unroll
;             for (int i = 0; i < 4; ++i) { const GAS bf16* q = proj + (size_t)(lr0 + hb * 4 + i) * NPROJ; rc[i] = __builtin_nontemporal_load((const GAS v4u*)(q + OFF_SCC + c)); rh[i] = __builtin_nontemporal_load((const GAS v4u*)(q + OFF_SCH + c)); rb[i] = __builtin_nontemporal_load((const GAS v4u*)(q + OFF_SCB + c)); }
; #pragma unroll
;             for (int i = 0; i < 4; ++i) { float bv[8], y[8]; unpack8(rc[i], t0); unpack8(rh[i], t1); unpack8(rb[i], bv);
; #pragma unroll
;                 for (int e = 0; e < 8; ++e) { p2[e] = t0[e] * t1[e]; y[e] = bv[e] * (w0[e] * p0[e] + w1[e] * p1[e] + w2[e] * p2[e]); p0[e] = p1[e]; p1[e] = p2[e]; }
;                 *(GAS v4u*)(ya + (size_t)(lr0 + hb * 4 + i) * DM + c) = pack8(y); } }
	v_lshlrev_b32_e32 v80, 16, v196
	v_lshlrev_b32_e32 v82, 16, v200
	s_waitcnt vmcnt(17)
	v_lshlrev_b32_e32 v83, 16, v192
	s_waitcnt vmcnt(16)
	v_lshlrev_b32_e32 v81, 16, v188
	v_add_f32_e32 v38, v98, v99
	v_pk_mul_f32 v[100:101], v[66:67], v[84:85]
	v_pk_mul_f32 v[106:107], v[68:69], v[86:87]
	v_pk_mul_f32 v[110:111], v[70:71], v[88:89]
	v_pk_mul_f32 v[114:115], v[72:73], v[90:91]
	v_pk_mul_f32 v[116:117], v[74:75], v[92:93]
	v_pk_mul_f32 v[120:121], v[76:77], v[94:95]
	v_add_f32_e32 v96, v124, v125
	v_pk_mul_f32 v[124:125], v[80:81], v[82:83]
	s_waitcnt vmcnt(14)
	v_lshlrev_b32_e32 v43, 16, v234
	v_and_b32_e32 v98, 0xffff0000, v196
	v_and_b32_e32 v28, 0xffff0000, v200
	v_add_f32_e32 v84, v100, v101
	v_lshlrev_b32_e32 v102, 16, v201
	v_add_f32_e32 v86, v106, v107
	v_and_b32_e32 v108, 0xffff0000, v201
	v_add_f32_e32 v88, v110, v111
	v_add_f32_e32 v90, v114, v115
	v_add_f32_e32 v92, v116, v117
	v_add_f32_e32 v94, v120, v121
	v_and_b32_e32 v29, 0xffff0000, v192
	v_and_b32_e32 v99, 0xffff0000, v188
	v_lshlrev_b32_e32 v101, 16, v189
	v_and_b32_e32 v107, 0xffff0000, v189
	v_lshlrev_b32_e32 v111, 16, v190
	v_and_b32_e32 v115, 0xffff0000, v190
	v_lshlrev_b32_e32 v117, 16, v191
	v_and_b32_e32 v121, 0xffff0000, v191
	s_waitcnt vmcnt(13)
	v_lshlrev_b32_e32 v24, 16, v230
	v_and_b32_e32 v25, 0xffff0000, v230
	v_lshlrev_b32_e32 v26, 16, v231
	v_and_b32_e32 v27, 0xffff0000, v231
	v_fmac_f32_e32 v38, v16, v124
	v_pk_mul_f32 v[20:21], v[44:45], v[124:125]
	v_lshlrev_b32_e32 v103, 16, v193
	v_and_b32_e32 v109, 0xffff0000, v193
	v_lshlrev_b32_e32 v32, 16, v232
	v_and_b32_e32 v33, 0xffff0000, v232
	v_mul_f32_e32 v22, v38, v43
	v_fma_f32 v20, v12, v39, v20
	v_pk_mul_f32 v[38:39], v[98:99], v[28:29]
	v_and_b32_e32 v126, 0xffff0000, v234
	v_add_f32_e32 v20, v20, v21
	v_fmac_f32_e32 v84, v17, v38
	v_mul_f32_e32 v43, v20, v24
	v_mul_f32_e32 v20, v84, v126
	v_lshlrev_b32_e32 v100, 16, v197
	v_lshlrev_b32_e32 v118, 16, v203
	v_and_b32_e32 v122, 0xffff0000, v203
	v_lshlrev_b32_e32 v113, 16, v194
	v_and_b32_e32 v31, 0xffff0000, v194
	v_lshlrev_b32_e32 v119, 16, v195
	v_and_b32_e32 v123, 0xffff0000, v195
	v_lshlrev_b32_e32 v34, 16, v233
	v_and_b32_e32 v35, 0xffff0000, v233
	v_cvt_pk_bf16_f32 v20, v22, v20
	v_pk_mul_f32 v[22:23], v[46:47], v[38:39]
	v_pk_mul_f32 v[126:127], v[100:101], v[102:103]
	v_fma_f32 v21, v13, v85, v22
	v_and_b32_e32 v106, 0xffff0000, v197
	v_add_f32_e32 v21, v21, v23
	v_pk_mul_f32 v[22:23], v[48:49], v[126:127]
	v_pk_mul_f32 v[108:109], v[106:107], v[108:109]
	v_fma_f32 v22, v14, v87, v22
	v_lshlrev_b32_e32 v128, 16, v235
	v_and_b32_e32 v129, 0xffff0000, v235
	v_fmac_f32_e32 v86, v18, v126
	v_add_f32_e32 v22, v22, v23
	v_fmac_f32_e32 v88, v19, v108
	v_mul_f32_e32 v28, v21, v25
	v_mul_f32_e32 v21, v86, v128
	v_mul_f32_e32 v26, v22, v26
	v_mul_f32_e32 v22, v88, v129
	v_cvt_pk_bf16_f32 v21, v21, v22
	v_pk_mul_f32 v[22:23], v[50:51], v[108:109]
	v_lshlrev_b32_e32 v110, 16, v198
	v_lshlrev_b32_e32 v112, 16, v202
	v_fma_f32 v22, v15, v89, v22
	v_add_f32_e32 v22, v22, v23
	v_pk_mul_f32 v[110:111], v[110:111], v[112:113]
	v_and_b32_e32 v114, 0xffff0000, v198
	v_and_b32_e32 v30, 0xffff0000, v202
	v_mul_f32_e32 v27, v22, v27
	v_pk_mul_f32 v[22:23], v[52:53], v[110:111]
	v_pk_mul_f32 v[112:113], v[114:115], v[30:31]
	v_fma_f32 v22, v4, v91, v22
	v_lshlrev_b32_e32 v130, 16, v236
	v_and_b32_e32 v131, 0xffff0000, v236
	v_fmac_f32_e32 v90, v8, v110
	v_add_f32_e32 v22, v22, v23
	v_fmac_f32_e32 v92, v9, v112
	v_mul_f32_e32 v24, v90, v130
	v_mul_f32_e32 v29, v22, v32
	v_mul_f32_e32 v22, v92, v131
	v_lshlrev_b32_e32 v116, 16, v199
	v_cvt_pk_bf16_f32 v22, v24, v22
	v_pk_mul_f32 v[24:25], v[56:57], v[112:113]
	v_and_b32_e32 v120, 0xffff0000, v199
	v_fma_f32 v23, v5, v93, v24
	v_pk_mul_f32 v[114:115], v[116:117], v[118:119]
	v_lshlrev_b32_e32 v132, 16, v237
	v_add_f32_e32 v23, v23, v25
	v_fmac_f32_e32 v94, v10, v114
	v_pk_mul_f32 v[24:25], v[58:59], v[114:115]
	v_pk_mul_f32 v[116:117], v[120:121], v[122:123]
	v_and_b32_e32 v133, 0xffff0000, v237
	v_mul_f32_e32 v30, v23, v33
	v_mul_f32_e32 v23, v94, v132
	v_fma_f32 v24, v6, v95, v24
	v_fmac_f32_e32 v96, v11, v116
	v_add_f32_e32 v24, v24, v25
	v_mul_f32_e32 v25, v96, v133
	v_cvt_pk_bf16_f32 v23, v23, v25
	global_store_dwordx4 v[104:105], v[20:23], off
	v_or_b32_e32 v251, 15, v42
	v_mad_i64_i32 v[248:249], s[48:49], v251, s4, v[62:63]
	v_lshl_add_u64 v[246:247], v[248:249], 0, v[60:61]
	v_add_co_u32_e64 v250, s[48:49], s33, v246
	v_addc_co_u32_e64 v245, s[48:49], 0, v247, s[48:49]
	v_mov_b32_e32 v232, v250
	v_mov_b32_e32 v233, v245
	global_load_dwordx4 v[234:237], v[232:233], off nt
	v_or_b32_e32 v251, 14, v42
	v_mad_i64_i32 v[248:249], s[48:49], v251, s4, v[62:63]
	v_lshl_add_u64 v[246:247], v[248:249], 0, v[60:61]
	global_load_dwordx4 v[230:233], v[246:247], off nt
	v_or_b32_e32 v251, 15, v42
	v_mad_i64_i32 v[248:249], s[48:49], v251, s4, v[62:63]
	v_lshl_add_u64 v[246:247], v[248:249], 0, v[60:61]
	global_load_dwordx4 v[202:205], v[246:247], off nt
	v_mul_f32_e32 v24, v24, v34
	v_or_b32_e32 v118, 12, v42
	v_pk_mul_f32 v[20:21], v[54:55], v[116:117]
	v_or_b32_e32 v120, 13, v42
	v_fma_f32 v20, v7, v97, v20
	v_add_f32_e32 v20, v20, v21
	v_mul_f32_e32 v23, v20, v35
	v_cvt_pk_bf16_f32 v20, v43, v28
	v_cvt_pk_bf16_f32 v21, v26, v27
	v_cvt_pk_bf16_f32 v22, v29, v30
	v_cvt_pk_bf16_f32 v23, v24, v23
	v_lshlrev_b64 v[24:25], 12, v[36:37]
	v_lshl_add_u64 v[24:25], v[40:41], 0, v[24:25]
	global_store_dwordx4 v[24:25], v[20:23], off
	v_or_b32_e32 v122, 14, v42
	v_pk_mul_f32 v[130:131], v[68:69], v[126:127]
	v_mad_i64_i32 v[20:21], s[24:25], v118, s4, v[62:63]
	v_lshl_add_u64 v[20:21], v[20:21], 0, v[60:61]
	s_nop 0
; #define GAS __attribute__((address_space(1)))
; __device__ __forceinline__ void unpack8(const v4u v, float (&f)[8]) { f[0] = bflo(v.x); f[1] = bfhi(v.x); f[2] = bflo(v.y); f[3] = bfhi(v.y); f[4] = bflo(v.z); f[5] = bfhi(v.z); f[6] = bflo(v.w); f[7] = bfhi(v.w); }
; __device__ __forceinline__ v4u pack8(const float (&f)[8]) { v4u o; o.x = cvt_pk_bf16(f[0], f[1]); o.y = cvt_pk_bf16(f[2], f[3]); o.z = cvt_pk_bf16(f[4], f[5]); o.w = cvt_pk_bf16(f[6], f[7]); return o; }
; __device__ __forceinline__ void phase_conv(const Params& P, int seg) {
;     ...
;         for (int hb = 0; hb < 4; ++hb) { v4u rc[4], rh[4], rb[4];
; #pragma unroll
;             for (int i = 0; i < 4; ++i) { const GAS bf16* q = proj + (size_t)(lr0 + hb * 4 + i) * NPROJ; rc[i] = __builtin_nontemporal_load((const GAS v4u*)(q + OFF_SCC + c)); rh[i] = __builtin_nontemporal_load((const GAS v4u*)(q + OFF_SCH + c)); rb[i] = __builtin_nontemporal_load((const GAS v4u*)(q + OFF_SCB + c)); }
; #pragma unroll
;             for (int i = 0; i < 4; ++i) { float bv[8], y[8]; unpack8(rc[i], t0); unpack8(rh[i], t1); unpack8(rb[i], bv);
; #pragma unroll
;                 for (int e = 0; e < 8; ++e) { p2[e] = t0[e] * t1[e]; y[e] = bv[e] * (w0[e] * p0[e] + w1[e] * p1[e] + w2[e] * p2[e]); p0[e] = p1[e]; p1[e] = p2[e]; }
;                 *(GAS v4u*)(ya + (size_t)(lr0 + hb * 4 + i) * DM + c) = pack8(y); } }
	v_add_co_u32_e32 v20, vcc, s33, v20
	v_add_f32_e32 v126, v130, v131
	s_nop 0
	v_addc_co_u32_e32 v21, vcc, 0, v21, vcc
	s_nop 0
	s_nop 0
	v_mad_i64_i32 v[20:21], s[24:25], v120, s4, v[62:63]
	v_lshl_add_u64 v[20:21], v[20:21], 0, v[60:61]
	v_add_co_u32_e32 v80, vcc, s33, v20
	v_pk_mul_f32 v[144:145], v[72:73], v[110:111]
	s_nop 0
	v_addc_co_u32_e32 v81, vcc, 0, v21, vcc
	s_nop 0
	s_nop 0
	s_nop 0
	v_pk_mul_f32 v[134:135], v[70:71], v[108:109]
	s_nop 0
	v_mad_i64_i32 v[20:21], s[24:25], v122, s4, v[62:63]
	v_lshl_add_u64 v[100:101], v[20:21], 0, v[60:61]
	v_add_co_u32_e32 v20, vcc, s33, v100
	v_add_f32_e32 v110, v144, v145
	s_nop 0
	v_addc_co_u32_e32 v21, vcc, 0, v101, vcc
	s_nop 0
	s_nop 0
	v_or_b32_e32 v20, 15, v42
	v_mad_i64_i32 v[42:43], s[24:25], v20, s4, v[62:63]
	v_lshl_add_u64 v[42:43], v[42:43], 0, v[60:61]
	v_add_co_u32_e32 v96, vcc, s33, v42
	v_pk_mul_f32 v[144:145], v[74:75], v[112:113]
	s_nop 0
	v_addc_co_u32_e32 v97, vcc, 0, v43, vcc
	s_nop 0
	s_nop 0
	s_nop 0
	s_nop 0
	s_nop 0
	s_nop 0
	s_nop 0
	v_pk_mul_f32 v[42:43], v[64:65], v[124:125]
	v_pk_mul_f32 v[148:149], v[76:77], v[114:115]
	v_add_f32_e32 v124, v42, v43
	v_pk_mul_f32 v[42:43], v[66:67], v[38:39]
	v_add_f32_e32 v108, v134, v135
	v_add_f32_e32 v38, v42, v43
	v_add_f32_e32 v112, v144, v145
	v_add_f32_e32 v114, v148, v149
	v_ashrrev_i32_e32 v119, 31, v118
	v_pk_mul_f32 v[152:153], v[78:79], v[116:117]
	v_lshlrev_b64 v[118:119], 12, v[118:119]
	v_add_f32_e32 v116, v152, v153
	v_lshl_add_u64 v[118:119], v[40:41], 0, v[118:119]
	v_ashrrev_i32_e32 v121, 31, v120
	v_ashrrev_i32_e32 v123, 31, v122
	v_ashrrev_i32_e32 v21, 31, v20
	v_cmp_le_i32_e32 vcc, s9, v140
	s_or_b64 s[28:29], vcc, s[28:29]
	s_waitcnt vmcnt(17)
	v_lshlrev_b32_e32 v141, 16, v168
	v_and_b32_e32 v154, 0xffff0000, v168
	v_lshlrev_b32_e32 v155, 16, v169
	v_and_b32_e32 v156, 0xffff0000, v169
	v_lshlrev_b32_e32 v157, 16, v170
	v_and_b32_e32 v158, 0xffff0000, v170
	v_lshlrev_b32_e32 v159, 16, v171
	v_and_b32_e32 v160, 0xffff0000, v171
	s_waitcnt vmcnt(15)
	v_lshlrev_b32_e32 v22, 16, v184
	s_waitcnt vmcnt(12)
	v_lshlrev_b32_e32 v24, 16, v226
	v_lshlrev_b32_e32 v128, 16, v227
	v_and_b32_e32 v132, 0xffff0000, v227
	v_and_b32_e32 v26, 0xffff0000, v184
	v_and_b32_e32 v30, 0xffff0000, v226
	s_waitcnt vmcnt(11)
	v_lshlrev_b32_e32 v25, 16, v222
	s_waitcnt vmcnt(10)
	v_lshlrev_b32_e32 v23, 16, v218
	v_and_b32_e32 v31, 0xffff0000, v222
	v_lshlrev_b32_e32 v129, 16, v223
	v_and_b32_e32 v133, 0xffff0000, v223
	v_pk_mul_f32 v[34:35], v[22:23], v[24:25]
	v_lshlrev_b32_e32 v42, 16, v185
	v_and_b32_e32 v130, 0xffff0000, v185
	v_and_b32_e32 v27, 0xffff0000, v218
	v_pk_mul_f32 v[22:23], v[44:45], v[34:35]
	v_pk_mul_f32 v[26:27], v[26:27], v[30:31]
	v_fma_f32 v22, v12, v125, v22
	v_lshlrev_b32_e32 v146, 16, v229
	v_and_b32_e32 v150, 0xffff0000, v229
	v_lshlrev_b32_e32 v143, 16, v224
	v_and_b32_e32 v33, 0xffff0000, v224
	s_waitcnt vmcnt(9)
	v_lshlrev_b32_e32 v36, 16, v214
	v_fmac_f32_e32 v124, v16, v34
	v_add_f32_e32 v22, v22, v23
	v_fmac_f32_e32 v38, v17, v26
	v_lshlrev_b32_e32 v144, 16, v187
	v_and_b32_e32 v148, 0xffff0000, v187
	v_lshlrev_b32_e32 v135, 16, v220
	v_and_b32_e32 v29, 0xffff0000, v220
	v_lshlrev_b32_e32 v145, 16, v221
	v_and_b32_e32 v149, 0xffff0000, v221
	v_lshlrev_b32_e32 v82, 16, v216
	v_and_b32_e32 v83, 0xffff0000, v216
	v_mul_f32_e32 v24, v124, v141
	v_mul_f32_e32 v86, v22, v36
	v_mul_f32_e32 v22, v38, v154
	v_lshlrev_b32_e32 v43, 16, v219
	v_cvt_pk_bf16_f32 v22, v24, v22
	v_pk_mul_f32 v[24:25], v[46:47], v[26:27]
	v_pk_mul_f32 v[30:31], v[42:43], v[128:129]
	v_fma_f32 v23, v13, v39, v24
	v_lshlrev_b32_e32 v147, 16, v225
	v_and_b32_e32 v151, 0xffff0000, v225
	v_and_b32_e32 v131, 0xffff0000, v219
	v_and_b32_e32 v37, 0xffff0000, v214
	v_add_f32_e32 v23, v23, v25
	v_pk_mul_f32 v[24:25], v[48:49], v[30:31]
	v_lshlrev_b32_e32 v80, 16, v215
	v_and_b32_e32 v81, 0xffff0000, v215
	v_lshlrev_b32_e32 v84, 16, v217
	v_and_b32_e32 v85, 0xffff0000, v217
	v_mul_f32_e32 v87, v23, v37
	v_fma_f32 v24, v14, v127, v24
	v_pk_mul_f32 v[36:37], v[130:131], v[132:133]
	v_fmac_f32_e32 v126, v18, v30
	v_add_f32_e32 v24, v24, v25
	v_fmac_f32_e32 v108, v19, v36
	v_mul_f32_e32 v23, v126, v155
	v_mul_f32_e32 v80, v24, v80
	v_mul_f32_e32 v24, v108, v156
	v_cvt_pk_bf16_f32 v23, v23, v24
	v_pk_mul_f32 v[24:25], v[50:51], v[36:37]
	v_lshlrev_b32_e32 v134, 16, v186
	v_lshlrev_b32_e32 v142, 16, v228
	v_fma_f32 v24, v15, v109, v24
	v_and_b32_e32 v28, 0xffff0000, v186
	v_and_b32_e32 v32, 0xffff0000, v228
	v_add_f32_e32 v24, v24, v25
	v_pk_mul_f32 v[38:39], v[134:135], v[142:143]
	v_mul_f32_e32 v81, v24, v81
	v_pk_mul_f32 v[24:25], v[52:53], v[38:39]
	v_pk_mul_f32 v[28:29], v[28:29], v[32:33]
	v_fma_f32 v24, v4, v111, v24
	v_pk_mul_f32 v[32:33], v[56:57], v[28:29]
	v_fmac_f32_e32 v110, v8, v38
	v_add_f32_e32 v24, v24, v25
	v_fmac_f32_e32 v112, v9, v28
	v_fma_f32 v25, v5, v113, v32
	v_mul_f32_e32 v42, v110, v157
	v_mul_f32_e32 v82, v24, v82
	v_mul_f32_e32 v24, v112, v158
	v_add_f32_e32 v25, v25, v33
	v_pk_mul_f32 v[32:33], v[144:145], v[146:147]
	v_cvt_pk_bf16_f32 v24, v42, v24
	v_mul_f32_e32 v83, v25, v83
	v_pk_mul_f32 v[42:43], v[58:59], v[32:33]
	v_fmac_f32_e32 v114, v10, v32
	v_fma_f32 v42, v6, v115, v42
	v_add_f32_e32 v42, v42, v43
	v_mul_f32_e32 v84, v42, v84
	v_pk_mul_f32 v[42:43], v[148:149], v[150:151]
	v_mul_f32_e32 v25, v114, v159
	v_fmac_f32_e32 v116, v11, v42
	v_mul_f32_e32 v108, v116, v160
	v_cvt_pk_bf16_f32 v25, v25, v108
	global_store_dwordx4 v[118:119], v[22:25], off
	v_pk_mul_f32 v[64:65], v[64:65], v[34:35]
	v_pk_mul_f32 v[66:67], v[66:67], v[26:27]
	v_pk_mul_f32 v[22:23], v[54:55], v[42:43]
	v_add_f32_e32 v34, v64, v65
	v_fma_f32 v22, v7, v117, v22
	v_add_f32_e32 v22, v22, v23
	v_mul_f32_e32 v25, v22, v85
	v_cvt_pk_bf16_f32 v22, v86, v87
	v_cvt_pk_bf16_f32 v23, v80, v81
	v_lshlrev_b64 v[80:81], 12, v[120:121]
	v_cvt_pk_bf16_f32 v24, v82, v83
	v_cvt_pk_bf16_f32 v25, v84, v25
	v_lshl_add_u64 v[80:81], v[40:41], 0, v[80:81]
	global_store_dwordx4 v[80:81], v[22:25], off
	s_waitcnt vmcnt(9)
; #define GAS __attribute__((address_space(1)))
; __device__ __forceinline__ void unpack8(const v4u v, float (&f)[8]) { f[0] = bflo(v.x); f[1] = bfhi(v.x); f[2] = bflo(v.y); f[3] = bfhi(v.y); f[4] = bflo(v.z); f[5] = bfhi(v.z); f[6] = bflo(v.w); f[7] = bfhi(v.w); }
; __device__ __forceinline__ v4u pack8(const float (&f)[8]) { v4u o; o.x = cvt_pk_bf16(f[0], f[1]); o.y = cvt_pk_bf16(f[2], f[3]); o.z = cvt_pk_bf16(f[4], f[5]); o.w = cvt_pk_bf16(f[6], f[7]); return o; }
; __device__ __forceinline__ void phase_conv(const Params& P, int seg) {
;     ...
;         for (int hb = 0; hb < 4; ++hb) { v4u rc[4], rh[4], rb[4];
; #pragma unroll
;             for (int i = 0; i < 4; ++i) { const GAS bf16* q = proj + (size_t)(lr0 + hb * 4 + i) * NPROJ; rc[i] = __builtin_nontemporal_load((const GAS v4u*)(q + OFF_SCC + c)); rh[i] = __builtin_nontemporal_load((const GAS v4u*)(q + OFF_SCH + c)); rb[i] = __builtin_nontemporal_load((const GAS v4u*)(q + OFF_SCB + c)); }
; #pragma unroll
;             for (int i = 0; i < 4; ++i) { float bv[8], y[8]; unpack8(rc[i], t0); unpack8(rh[i], t1); unpack8(rb[i], bv);
; #pragma unroll
;                 for (int e = 0; e < 8; ++e) { p2[e] = t0[e] * t1[e]; y[e] = bv[e] * (w0[e] * p0[e] + w1[e] * p1[e] + w2[e] * p2[e]); p0[e] = p1[e]; p1[e] = p2[e]; }
;                 *(GAS v4u*)(ya + (size_t)(lr0 + hb * 4 + i) * DM + c) = pack8(y); } }
	v_and_b32_e32 v64, 0xffff0000, v164
	v_and_b32_e32 v80, 0xffff0000, v210
	v_lshlrev_b32_e32 v22, 16, v164
	v_lshlrev_b32_e32 v24, 16, v210
	s_waitcnt vmcnt(7)
	v_lshlrev_b32_e32 v25, 16, v206
	s_waitcnt vmcnt(5)
	v_lshlrev_b32_e32 v23, 16, v234
	v_pk_mul_f32 v[22:23], v[22:23], v[24:25]
	v_and_b32_e32 v81, 0xffff0000, v206
	v_fmac_f32_e32 v34, v16, v22
	v_pk_mul_f32 v[22:23], v[44:45], v[22:23]
	v_and_b32_e32 v65, 0xffff0000, v234
	v_fma_f32 v12, v12, v35, v22
	v_add_f32_e32 v26, v66, v67
	v_add_f32_e32 v12, v12, v23
	v_pk_mul_f32 v[22:23], v[64:65], v[80:81]
	s_waitcnt vmcnt(4)
	v_lshlrev_b32_e32 v108, 16, v230
	v_and_b32_e32 v100, 0xffff0000, v230
	s_waitcnt vmcnt(3)
	v_lshlrev_b32_e32 v60, 16, v202
	v_fmac_f32_e32 v26, v17, v22
	v_mul_f32_e32 v16, v34, v108
	v_mul_f32_e32 v24, v12, v60
	v_mul_f32_e32 v12, v26, v100
	v_cvt_pk_bf16_f32 v12, v16, v12
	v_pk_mul_f32 v[16:17], v[46:47], v[22:23]
	v_lshlrev_b32_e32 v66, 16, v165
	v_lshlrev_b32_e32 v82, 16, v211
	v_pk_mul_f32 v[68:69], v[68:69], v[30:31]
	v_lshlrev_b32_e32 v83, 16, v207
	v_lshlrev_b32_e32 v67, 16, v235
	v_fma_f32 v13, v13, v27, v16
	v_add_f32_e32 v30, v68, v69
	v_add_f32_e32 v13, v13, v17
	v_pk_mul_f32 v[16:17], v[66:67], v[82:83]
	v_and_b32_e32 v68, 0xffff0000, v165
	v_fmac_f32_e32 v30, v18, v16
	v_pk_mul_f32 v[16:17], v[48:49], v[16:17]
	v_and_b32_e32 v84, 0xffff0000, v211
	v_pk_mul_f32 v[70:71], v[70:71], v[36:37]
	v_and_b32_e32 v85, 0xffff0000, v207
	v_and_b32_e32 v69, 0xffff0000, v235
	v_fma_f32 v14, v14, v31, v16
	v_add_f32_e32 v36, v70, v71
	v_add_f32_e32 v14, v14, v17
	v_pk_mul_f32 v[16:17], v[68:69], v[84:85]
	v_lshlrev_b32_e32 v109, 16, v231
	v_and_b32_e32 v101, 0xffff0000, v231
	v_lshlrev_b32_e32 v87, 16, v208
	v_and_b32_e32 v89, 0xffff0000, v208
	v_and_b32_e32 v61, 0xffff0000, v202
	v_lshlrev_b32_e32 v62, 16, v203
	v_fmac_f32_e32 v36, v19, v16
	v_mul_f32_e32 v22, v13, v61
	v_mul_f32_e32 v13, v30, v109
	v_mul_f32_e32 v18, v14, v62
	v_mul_f32_e32 v14, v36, v101
	v_pk_mul_f32 v[16:17], v[50:51], v[16:17]
	v_cvt_pk_bf16_f32 v13, v13, v14
	v_lshlrev_b32_e32 v70, 16, v166
	v_fma_f32 v14, v15, v37, v16
	v_lshlrev_b32_e32 v86, 16, v212
	v_pk_mul_f32 v[72:73], v[72:73], v[38:39]
	v_and_b32_e32 v88, 0xffff0000, v212
	v_lshlrev_b32_e32 v90, 16, v213
	v_and_b32_e32 v92, 0xffff0000, v213
	v_lshlrev_b32_e32 v91, 16, v209
	v_and_b32_e32 v93, 0xffff0000, v209
	v_lshlrev_b32_e32 v71, 16, v236
	v_and_b32_e32 v63, 0xffff0000, v203
	v_add_f32_e32 v14, v14, v17
	v_add_f32_e32 v38, v72, v73
	v_mul_f32_e32 v19, v14, v63
	v_pk_mul_f32 v[14:15], v[70:71], v[86:87]
	v_and_b32_e32 v72, 0xffff0000, v166
	v_pk_mul_f32 v[74:75], v[74:75], v[28:29]
	v_and_b32_e32 v73, 0xffff0000, v236
	v_fmac_f32_e32 v38, v8, v14
	v_pk_mul_f32 v[14:15], v[52:53], v[14:15]
	v_lshlrev_b32_e32 v110, 16, v232
	v_add_f32_e32 v28, v74, v75
	v_fma_f32 v4, v4, v39, v14
	v_pk_mul_f32 v[16:17], v[72:73], v[88:89]
	v_and_b32_e32 v102, 0xffff0000, v232
	v_lshlrev_b32_e32 v94, 16, v204
	v_mul_f32_e32 v8, v38, v110
	v_add_f32_e32 v4, v4, v15
	v_fmac_f32_e32 v28, v9, v16
	v_mul_f32_e32 v23, v4, v94
	v_mul_f32_e32 v4, v28, v102
	v_cvt_pk_bf16_f32 v14, v8, v4
	v_pk_mul_f32 v[8:9], v[56:57], v[16:17]
	v_pk_mul_f32 v[76:77], v[76:77], v[32:33]
	v_fma_f32 v4, v5, v29, v8
	v_lshlrev_b32_e32 v74, 16, v167
	v_add_f32_e32 v32, v76, v77
	v_and_b32_e32 v76, 0xffff0000, v167
	v_lshlrev_b32_e32 v75, 16, v237
	v_and_b32_e32 v95, 0xffff0000, v204
	v_add_f32_e32 v4, v4, v9
	v_mul_f32_e32 v8, v4, v95
	v_pk_mul_f32 v[4:5], v[74:75], v[90:91]
	v_pk_mul_f32 v[78:79], v[78:79], v[42:43]
	v_fmac_f32_e32 v32, v10, v4
	v_pk_mul_f32 v[4:5], v[58:59], v[4:5]
	v_and_b32_e32 v77, 0xffff0000, v237
	v_fma_f32 v4, v6, v33, v4
	v_lshlrev_b32_e32 v96, 16, v205
	v_add_f32_e32 v4, v4, v5
	v_add_f32_e32 v42, v78, v79
	v_mul_f32_e32 v10, v4, v96
	v_pk_mul_f32 v[4:5], v[76:77], v[92:93]
	v_lshlrev_b32_e32 v111, 16, v233
	v_fmac_f32_e32 v42, v11, v4
	v_pk_mul_f32 v[4:5], v[54:55], v[4:5]
	v_and_b32_e32 v103, 0xffff0000, v233
	v_lshlrev_b64 v[78:79], 12, v[122:123]
	v_fma_f32 v4, v7, v43, v4
	v_lshl_add_u64 v[78:79], v[40:41], 0, v[78:79]
	v_and_b32_e32 v97, 0xffff0000, v205
	v_mul_f32_e32 v9, v32, v111
	v_mul_f32_e32 v6, v42, v103
	v_add_f32_e32 v4, v4, v5
	v_cvt_pk_bf16_f32 v15, v9, v6
	global_store_dwordx4 v[78:79], v[12:15], off
	v_mul_f32_e32 v7, v4, v97
	v_cvt_pk_bf16_f32 v4, v24, v22
	v_cvt_pk_bf16_f32 v5, v18, v19
	v_cvt_pk_bf16_f32 v6, v23, v8
	v_lshlrev_b64 v[8:9], 12, v[20:21]
	v_lshl_add_u64 v[8:9], v[40:41], 0, v[8:9]
	v_cvt_pk_bf16_f32 v7, v10, v7
	global_store_dwordx4 v[8:9], v[4:7], off
	s_andn2_b64 exec, exec, s[28:29]
	s_cbranch_execz .LBB0_226
